# LDS-DMA whole-line layout (8 rows x 128 B per instruction, XOR-swizzled slots) in the GEMM main loops of P1, P2, P4, P9, P11, P12
# speedup vs baseline: 1.0063x; 1.0034x over previous
; #define PG8_STAGE(bufoff, gbase, voff) do { _Pragma("unroll") for (int _i = 0; _i < 2; ++_i) \
;         __builtin_amdgcn_global_load_lds((const unsigned*)((const char*)(gbase) + (voff)[_i]), (PG8_LAS unsigned*)(lds + (bufoff) + ldsw + _i * 8192), 16, 0, 0); } while (0)
; template <class Epi, class Sched, bool ALIGN_EPI = false, bool SP2 = false>
; __device__ __forceinline__ void gemm_phase(PG8_LAS unsigned char* lds, const Gemm g, const Sched& S, const Epi& E) {
;     ...
;     for (int i = 0; i < 2; ++i) { int R, C; stage_rc(tid * 16 + i * 8192, R, C); const int Rb = Epi::PERM ? ((R & ~31) + perm32(R & 31)) : R;
;         voffA[i] = (unsigned)(R * K + C) * 2u; voffB[i] = (unsigned)(Rb * K + C) * 2u; }
;     ...
;     const char* cA = (const char*)g.A + (size_t)cur.pm * tstep; const char* cB = (const char*)g.Bt + (size_t)cur.pn * tstep;
;     S.a_ready(cur);
;     if constexpr (SP2) {
;         PG8_STAGE(PG8_SB(0, 0), cB, voffB); PG8_STAGE(PG8_SB(0, 1), cB + hstep, voffB); PG8_STAGE(PG8_SA(0, 0), cA, voffA); PG8_STAGE(PG8_SA(0, 1), cA + hstep, voffA);
.LBB0_203:
	s_mov_b64 s[8:9], s[80:81]
	s_mov_b64 s[12:13], s[80:81]
	s_mov_b64 s[4:5], s[80:81]
	v_mov_b32_e32 v8, v182
	s_cmpk_lt_i32 s33, 0xb00
	s_barrier
	s_cselect_b64 s[48:49], -1, 0
	s_cmpk_gt_i32 s33, 0xaff
	v_readfirstlane_b32 s10, v8
	s_cbranch_scc1 .LBB0_219
	v_lshlrev_b32_e32 v0, 4, v8
	v_add_u32_e32 v1, 0x2000, v0
	v_ashrrev_i32_e32 v2, 31, v1
	v_lshrrev_b32_e32 v2, 22, v2
	v_add_u32_e32 v2, v1, v2
	v_ashrrev_i32_e32 v9, 10, v2
	v_mul_i32_i24_e32 v2, 0x400, v9
	v_sub_u32_e32 v1, v1, v2
	v_lshrrev_b32_e32 v2, 4, v1
	v_bitop3_b32 v1, v2, v1, 32 bitop3:0x6c
	v_ashrrev_i32_e32 v2, 31, v1
	s_load_dwordx2 s[0:1], s[8:9], 0x110
	s_load_dwordx2 s[2:3], s[12:13], 0x110
	v_lshrrev_b32_e32 v2, 26, v2
	v_add_u32_e32 v2, v1, v2
	v_lshlrev_b32_e32 v3, 3, v9
	v_ashrrev_i32_e32 v10, 6, v2
	v_and_b32_e32 v3, -16, v3
	v_add_u32_e32 v3, v10, v3
	s_waitcnt lgkmcnt(0)
	s_add_u32 s36, s0, 0x3000000
	v_and_b32_e32 v4, 3, v10
	s_mov_b32 s0, 0x1fffe0
	v_lshrrev_b32_e32 v5, 2, v3
	v_lshlrev_b32_e32 v6, 1, v3
	v_and_b32_e32 v2, 0xc0, v2
	v_and_or_b32 v4, v3, s0, v4
	v_and_b32_e32 v5, 4, v5
	v_and_b32_e32 v6, 24, v6
	v_sub_u32_e32 v1, v1, v2
	v_mov_b32_e32 v2, 1
	v_or3_b32 v4, v4, v5, v6
	v_lshlrev_b32_e32 v5, 5, v9
	v_ashrrev_i16_sdwa v1, v2, sext(v1) dst_sel:DWORD dst_unused:UNUSED_PAD src0_sel:DWORD src1_sel:BYTE_0
	v_and_b32_e32 v5, 32, v5
	v_bfe_i32 v11, v1, 0, 16
	v_add_lshl_u32 v1, v5, v11, 1
	v_lshl_add_u32 v128, v4, 11, v1
	v_lshl_add_u32 v130, v3, 11, v1
	v_bfe_i32 v1, v8, 27, 1
	v_lshrrev_b32_e32 v1, 22, v1
	v_add_u32_e32 v1, v0, v1
	v_and_b32_e32 v1, 0xfffffc00, v1
	v_sub_u32_e32 v0, v0, v1
	v_lshrrev_b32_e32 v1, 4, v0
	v_bitop3_b32 v1, v1, v0, 32 bitop3:0x6c
	v_ashrrev_i32_e32 v0, 31, v0
	v_lshrrev_b32_e32 v0, 26, v0
	v_add_u32_e32 v0, v1, v0
	v_ashrrev_i32_e32 v12, 6, v0
	v_ashrrev_i32_e32 v0, 31, v8
	v_lshrrev_b32_e32 v0, 26, v0
	v_add_u32_e32 v0, v8, v0
	v_ashrrev_i32_e32 v13, 6, v0
	s_addc_u32 s37, s1, 0
	v_lshlrev_b32_e32 v0, 3, v13
	s_add_u32 s38, s2, 0x100000
	v_and_b32_e32 v0, -16, v0
	s_addc_u32 s39, s3, 0
	v_add_u32_e32 v0, v12, v0
	v_and_b32_e32 v3, 3, v12
	s_ashr_i32 s41, s33, 31
	v_and_or_b32 v3, v0, s0, v3
	s_lshr_b32 s0, s41, 29
	s_add_i32 s0, s33, s0
	s_ashr_i32 s14, s10, 6
	s_ashr_i32 s1, s0, 3
	s_and_b32 s0, s0, -8
	s_ashr_i32 s11, s10, 8
	s_lshl_b32 s40, s14, 10
	s_sub_i32 s0, s33, s0
	s_cmp_lt_i32 s0, 0
	s_movk_i32 s42, 0x161
	s_cselect_b32 s2, s42, 0x160
	s_mul_i32 s0, s0, s2
	s_add_i32 s0, s0, s1
	s_mul_hi_i32 s1, s0, 0x2e8ba2e9
	s_lshr_b32 s2, s1, 31
	s_ashr_i32 s1, s1, 5
	s_add_i32 s1, s1, s2
	s_lshl_b32 s2, s1, 3
	s_mulk_i32 s1, 0xb0
	s_sub_i32 s0, s0, s1
	s_sext_i32_i16 s1, s0
	s_bfe_u32 s1, s1, 0x3001c
	s_add_i32 s1, s0, s1
	s_sext_i32_i16 s3, s1
	s_and_b32 s1, s1, 0xfff8
	v_lshrrev_b32_e32 v4, 2, v0
	v_lshlrev_b32_e32 v5, 1, v0
	s_sub_i32 s0, s0, s1
	v_and_b32_e32 v4, 4, v4
	v_and_b32_e32 v5, 24, v5
	s_sext_i32_i16 s0, s0
	v_or3_b32 v3, v3, v4, v5
	v_mul_i32_i24_e32 v5, 64, v12
	s_lshr_b32 s16, s3, 3
	s_add_i32 s26, s2, s0
	v_sub_u32_e32 v1, v1, v5
	s_ashr_i32 s27, s26, 31
	s_bfe_i64 s[2:3], s[16:17], 0x100000
	v_lshlrev_b32_e32 v4, 5, v13
	v_ashrrev_i16_sdwa v1, v2, sext(v1) dst_sel:DWORD dst_unused:UNUSED_PAD src0_sel:DWORD src1_sel:BYTE_0
	s_lshl_b64 s[0:1], s[26:27], 19
	s_lshl_b64 s[2:3], s[2:3], 19
	v_and_b32_e32 v4, 32, v4
	v_bfe_i32 v14, v1, 0, 16
	s_add_u32 s30, s38, s2
	v_add_lshl_u32 v1, v4, v14, 1
	s_addc_u32 s31, s39, s3
	s_add_i32 s27, s40, 0
	v_lshl_add_u32 v132, v3, 11, v1
	s_add_i32 m0, s27, 0x10000
	v_lshl_add_u32 v134, v0, 11, v1
	v_bfe_u32 v239, v8, 3, 3
	v_and_b32_e32 v240, 7, v8
	v_xor_b32_e32 v240, v240, v239
	v_lshlrev_b32_e32 v240, 4, v240
	v_lshrrev_b32_e32 v241, 6, v8
	v_lshl_add_u32 v242, v241, 3, v239
	v_mov_b32_e32 v243, 0x800
	v_mad_u32_u24 v134, v242, v243, v240
	v_add_u32_e32 v130, 0x20000, v134
	v_lshrrev_b32_e32 v244, 2, v241
	v_lshlrev_b32_e32 v244, 5, v244
	v_and_b32_e32 v245, 1, v241
	v_lshrrev_b32_e32 v246, 2, v239
	v_lshl_add_u32 v245, v245, 1, v246
	v_lshl_add_u32 v244, v245, 3, v244
	v_bfe_u32 v245, v241, 1, 1
	v_lshl_add_u32 v244, v245, 2, v244
	v_and_b32_e32 v245, 3, v239
	v_add_u32_e32 v244, v244, v245
	v_mad_u32_u24 v132, v244, v243, v240
	v_add_u32_e32 v128, 0x20000, v132
	global_load_lds_dwordx4 v132, s[30:31]
	s_add_i32 m0, s27, 0x12000
	s_add_u32 s2, s30, 0x40000
	global_load_lds_dwordx4 v128, s[30:31]
	s_addc_u32 s3, s31, 0
	s_add_i32 m0, s27, 0x14000
	s_load_dwordx2 s[4:5], s[4:5], 0x110
	global_load_lds_dwordx4 v132, s[2:3]
	s_add_i32 m0, s27, 0x16000
	s_add_u32 s28, s36, s0
	s_addc_u32 s29, s37, s1
	s_add_i32 s43, s27, 0x2000
	global_load_lds_dwordx4 v128, s[2:3]
	s_mov_b32 m0, s27
	s_add_u32 s0, s28, 0x40000
	global_load_lds_dwordx4 v134, s[28:29]
	s_mov_b32 m0, s43
	s_addc_u32 s1, s29, 0
	s_add_i32 s47, s27, 0x4000
	global_load_lds_dwordx4 v130, s[28:29]
	s_mov_b32 m0, s47
	s_add_i32 s50, s27, 0x6000
	global_load_lds_dwordx4 v134, s[0:1]
	s_mov_b32 m0, s50
	v_mov_b32_e32 v133, 0
	global_load_lds_dwordx4 v130, s[0:1]
	v_mov_b32_e32 v129, v133
	v_mov_b32_e32 v135, v133
	v_mov_b32_e32 v131, v133
	s_cmp_eq_u32 s11, 1
	s_mov_b32 s51, 0
	v_lshl_add_u64 v[6:7], s[30:31], 0, v[132:133]
	v_lshl_add_u64 v[4:5], s[30:31], 0, v[128:129]
	v_lshl_add_u64 v[0:1], s[28:29], 0, v[134:135]
	s_cselect_b64 s[8:9], -1, 0
	s_cmp_lg_u32 s11, 1
	v_lshl_add_u64 v[2:3], s[28:29], 0, v[130:131]
	s_cbranch_scc1 .LBB0_206
	s_barrier
; #define PG8_STAGE(bufoff, gbase, voff) do { _Pragma("unroll") for (int _i = 0; _i < 2; ++_i) \
;         __builtin_amdgcn_global_load_lds((const unsigned*)((const char*)(gbase) + (voff)[_i]), (PG8_LAS unsigned*)(lds + (bufoff) + ldsw + _i * 8192), 16, 0, 0); } while (0)
; #define PG8_WAIT_V(n) asm volatile("s_waitcnt vmcnt(" #n ")" ::: "memory")
; #define PG8_BAR __builtin_amdgcn_s_barrier()
; template <class Epi, class Sched, bool ALIGN_EPI = false, bool SP2 = false>
; __device__ __forceinline__ void gemm_phase(PG8_LAS unsigned char* lds, const Gemm g, const Sched& S, const Epi& E) {
;     ...
;     const unsigned ldsw = (unsigned)wid * 1024u;
;     const int aoff = lds_byte(wr * 64 + fr, fq * 8), boff = lds_byte(wc * 32 + fr, fq * 8);
;     ...
;         PG8_STAGE(PG8_SB(1, 0), cB + kstep, voffB); PG8_STAGE(PG8_SA(1, 0), cA + kstep, voffA); PG8_STAGE(PG8_SB(1, 1), cB + hstep + kstep, voffB);
;         PG8_WAIT_V(6); PG8_BAR;
.LBB0_206:
	s_waitcnt lgkmcnt(0)
	s_add_u32 s12, s4, 0xb200000
	s_addc_u32 s13, s5, 0
	s_lshl_b32 s0, s14, 5
	s_mov_b64 s[14:15], 0x80
	s_and_b32 s3, s0, 0x60
	s_add_i32 m0, s27, 0x18000
	v_lshl_add_u64 v[6:7], v[6:7], 0, s[14:15]
	s_lshl_b32 s2, s11, 13
	s_lshl_b32 s4, s3, 7
	s_waitcnt vmcnt(2)
	s_barrier
	global_load_lds_dwordx4 v[6:7], off
	v_lshl_add_u64 v[4:5], v[4:5], 0, s[14:15]
	s_add_i32 m0, s27, 0x1a000
	s_add_i32 s52, s27, 0x8000
	s_add_i32 s53, s27, 0xa000
	global_load_lds_dwordx4 v[4:5], off
	v_lshl_add_u64 v[0:1], v[0:1], 0, s[14:15]
	s_mov_b32 m0, s52
	s_add_u32 s0, s30, 0x40080
	global_load_lds_dwordx4 v[0:1], off
	v_lshl_add_u64 v[0:1], v[2:3], 0, s[14:15]
	s_mov_b32 m0, s53
	s_addc_u32 s1, s31, 0
	global_load_lds_dwordx4 v[0:1], off
	s_add_i32 m0, s27, 0x1c000
	v_lshl_add_u64 v[0:1], s[0:1], 0, v[132:133]
	global_load_lds_dwordx4 v[0:1], off
	v_lshl_add_u64 v[0:1], s[0:1], 0, v[128:129]
	s_add_i32 m0, s27, 0x1e000
	s_cmpk_lt_u32 s10, 0x100
	global_load_lds_dwordx4 v[0:1], off
	v_lshrrev_b32_e32 v1, 1, v8
	v_and_b32_e32 v1, 24, v1
	v_and_b32_e32 v0, 15, v8
	v_lshlrev_b32_e32 v2, 1, v1
	v_lshl_or_b32 v148, s11, 6, v0
	v_lshl_or_b32 v0, v0, 6, v2
	v_lshlrev_b32_e32 v2, 2, v8
	v_and_b32_e32 v2, 32, v2
	v_bitop3_b32 v3, v0, s2, v2 bitop3:0xde
	v_bitop3_b32 v149, v0, s4, v2 bitop3:0xde
	v_and_b32_e32 v239, 15, v8
	v_and_b32_e32 v240, 7, v239
	v_lshrrev_b32_e32 v239, 3, v239
	v_lshlrev_b32_e32 v239, 10, v239
	v_lshl_add_u32 v239, v240, 7, v239
	v_bfe_u32 v241, v8, 4, 2
	v_xor_b32_e32 v242, v241, v240
	v_or_b32_e32 v241, 4, v241
	v_xor_b32_e32 v243, v241, v240
	v_lshl_add_u32 v242, v242, 4, v239
	v_lshl_add_u32 v243, v243, 4, v239
	v_lshrrev_b32_e32 v244, 8, v8
	v_lshlrev_b32_e32 v244, 13, v244
	v_add_u32_e32 v3, v244, v242
	v_add_u32_e32 v233, v244, v243
	v_bfe_u32 v244, v8, 6, 2
	v_lshlrev_b32_e32 v244, 12, v244
	v_add_u32_e32 v149, v244, v242
	v_add_u32_e32 v234, v244, v243
	v_lshlrev_b32_e32 v0, 14, v13
	v_and_b32_e32 v0, 0xffff8000, v0
	v_or_b32_e32 v150, s3, v1
	v_lshl_add_u32 v0, v12, 11, v0
	v_and_b32_e32 v1, 1, v13
	v_lshl_or_b32 v0, v1, 6, v0
	v_lshl_add_u32 v136, v14, 1, v0
	v_mov_b32_e32 v136, v134
	v_lshlrev_b32_e32 v0, 14, v9
	v_and_b32_e32 v0, 0xffff8000, v0
	s_waitcnt vmcnt(6)
	v_lshl_add_u32 v0, v10, 11, v0
	v_and_b32_e32 v1, 1, v9
	s_sext_i32_i16 s59, s16
	s_cselect_b64 s[16:17], -1, 0
	v_lshl_or_b32 v0, v1, 6, v0
	s_add_i32 s56, 0, 0x10000
	s_add_i32 s57, 0, 0x14000
	s_ashr_i32 s54, s94, 31
	s_mov_b32 s55, s94
	v_mov_b32_e32 v137, v133
	v_lshl_add_u32 v138, v11, 1, v0
	v_mov_b32_e32 v138, v130
	v_mov_b32_e32 v139, v133
	v_mov_b64_e32 v[140:141], 0xb00
	v_mov_b64_e32 v[142:143], 0xaff
	v_add_u32_e32 v151, s56, v149
	v_add_u32_e32 v235, s56, v234
	v_add_u32_e32 v152, s57, v149
	v_add_u32_e32 v236, s57, v234
	v_add_u32_e32 v153, 0, v3
	s_movk_i32 s58, 0x1600
	s_barrier
	s_branch .LBB0_209

; #define PG8_STAGE(bufoff, gbase, voff) do { _Pragma("unroll") for (int _i = 0; _i < 2; ++_i) \
;         __builtin_amdgcn_global_load_lds((const unsigned*)((const char*)(gbase) + (voff)[_i]), (PG8_LAS unsigned*)(lds + (bufoff) + ldsw + _i * 8192), 16, 0, 0); } while (0)
; #define PG8_LDA(dst, b, h) do { _Pragma("unroll") for (int m = 0; m < 4; ++m) _Pragma("unroll") for (int k = 0; k < 2; ++k) dst[m][k] = *(const PG8_LAS bf16x8*)(lds + PG8_SA(b, h) + aoff + m * 2048 + k * 1024); } while (0)
; #define PG8_LDB(dst, b, h) do { _Pragma("unroll") for (int n = 0; n < 2; ++n) _Pragma("unroll") for (int k = 0; k < 2; ++k) dst[n][k] = *(const PG8_LAS bf16x8*)(lds + PG8_SB(b, h) + boff + n * 2048 + k * 1024); } while (0)
; #define PG8_MMA(ai, bj, At, Bt) do { __builtin_amdgcn_s_setprio(1); _Pragma("unroll") for (int m = 0; m < 4; ++m) _Pragma("unroll") for (int n = 0; n < 2; ++n) _Pragma("unroll") for (int k = 0; k < 2; ++k) \
;         acc[ai][bj][m][n] = __builtin_amdgcn_mfma_f32_16x16x32_bf16(Bt[n][k], At[m][k], acc[ai][bj][m][n], 0, 0, 0); __builtin_amdgcn_s_setprio(0); } while (0)
; #define PG8_WAIT_V(n) asm volatile("s_waitcnt vmcnt(" #n ")" ::: "memory")
; #define PG8_WAIT_L(n) asm volatile("s_waitcnt lgkmcnt(" #n ")" ::: "memory")
; #define PG8_BAR __builtin_amdgcn_s_barrier()
; #define PG8_SCHED __builtin_amdgcn_sched_barrier(0)
; template <class Epi, class Sched, bool ALIGN_EPI = false, bool SP2 = false>
; __device__ __forceinline__ void gemm_phase(PG8_LAS unsigned char* lds, const Gemm g, const Sched& S, const Epi& E) {
;     ...
;             PG8_LDB(B0, 0, 0); PG8_LDB(B1, 0, 1); PG8_SCHED; PG8_LDA(At, 0, 0); PG8_STAGE(PG8_SA(1, 1), a1 + hstep, voffA);
;             PG8_WAIT_V(8); PG8_WAIT_L(0); PG8_BAR; PG8_MMA(0, 0, At, B0); PG8_MMA(0, 1, At, B1); PG8_BAR; PG8_SCHED;
;             PG8_LDA(At, 0, 1); PG8_STAGE(PG8_SB(0, 0), b2, voffB); PG8_STAGE(PG8_SB(0, 1), b2 + hstep, voffB); PG8_STAGE(PG8_SA(0, 0), a2, voffA);
.LBB0_212:
	ds_read_b128 v[144:147], v151
	ds_read_b128 v[154:157], v235
	ds_read_b128 v[158:161], v151 offset:2048
	ds_read_b128 v[162:165], v235 offset:2048
	ds_read_b128 v[166:169], v152
	ds_read_b128 v[170:173], v236
	ds_read_b128 v[174:177], v152 offset:2048
	ds_read_b128 v[178:181], v236 offset:2048
	s_add_u32 s0, s28, 0xfffc0080
	s_addc_u32 s1, s29, -1
	s_cmp_eq_u32 s64, 12
	s_cselect_b32 s35, s21, s1
	s_cselect_b32 s34, s60, s0
	s_cselect_b32 s31, s19, s63
	s_cselect_b32 s30, s61, s62
	v_lshl_add_u64 v[222:223], s[28:29], 0, v[136:137]
	s_add_i32 m0, s27, 0xc000
	ds_read_b128 v[190:193], v153
	ds_read_b128 v[194:197], v233
	ds_read_b128 v[198:201], v153 offset:2048
	ds_read_b128 v[202:205], v233 offset:2048
	ds_read_b128 v[206:209], v153 offset:4096
	ds_read_b128 v[210:213], v233 offset:4096
	ds_read_b128 v[214:217], v153 offset:6144
	ds_read_b128 v[218:221], v233 offset:6144
	global_load_lds_dwordx4 v[222:223], off
	v_lshl_add_u64 v[222:223], s[28:29], 0, v[138:139]
	s_add_i32 m0, s27, 0xe000
	s_nop 0
	global_load_lds_dwordx4 v[222:223], off
	s_waitcnt vmcnt(8)
	s_waitcnt lgkmcnt(0)
	s_barrier
	s_setprio 1
	s_waitcnt lgkmcnt(0)
	v_mfma_f32_16x16x32_bf16 v[124:127], v[144:147], v[190:193], v[124:127]
	v_mfma_f32_16x16x32_bf16 v[120:123], v[158:161], v[190:193], v[120:123]
	v_mfma_f32_16x16x32_bf16 v[108:111], v[144:147], v[198:201], v[108:111]
	v_mfma_f32_16x16x32_bf16 v[104:107], v[158:161], v[198:201], v[104:107]
	v_mfma_f32_16x16x32_bf16 v[92:95], v[144:147], v[206:209], v[92:95]
	v_mfma_f32_16x16x32_bf16 v[88:91], v[158:161], v[206:209], v[88:91]
	v_mfma_f32_16x16x32_bf16 v[76:79], v[144:147], v[214:217], v[76:79]
	v_mfma_f32_16x16x32_bf16 v[72:75], v[158:161], v[214:217], v[72:75]
	v_mfma_f32_16x16x32_bf16 v[124:127], v[154:157], v[194:197], v[124:127]
	v_mfma_f32_16x16x32_bf16 v[120:123], v[162:165], v[194:197], v[120:123]
	v_mfma_f32_16x16x32_bf16 v[108:111], v[154:157], v[202:205], v[108:111]
	v_mfma_f32_16x16x32_bf16 v[104:107], v[162:165], v[202:205], v[104:107]
	v_mfma_f32_16x16x32_bf16 v[92:95], v[154:157], v[210:213], v[92:95]
	v_mfma_f32_16x16x32_bf16 v[88:91], v[162:165], v[210:213], v[88:91]
	v_mfma_f32_16x16x32_bf16 v[76:79], v[154:157], v[218:221], v[76:79]
	v_mfma_f32_16x16x32_bf16 v[72:75], v[162:165], v[218:221], v[72:75]
	s_setprio 0
	s_setprio 1
	v_mfma_f32_16x16x32_bf16 v[116:119], v[166:169], v[190:193], v[116:119]
	v_mfma_f32_16x16x32_bf16 v[112:115], v[174:177], v[190:193], v[112:115]
	v_mfma_f32_16x16x32_bf16 v[100:103], v[166:169], v[198:201], v[100:103]
	v_mfma_f32_16x16x32_bf16 v[96:99], v[174:177], v[198:201], v[96:99]
	v_mfma_f32_16x16x32_bf16 v[84:87], v[166:169], v[206:209], v[84:87]
	v_mfma_f32_16x16x32_bf16 v[80:83], v[174:177], v[206:209], v[80:83]
	v_mfma_f32_16x16x32_bf16 v[68:71], v[166:169], v[214:217], v[68:71]
	v_mfma_f32_16x16x32_bf16 v[64:67], v[174:177], v[214:217], v[64:67]
	v_mfma_f32_16x16x32_bf16 v[116:119], v[170:173], v[194:197], v[116:119]
	v_mfma_f32_16x16x32_bf16 v[112:115], v[178:181], v[194:197], v[112:115]
	v_mfma_f32_16x16x32_bf16 v[100:103], v[170:173], v[202:205], v[100:103]
	v_mfma_f32_16x16x32_bf16 v[96:99], v[178:181], v[202:205], v[96:99]
	v_mfma_f32_16x16x32_bf16 v[84:87], v[170:173], v[210:213], v[84:87]
	v_mfma_f32_16x16x32_bf16 v[80:83], v[178:181], v[210:213], v[80:83]
	v_mfma_f32_16x16x32_bf16 v[68:71], v[170:173], v[218:221], v[68:71]
	v_mfma_f32_16x16x32_bf16 v[64:67], v[178:181], v[218:221], v[64:67]
	s_setprio 0
	s_barrier
	s_add_i32 s0, s56, s40
	v_lshl_add_u64 v[222:223], s[30:31], 0, v[132:133]
	s_mov_b32 m0, s0
	ds_read_b128 v[190:193], v153 offset:16384
	ds_read_b128 v[194:197], v233 offset:16384
	ds_read_b128 v[198:201], v153 offset:18432
	ds_read_b128 v[202:205], v233 offset:18432
	ds_read_b128 v[206:209], v153 offset:20480
	ds_read_b128 v[210:213], v233 offset:20480
	ds_read_b128 v[214:217], v153 offset:22528
	ds_read_b128 v[218:221], v233 offset:22528
	global_load_lds_dwordx4 v[222:223], off
	s_add_i32 m0, s0, 0x2000
	s_add_u32 s0, s30, 0x40000
	v_lshl_add_u64 v[224:225], s[30:31], 0, v[128:129]
	s_addc_u32 s1, s31, 0
	s_add_i32 s2, s57, s40
	global_load_lds_dwordx4 v[224:225], off
	v_lshl_add_u64 v[226:227], s[0:1], 0, v[132:133]
	s_mov_b32 m0, s2
	v_lshl_add_u64 v[228:229], s[34:35], 0, v[130:131]
	global_load_lds_dwordx4 v[226:227], off
	v_lshl_add_u64 v[226:227], s[0:1], 0, v[128:129]
	s_add_i32 m0, s2, 0x2000
	s_nop 0
	global_load_lds_dwordx4 v[226:227], off
	v_lshl_add_u64 v[226:227], s[34:35], 0, v[134:135]
	s_mov_b32 m0, s27
	s_nop 0
	global_load_lds_dwordx4 v[226:227], off
	s_mov_b32 m0, s43
	s_nop 0
	global_load_lds_dwordx4 v[228:229], off
	s_waitcnt vmcnt(8)
	s_waitcnt lgkmcnt(0)
	s_barrier
; #define PG8_STAGE(bufoff, gbase, voff) do { _Pragma("unroll") for (int _i = 0; _i < 2; ++_i) \
;         __builtin_amdgcn_global_load_lds((const unsigned*)((const char*)(gbase) + (voff)[_i]), (PG8_LAS unsigned*)(lds + (bufoff) + ldsw + _i * 8192), 16, 0, 0); } while (0)
; #define PG8_LDA(dst, b, h) do { _Pragma("unroll") for (int m = 0; m < 4; ++m) _Pragma("unroll") for (int k = 0; k < 2; ++k) dst[m][k] = *(const PG8_LAS bf16x8*)(lds + PG8_SA(b, h) + aoff + m * 2048 + k * 1024); } while (0)
; #define PG8_LDB(dst, b, h) do { _Pragma("unroll") for (int n = 0; n < 2; ++n) _Pragma("unroll") for (int k = 0; k < 2; ++k) dst[n][k] = *(const PG8_LAS bf16x8*)(lds + PG8_SB(b, h) + boff + n * 2048 + k * 1024); } while (0)
; #define PG8_MMA(ai, bj, At, Bt) do { __builtin_amdgcn_s_setprio(1); _Pragma("unroll") for (int m = 0; m < 4; ++m) _Pragma("unroll") for (int n = 0; n < 2; ++n) _Pragma("unroll") for (int k = 0; k < 2; ++k) \
;         acc[ai][bj][m][n] = __builtin_amdgcn_mfma_f32_16x16x32_bf16(Bt[n][k], At[m][k], acc[ai][bj][m][n], 0, 0, 0); __builtin_amdgcn_s_setprio(0); } while (0)
; #define PG8_WAIT_V(n) asm volatile("s_waitcnt vmcnt(" #n ")" ::: "memory")
; #define PG8_WAIT_L(n) asm volatile("s_waitcnt lgkmcnt(" #n ")" ::: "memory")
; #define PG8_BAR __builtin_amdgcn_s_barrier()
; #define PG8_SCHED __builtin_amdgcn_sched_barrier(0)
; template <class Epi, class Sched, bool ALIGN_EPI = false, bool SP2 = false>
; __device__ __forceinline__ void gemm_phase(PG8_LAS unsigned char* lds, const Gemm g, const Sched& S, const Epi& E) {
;     ...
;             PG8_WAIT_V(8); PG8_WAIT_L(0); PG8_BAR; PG8_MMA(0, 0, At, B0); PG8_MMA(0, 1, At, B1); PG8_BAR; PG8_SCHED;
;             PG8_LDA(At, 0, 1); PG8_STAGE(PG8_SB(0, 0), b2, voffB); PG8_STAGE(PG8_SB(0, 1), b2 + hstep, voffB); PG8_STAGE(PG8_SA(0, 0), a2, voffA);
;             PG8_WAIT_V(8); PG8_WAIT_L(0); PG8_BAR; PG8_MMA(1, 0, At, B0); PG8_MMA(1, 1, At, B1); PG8_BAR; PG8_SCHED;
;             PG8_LDB(B0, 1, 0); PG8_LDB(B1, 1, 1); PG8_SCHED; PG8_LDA(At, 1, 0); PG8_STAGE(PG8_SA(0, 1), a2 + hstep, voffA);
;             PG8_WAIT_V(8); PG8_WAIT_L(0); PG8_BAR; PG8_MMA(0, 0, At, B0); PG8_MMA(0, 1, At, B1); PG8_BAR; PG8_SCHED;
;             PG8_LDA(At, 1, 1); PG8_STAGE(PG8_SB(1, 0), b3, voffB); PG8_STAGE(PG8_SB(1, 1), b3 + hstep, voffB); PG8_STAGE(PG8_SA(1, 0), a3, voffA);
	s_setprio 1
	s_waitcnt lgkmcnt(0)
	v_mfma_f32_16x16x32_bf16 v[60:63], v[144:147], v[190:193], v[60:63]
	v_mfma_f32_16x16x32_bf16 v[56:59], v[158:161], v[190:193], v[56:59]
	v_mfma_f32_16x16x32_bf16 v[44:47], v[144:147], v[198:201], v[44:47]
	v_mfma_f32_16x16x32_bf16 v[40:43], v[158:161], v[198:201], v[40:43]
	v_mfma_f32_16x16x32_bf16 v[28:31], v[144:147], v[206:209], v[28:31]
	v_mfma_f32_16x16x32_bf16 v[24:27], v[158:161], v[206:209], v[24:27]
	v_mfma_f32_16x16x32_bf16 v[12:15], v[144:147], v[214:217], v[12:15]
	v_mfma_f32_16x16x32_bf16 v[8:11], v[158:161], v[214:217], v[8:11]
	v_mfma_f32_16x16x32_bf16 v[60:63], v[154:157], v[194:197], v[60:63]
	v_mfma_f32_16x16x32_bf16 v[56:59], v[162:165], v[194:197], v[56:59]
	v_mfma_f32_16x16x32_bf16 v[44:47], v[154:157], v[202:205], v[44:47]
	v_mfma_f32_16x16x32_bf16 v[40:43], v[162:165], v[202:205], v[40:43]
	v_mfma_f32_16x16x32_bf16 v[28:31], v[154:157], v[210:213], v[28:31]
	v_mfma_f32_16x16x32_bf16 v[24:27], v[162:165], v[210:213], v[24:27]
	v_mfma_f32_16x16x32_bf16 v[12:15], v[154:157], v[218:221], v[12:15]
	v_mfma_f32_16x16x32_bf16 v[8:11], v[162:165], v[218:221], v[8:11]
	s_setprio 0
	s_setprio 1
	v_mfma_f32_16x16x32_bf16 v[52:55], v[166:169], v[190:193], v[52:55]
	v_mfma_f32_16x16x32_bf16 v[48:51], v[174:177], v[190:193], v[48:51]
	v_mfma_f32_16x16x32_bf16 v[36:39], v[166:169], v[198:201], v[36:39]
	v_mfma_f32_16x16x32_bf16 v[32:35], v[174:177], v[198:201], v[32:35]
	v_mfma_f32_16x16x32_bf16 v[20:23], v[166:169], v[206:209], v[20:23]
	v_mfma_f32_16x16x32_bf16 v[16:19], v[174:177], v[206:209], v[16:19]
	v_mfma_f32_16x16x32_bf16 v[4:7], v[166:169], v[214:217], v[4:7]
	v_mfma_f32_16x16x32_bf16 v[0:3], v[174:177], v[214:217], v[0:3]
	v_mfma_f32_16x16x32_bf16 v[52:55], v[170:173], v[194:197], v[52:55]
	v_mfma_f32_16x16x32_bf16 v[48:51], v[178:181], v[194:197], v[48:51]
	v_mfma_f32_16x16x32_bf16 v[36:39], v[170:173], v[202:205], v[36:39]
	v_mfma_f32_16x16x32_bf16 v[32:35], v[178:181], v[202:205], v[32:35]
	v_mfma_f32_16x16x32_bf16 v[20:23], v[170:173], v[210:213], v[20:23]
	v_mfma_f32_16x16x32_bf16 v[16:19], v[178:181], v[210:213], v[16:19]
	v_mfma_f32_16x16x32_bf16 v[4:7], v[170:173], v[218:221], v[4:7]
	v_mfma_f32_16x16x32_bf16 v[0:3], v[178:181], v[218:221], v[0:3]
	s_setprio 0
	s_barrier
	s_add_i32 s2, 0, 0x18000
	s_add_i32 s3, 0, 0x1c000
	v_add_u32_e32 v162, s2, v149
	v_add_u32_e32 v237, s2, v234
	v_add_u32_e32 v178, s3, v149
	v_add_u32_e32 v238, s3, v234
	ds_read_b128 v[144:147], v162
	ds_read_b128 v[154:157], v237
	ds_read_b128 v[158:161], v162 offset:2048
	ds_read_b128 v[162:165], v237 offset:2048
	ds_read_b128 v[166:169], v178
	ds_read_b128 v[170:173], v238
	ds_read_b128 v[174:177], v178 offset:2048
	ds_read_b128 v[178:181], v238 offset:2048
	s_add_u32 s0, s34, 0x40000
	s_addc_u32 s1, s35, 0
	s_mov_b32 m0, s47
	v_lshl_add_u64 v[230:231], s[0:1], 0, v[134:135]
	ds_read_b128 v[190:193], v153 offset:32768
	ds_read_b128 v[194:197], v233 offset:32768
	ds_read_b128 v[198:201], v153 offset:34816
	ds_read_b128 v[202:205], v233 offset:34816
	ds_read_b128 v[206:209], v153 offset:36864
	ds_read_b128 v[210:213], v233 offset:36864
	ds_read_b128 v[214:217], v153 offset:38912
	ds_read_b128 v[218:221], v233 offset:38912
	global_load_lds_dwordx4 v[230:231], off
	v_lshl_add_u64 v[230:231], s[0:1], 0, v[130:131]
	s_mov_b32 m0, s50
	s_nop 0
	global_load_lds_dwordx4 v[230:231], off
	s_waitcnt vmcnt(8)
	s_waitcnt lgkmcnt(0)
	s_barrier
	s_setprio 1
	s_waitcnt lgkmcnt(0)
	v_mfma_f32_16x16x32_bf16 v[124:127], v[144:147], v[190:193], v[124:127]
	v_mfma_f32_16x16x32_bf16 v[120:123], v[158:161], v[190:193], v[120:123]
	v_mfma_f32_16x16x32_bf16 v[108:111], v[144:147], v[198:201], v[108:111]
	v_mfma_f32_16x16x32_bf16 v[104:107], v[158:161], v[198:201], v[104:107]
	v_mfma_f32_16x16x32_bf16 v[92:95], v[144:147], v[206:209], v[92:95]
	v_mfma_f32_16x16x32_bf16 v[88:91], v[158:161], v[206:209], v[88:91]
	v_mfma_f32_16x16x32_bf16 v[76:79], v[144:147], v[214:217], v[76:79]
	v_mfma_f32_16x16x32_bf16 v[72:75], v[158:161], v[214:217], v[72:75]
	v_mfma_f32_16x16x32_bf16 v[124:127], v[154:157], v[194:197], v[124:127]
	v_mfma_f32_16x16x32_bf16 v[120:123], v[162:165], v[194:197], v[120:123]
	v_mfma_f32_16x16x32_bf16 v[108:111], v[154:157], v[202:205], v[108:111]
	v_mfma_f32_16x16x32_bf16 v[104:107], v[162:165], v[202:205], v[104:107]
	v_mfma_f32_16x16x32_bf16 v[92:95], v[154:157], v[210:213], v[92:95]
	v_mfma_f32_16x16x32_bf16 v[88:91], v[162:165], v[210:213], v[88:91]
	v_mfma_f32_16x16x32_bf16 v[76:79], v[154:157], v[218:221], v[76:79]
	v_mfma_f32_16x16x32_bf16 v[72:75], v[162:165], v[218:221], v[72:75]
	s_setprio 0
	s_setprio 1
	v_mfma_f32_16x16x32_bf16 v[116:119], v[166:169], v[190:193], v[116:119]
	v_mfma_f32_16x16x32_bf16 v[112:115], v[174:177], v[190:193], v[112:115]
	v_mfma_f32_16x16x32_bf16 v[100:103], v[166:169], v[198:201], v[100:103]
	v_mfma_f32_16x16x32_bf16 v[96:99], v[174:177], v[198:201], v[96:99]
	v_mfma_f32_16x16x32_bf16 v[84:87], v[166:169], v[206:209], v[84:87]
	v_mfma_f32_16x16x32_bf16 v[80:83], v[174:177], v[206:209], v[80:83]
	v_mfma_f32_16x16x32_bf16 v[68:71], v[166:169], v[214:217], v[68:71]
	v_mfma_f32_16x16x32_bf16 v[64:67], v[174:177], v[214:217], v[64:67]
	v_mfma_f32_16x16x32_bf16 v[116:119], v[170:173], v[194:197], v[116:119]
	v_mfma_f32_16x16x32_bf16 v[112:115], v[178:181], v[194:197], v[112:115]
	v_mfma_f32_16x16x32_bf16 v[100:103], v[170:173], v[202:205], v[100:103]
	v_mfma_f32_16x16x32_bf16 v[96:99], v[178:181], v[202:205], v[96:99]
	v_mfma_f32_16x16x32_bf16 v[84:87], v[170:173], v[210:213], v[84:87]
	v_mfma_f32_16x16x32_bf16 v[80:83], v[178:181], v[210:213], v[80:83]
	v_mfma_f32_16x16x32_bf16 v[68:71], v[170:173], v[218:221], v[68:71]
	v_mfma_f32_16x16x32_bf16 v[64:67], v[178:181], v[218:221], v[64:67]
	s_setprio 0
	s_barrier
;     __device__ __forceinline__ void operator()(const f32x4 (&acc)[2][2][4][2], const Unit& u, int wr, int wc, int fr, int fq) const {
;         const int row0 = u.pm * BM + wr * 64 + fr; const int col0 = u.pn * HALF + wc * 32 + 8 * fq;
; #pragma unroll
;         for (int ai = 0; ai < 2; ++ai)
; #pragma unroll
;             for (int m = 0; m < 4; ++m) {
;                 bf16_t* rowp = O + (size_t)(row0 + ai * HALF + m * 16) * ldc + col0;
;                 const f32x4 g0 = acc[ai][0][m][0], g1 = acc[ai][0][m][1], u0 = acc[ai][1][m][0], u1 = acc[ai][1][m][1];
; template <class Epi, class Sched, bool ALIGN_EPI = false, bool SP2 = false>
; __device__ __forceinline__ void gemm_phase(PG8_LAS unsigned char* lds, const Gemm g, const Sched& S, const Epi& E) {
;     ...
;             PG8_LDA(At, 1, 1); PG8_STAGE(PG8_SB(1, 0), b3, voffB); PG8_STAGE(PG8_SB(1, 1), b3 + hstep, voffB); PG8_STAGE(PG8_SA(1, 0), a3, voffA);
;             PG8_WAIT_V(8); PG8_WAIT_L(0); PG8_BAR; PG8_MMA(1, 0, At, B0); PG8_MMA(1, 1, At, B1); PG8_BAR; PG8_SCHED;
;             } else {
;             PG8_LDB(B0, 0, 0); PG8_SCHED; PG8_LDA(At, 0, 0); PG8_STAGE(PG8_SA(1, 1), a1 + hstep, voffA);
;             PG8_WAIT_L(8); PG8_BAR; PG8_WAIT_L(0); PG8_MMA(0, 0, At, B0); PG8_BAR; PG8_SCHED;
;             PG8_LDB(B1, 0, 1); PG8_STAGE(PG8_SB(0, 0), b2, voffB);
;             PG8_BAR; PG8_WAIT_L(0); PG8_MMA(0, 1, At, B1); PG8_BAR;
;             PG8_LDA(At, 0, 1); PG8_STAGE(PG8_SA(0, 0), a2, voffA);
;             PG8_BAR; PG8_WAIT_L(0); PG8_MMA(1, 0, At, B0); PG8_BAR; PG8_SCHED;
;             PG8_STAGE(PG8_SB(0, 1), b2 + hstep, voffB);
;             PG8_WAIT_V(6); PG8_BAR; PG8_MMA(1, 1, At, B1); PG8_BAR;
;             PG8_LDB(B0, 1, 0); PG8_SCHED; PG8_LDA(At, 1, 0); PG8_STAGE(PG8_SA(0, 1), a2 + hstep, voffA);
;             PG8_WAIT_L(8); PG8_BAR; PG8_WAIT_L(0); PG8_MMA(0, 0, At, B0); PG8_BAR; PG8_SCHED;
;             PG8_LDB(B1, 1, 1); PG8_STAGE(PG8_SB(1, 0), b3, voffB);
;             PG8_BAR; PG8_WAIT_L(0); PG8_MMA(0, 1, At, B1); PG8_BAR;
;             PG8_LDA(At, 1, 1); PG8_STAGE(PG8_SA(1, 0), a3, voffA);
;             PG8_BAR; PG8_WAIT_L(0); PG8_MMA(1, 0, At, B0); PG8_BAR; PG8_SCHED;
;             PG8_STAGE(PG8_SB(1, 1), b3 + hstep, voffB);
;             PG8_WAIT_V(6); PG8_BAR; PG8_MMA(1, 1, At, B1); PG8_BAR;
;             }
;         }
;         if constexpr (ALIGN_EPI) { if (wr == 0) PG8_BAR; }
	s_add_i32 s0, s2, s40
	v_lshl_add_u64 v[222:223], v[222:223], 0, s[14:15]
	s_mov_b32 m0, s0
	ds_read_b128 v[190:193], v153 offset:49152
	ds_read_b128 v[194:197], v233 offset:49152
	ds_read_b128 v[198:201], v153 offset:51200
	ds_read_b128 v[202:205], v233 offset:51200
	ds_read_b128 v[206:209], v153 offset:53248
	ds_read_b128 v[210:213], v233 offset:53248
	ds_read_b128 v[214:217], v153 offset:55296
	ds_read_b128 v[218:221], v233 offset:55296
	global_load_lds_dwordx4 v[222:223], off
	s_add_i32 m0, s0, 0x2000
	s_add_u32 s0, s30, 0x40080
	v_lshl_add_u64 v[222:223], v[224:225], 0, s[14:15]
	s_addc_u32 s1, s31, 0
	s_add_i32 s2, s3, s40
	global_load_lds_dwordx4 v[222:223], off
	v_lshl_add_u64 v[222:223], s[0:1], 0, v[132:133]
	s_mov_b32 m0, s2
	s_nop 0
	global_load_lds_dwordx4 v[222:223], off
	v_lshl_add_u64 v[222:223], s[0:1], 0, v[128:129]
	s_add_i32 m0, s2, 0x2000
	s_nop 0
	global_load_lds_dwordx4 v[222:223], off
	v_lshl_add_u64 v[222:223], v[226:227], 0, s[14:15]
	s_mov_b32 m0, s52
	s_nop 0
	global_load_lds_dwordx4 v[222:223], off
	v_lshl_add_u64 v[222:223], v[228:229], 0, s[14:15]
	s_mov_b32 m0, s53
	s_nop 0
	global_load_lds_dwordx4 v[222:223], off
	s_waitcnt vmcnt(8)
	s_waitcnt lgkmcnt(0)
	s_barrier
	s_setprio 1
	s_waitcnt lgkmcnt(0)
	v_mfma_f32_16x16x32_bf16 v[60:63], v[144:147], v[190:193], v[60:63]
	v_mfma_f32_16x16x32_bf16 v[56:59], v[158:161], v[190:193], v[56:59]
	v_mfma_f32_16x16x32_bf16 v[44:47], v[144:147], v[198:201], v[44:47]
	v_mfma_f32_16x16x32_bf16 v[40:43], v[158:161], v[198:201], v[40:43]
	v_mfma_f32_16x16x32_bf16 v[28:31], v[144:147], v[206:209], v[28:31]
	v_mfma_f32_16x16x32_bf16 v[24:27], v[158:161], v[206:209], v[24:27]
	v_mfma_f32_16x16x32_bf16 v[12:15], v[144:147], v[214:217], v[12:15]
	v_mfma_f32_16x16x32_bf16 v[8:11], v[158:161], v[214:217], v[8:11]
	v_mfma_f32_16x16x32_bf16 v[60:63], v[154:157], v[194:197], v[60:63]
	v_mfma_f32_16x16x32_bf16 v[56:59], v[162:165], v[194:197], v[56:59]
	v_mfma_f32_16x16x32_bf16 v[44:47], v[154:157], v[202:205], v[44:47]
	v_mfma_f32_16x16x32_bf16 v[40:43], v[162:165], v[202:205], v[40:43]
	v_mfma_f32_16x16x32_bf16 v[28:31], v[154:157], v[210:213], v[28:31]
	v_mfma_f32_16x16x32_bf16 v[24:27], v[162:165], v[210:213], v[24:27]
	v_mfma_f32_16x16x32_bf16 v[12:15], v[154:157], v[218:221], v[12:15]
	v_mfma_f32_16x16x32_bf16 v[8:11], v[162:165], v[218:221], v[8:11]
	s_setprio 0
	s_setprio 1
	v_mfma_f32_16x16x32_bf16 v[52:55], v[166:169], v[190:193], v[52:55]
	v_mfma_f32_16x16x32_bf16 v[48:51], v[174:177], v[190:193], v[48:51]
	v_mfma_f32_16x16x32_bf16 v[36:39], v[166:169], v[198:201], v[36:39]
	v_mfma_f32_16x16x32_bf16 v[32:35], v[174:177], v[198:201], v[32:35]
	v_mfma_f32_16x16x32_bf16 v[20:23], v[166:169], v[206:209], v[20:23]
	v_mfma_f32_16x16x32_bf16 v[16:19], v[174:177], v[206:209], v[16:19]
	v_mfma_f32_16x16x32_bf16 v[4:7], v[166:169], v[214:217], v[4:7]
	v_mfma_f32_16x16x32_bf16 v[0:3], v[174:177], v[214:217], v[0:3]
	v_mfma_f32_16x16x32_bf16 v[52:55], v[170:173], v[194:197], v[52:55]
	v_mfma_f32_16x16x32_bf16 v[48:51], v[178:181], v[194:197], v[48:51]
	v_mfma_f32_16x16x32_bf16 v[36:39], v[170:173], v[202:205], v[36:39]
	v_mfma_f32_16x16x32_bf16 v[32:35], v[178:181], v[202:205], v[32:35]
	v_mfma_f32_16x16x32_bf16 v[20:23], v[170:173], v[210:213], v[20:23]
	v_mfma_f32_16x16x32_bf16 v[16:19], v[178:181], v[210:213], v[16:19]
	v_mfma_f32_16x16x32_bf16 v[4:7], v[170:173], v[218:221], v[4:7]
	v_mfma_f32_16x16x32_bf16 v[0:3], v[178:181], v[218:221], v[0:3]
	s_setprio 0
	s_barrier
	s_add_i32 s64, s64, 2
	s_add_u32 s28, s28, 0x100
	s_addc_u32 s29, s29, 0
	s_add_u32 s62, s62, 0x100
	s_addc_u32 s63, s63, 0
	s_cmp_gt_u32 s64, 13
	s_cbranch_scc0 .LBB0_212
	s_and_b64 vcc, exec, s[16:17]
	s_cbranch_vccz .LBB0_215
	s_barrier
.LBB0_215:
	v_lshl_or_b32 v146, s59, 7, v150
	v_lshl_add_u32 v154, s26, 8, v148
	v_ashrrev_i32_e32 v147, 31, v146
	v_mov_b64_e32 v[144:145], s[12:13]
	v_mad_i64_i32 v[156:157], s[0:1], v154, s58, v[144:145]
	v_lshlrev_b64 v[146:147], 1, v[146:147]
	v_lshl_add_u64 v[156:157], v[156:157], 0, v[146:147]
	s_mov_b32 s98, 0xbfb8aa3b
	s_mov_b32 s100, 1.0
	v_pk_mul_f32 v[242:243], v[124:125], s[98:99] op_sel_hi:[1,0]
	v_pk_mul_f32 v[244:245], v[126:127], s[98:99] op_sel_hi:[1,0]
	v_pk_mul_f32 v[246:247], v[120:121], s[98:99] op_sel_hi:[1,0]
	v_pk_mul_f32 v[248:249], v[122:123], s[98:99] op_sel_hi:[1,0]
	v_exp_f32_e32 v242, v242
	v_exp_f32_e32 v243, v243
	v_exp_f32_e32 v244, v244
	v_exp_f32_e32 v245, v245
	v_exp_f32_e32 v246, v246
	v_exp_f32_e32 v247, v247
	v_exp_f32_e32 v248, v248
	v_exp_f32_e32 v249, v249
	v_pk_add_f32 v[242:243], v[242:243], s[100:101] op_sel_hi:[1,0]
	v_pk_add_f32 v[244:245], v[244:245], s[100:101] op_sel_hi:[1,0]
	v_pk_add_f32 v[246:247], v[246:247], s[100:101] op_sel_hi:[1,0]
	v_pk_add_f32 v[248:249], v[248:249], s[100:101] op_sel_hi:[1,0]
	v_rcp_f32_e32 v242, v242
	v_rcp_f32_e32 v243, v243
	v_rcp_f32_e32 v244, v244
	v_rcp_f32_e32 v245, v245
	v_rcp_f32_e32 v246, v246
	v_rcp_f32_e32 v247, v247
	v_rcp_f32_e32 v248, v248
	v_rcp_f32_e32 v249, v249
	v_pk_mul_f32 v[242:243], v[124:125], v[242:243]
	v_pk_mul_f32 v[244:245], v[126:127], v[244:245]
	v_pk_mul_f32 v[246:247], v[120:121], v[246:247]
	v_pk_mul_f32 v[248:249], v[122:123], v[248:249]
	v_pk_mul_f32 v[242:243], v[242:243], v[116:117]
	v_pk_mul_f32 v[244:245], v[244:245], v[118:119]
	v_pk_mul_f32 v[246:247], v[246:247], v[112:113]
	v_pk_mul_f32 v[248:249], v[248:249], v[114:115]
	v_cvt_pk_bf16_f32 v116, v242, v243
	v_cvt_pk_bf16_f32 v117, v244, v245
	v_cvt_pk_bf16_f32 v118, v246, v247
	v_cvt_pk_bf16_f32 v119, v248, v249
	global_store_dwordx4 v[156:157], v[116:119], off
	v_or_b32_e32 v112, 16, v154
; __device__ __forceinline__ unsigned cvt_pk_bf16(float lo, float hi) { unsigned r; asm volatile("v_cvt_pk_bf16_f32 %0, %1, %2" : "=v"(r) : "v"(lo), "v"(hi)); return r; }
; __device__ __forceinline__ float silu_f(float x) { return x * sigmoid_f(x); }
;     __device__ __forceinline__ void operator()(const f32x4 (&acc)[2][2][4][2], const Unit& u, int wr, int wc, int fr, int fq) const {
;         const int row0 = u.pm * BM + wr * 64 + fr; const int col0 = u.pn * HALF + wc * 32 + 8 * fq;
; #pragma unroll
;         for (int ai = 0; ai < 2; ++ai)
; #pragma unroll
;             for (int m = 0; m < 4; ++m) {
;                 bf16_t* rowp = O + (size_t)(row0 + ai * HALF + m * 16) * ldc + col0;
;                 const f32x4 g0 = acc[ai][0][m][0], g1 = acc[ai][0][m][1], u0 = acc[ai][1][m][0], u1 = acc[ai][1][m][1];
;                 u32x4 w;
;                 w.x = cvt_pk_bf16(silu_f(g0[0]) * u0[0], silu_f(g0[1]) * u0[1]); w.y = cvt_pk_bf16(silu_f(g0[2]) * u0[2], silu_f(g0[3]) * u0[3]);
;                 w.z = cvt_pk_bf16(silu_f(g1[0]) * u1[0], silu_f(g1[1]) * u1[1]); w.w = cvt_pk_bf16(silu_f(g1[2]) * u1[2], silu_f(g1[3]) * u1[3]);
;                 *(u32x4*)rowp = w;
	v_mad_i64_i32 v[112:113], s[0:1], v112, s58, v[144:145]
	v_lshl_add_u64 v[112:113], v[112:113], 0, v[146:147]
	v_pk_mul_f32 v[242:243], v[108:109], s[98:99] op_sel_hi:[1,0]
	v_pk_mul_f32 v[244:245], v[110:111], s[98:99] op_sel_hi:[1,0]
	v_pk_mul_f32 v[246:247], v[104:105], s[98:99] op_sel_hi:[1,0]
	v_pk_mul_f32 v[248:249], v[106:107], s[98:99] op_sel_hi:[1,0]
	v_exp_f32_e32 v242, v242
	v_exp_f32_e32 v243, v243
	v_exp_f32_e32 v244, v244
	v_exp_f32_e32 v245, v245
	v_exp_f32_e32 v246, v246
	v_exp_f32_e32 v247, v247
	v_exp_f32_e32 v248, v248
	v_exp_f32_e32 v249, v249
	v_pk_add_f32 v[242:243], v[242:243], s[100:101] op_sel_hi:[1,0]
	v_pk_add_f32 v[244:245], v[244:245], s[100:101] op_sel_hi:[1,0]
	v_pk_add_f32 v[246:247], v[246:247], s[100:101] op_sel_hi:[1,0]
	v_pk_add_f32 v[248:249], v[248:249], s[100:101] op_sel_hi:[1,0]
	v_rcp_f32_e32 v242, v242
	v_rcp_f32_e32 v243, v243
	v_rcp_f32_e32 v244, v244
	v_rcp_f32_e32 v245, v245
	v_rcp_f32_e32 v246, v246
	v_rcp_f32_e32 v247, v247
	v_rcp_f32_e32 v248, v248
	v_rcp_f32_e32 v249, v249
	v_pk_mul_f32 v[242:243], v[108:109], v[242:243]
	v_pk_mul_f32 v[244:245], v[110:111], v[244:245]
	v_pk_mul_f32 v[246:247], v[104:105], v[246:247]
	v_pk_mul_f32 v[248:249], v[106:107], v[248:249]
	v_pk_mul_f32 v[242:243], v[242:243], v[100:101]
	v_pk_mul_f32 v[244:245], v[244:245], v[102:103]
	v_pk_mul_f32 v[246:247], v[246:247], v[96:97]
	v_pk_mul_f32 v[248:249], v[248:249], v[98:99]
	v_cvt_pk_bf16_f32 v100, v242, v243
	v_cvt_pk_bf16_f32 v101, v244, v245
	v_cvt_pk_bf16_f32 v102, v246, v247
	v_cvt_pk_bf16_f32 v103, v248, v249
	global_store_dwordx4 v[112:113], v[100:103], off
	v_or_b32_e32 v96, 32, v154
	v_mad_i64_i32 v[96:97], s[0:1], v96, s58, v[144:145]
	v_lshl_add_u64 v[96:97], v[96:97], 0, v[146:147]
	v_pk_mul_f32 v[242:243], v[92:93], s[98:99] op_sel_hi:[1,0]
	v_pk_mul_f32 v[244:245], v[94:95], s[98:99] op_sel_hi:[1,0]
	v_pk_mul_f32 v[246:247], v[88:89], s[98:99] op_sel_hi:[1,0]
	v_pk_mul_f32 v[248:249], v[90:91], s[98:99] op_sel_hi:[1,0]
	v_exp_f32_e32 v242, v242
	v_exp_f32_e32 v243, v243
	v_exp_f32_e32 v244, v244
	v_exp_f32_e32 v245, v245
	v_exp_f32_e32 v246, v246
	v_exp_f32_e32 v247, v247
	v_exp_f32_e32 v248, v248
	v_exp_f32_e32 v249, v249
	v_pk_add_f32 v[242:243], v[242:243], s[100:101] op_sel_hi:[1,0]
	v_pk_add_f32 v[244:245], v[244:245], s[100:101] op_sel_hi:[1,0]
	v_pk_add_f32 v[246:247], v[246:247], s[100:101] op_sel_hi:[1,0]
	v_pk_add_f32 v[248:249], v[248:249], s[100:101] op_sel_hi:[1,0]
	v_rcp_f32_e32 v242, v242
	v_rcp_f32_e32 v243, v243
	v_rcp_f32_e32 v244, v244
	v_rcp_f32_e32 v245, v245
	v_rcp_f32_e32 v246, v246
	v_rcp_f32_e32 v247, v247
	v_rcp_f32_e32 v248, v248
	v_rcp_f32_e32 v249, v249
	v_pk_mul_f32 v[242:243], v[92:93], v[242:243]
	v_pk_mul_f32 v[244:245], v[94:95], v[244:245]
	v_pk_mul_f32 v[246:247], v[88:89], v[246:247]
	v_pk_mul_f32 v[248:249], v[90:91], v[248:249]
	v_pk_mul_f32 v[242:243], v[242:243], v[84:85]
	v_pk_mul_f32 v[244:245], v[244:245], v[86:87]
	v_pk_mul_f32 v[246:247], v[246:247], v[80:81]
	v_pk_mul_f32 v[248:249], v[248:249], v[82:83]
	v_cvt_pk_bf16_f32 v84, v242, v243
	v_cvt_pk_bf16_f32 v85, v244, v245
	v_cvt_pk_bf16_f32 v86, v246, v247
	v_cvt_pk_bf16_f32 v87, v248, v249
	global_store_dwordx4 v[96:97], v[84:87], off
	v_or_b32_e32 v80, 48, v154
	v_mad_i64_i32 v[80:81], s[0:1], v80, s58, v[144:145]
	v_lshl_add_u64 v[80:81], v[80:81], 0, v[146:147]
	v_pk_mul_f32 v[242:243], v[76:77], s[98:99] op_sel_hi:[1,0]
	v_pk_mul_f32 v[244:245], v[78:79], s[98:99] op_sel_hi:[1,0]
	v_pk_mul_f32 v[246:247], v[72:73], s[98:99] op_sel_hi:[1,0]
	v_pk_mul_f32 v[248:249], v[74:75], s[98:99] op_sel_hi:[1,0]
	v_exp_f32_e32 v242, v242
	v_exp_f32_e32 v243, v243
	v_exp_f32_e32 v244, v244
	v_exp_f32_e32 v245, v245
	v_exp_f32_e32 v246, v246
	v_exp_f32_e32 v247, v247
	v_exp_f32_e32 v248, v248
	v_exp_f32_e32 v249, v249
	v_pk_add_f32 v[242:243], v[242:243], s[100:101] op_sel_hi:[1,0]
	v_pk_add_f32 v[244:245], v[244:245], s[100:101] op_sel_hi:[1,0]
	v_pk_add_f32 v[246:247], v[246:247], s[100:101] op_sel_hi:[1,0]
	v_pk_add_f32 v[248:249], v[248:249], s[100:101] op_sel_hi:[1,0]
	v_rcp_f32_e32 v242, v242
	v_rcp_f32_e32 v243, v243
	v_rcp_f32_e32 v244, v244
	v_rcp_f32_e32 v245, v245
	v_rcp_f32_e32 v246, v246
	v_rcp_f32_e32 v247, v247
	v_rcp_f32_e32 v248, v248
	v_rcp_f32_e32 v249, v249
	v_pk_mul_f32 v[242:243], v[76:77], v[242:243]
	v_pk_mul_f32 v[244:245], v[78:79], v[244:245]
	v_pk_mul_f32 v[246:247], v[72:73], v[246:247]
	v_pk_mul_f32 v[248:249], v[74:75], v[248:249]
	v_pk_mul_f32 v[242:243], v[242:243], v[68:69]
	v_pk_mul_f32 v[244:245], v[244:245], v[70:71]
	v_pk_mul_f32 v[246:247], v[246:247], v[64:65]
	v_pk_mul_f32 v[248:249], v[248:249], v[66:67]
	v_cvt_pk_bf16_f32 v68, v242, v243
	v_cvt_pk_bf16_f32 v69, v244, v245
	v_cvt_pk_bf16_f32 v70, v246, v247
	v_cvt_pk_bf16_f32 v71, v248, v249
	global_store_dwordx4 v[80:81], v[68:71], off
	v_add_u32_e32 v64, 0x80, v154
	v_mad_i64_i32 v[64:65], s[0:1], v64, s58, v[144:145]
	v_lshl_add_u64 v[64:65], v[64:65], 0, v[146:147]
	v_pk_mul_f32 v[242:243], v[60:61], s[98:99] op_sel_hi:[1,0]
	v_pk_mul_f32 v[244:245], v[62:63], s[98:99] op_sel_hi:[1,0]
	v_pk_mul_f32 v[246:247], v[56:57], s[98:99] op_sel_hi:[1,0]
	v_pk_mul_f32 v[248:249], v[58:59], s[98:99] op_sel_hi:[1,0]
	v_exp_f32_e32 v242, v242
	v_exp_f32_e32 v243, v243
	v_exp_f32_e32 v244, v244
	v_exp_f32_e32 v245, v245
	v_exp_f32_e32 v246, v246
	v_exp_f32_e32 v247, v247
	v_exp_f32_e32 v248, v248
	v_exp_f32_e32 v249, v249
	v_pk_add_f32 v[242:243], v[242:243], s[100:101] op_sel_hi:[1,0]
	v_pk_add_f32 v[244:245], v[244:245], s[100:101] op_sel_hi:[1,0]
	v_pk_add_f32 v[246:247], v[246:247], s[100:101] op_sel_hi:[1,0]
; __device__ __forceinline__ unsigned cvt_pk_bf16(float lo, float hi) { unsigned r; asm volatile("v_cvt_pk_bf16_f32 %0, %1, %2" : "=v"(r) : "v"(lo), "v"(hi)); return r; }
; __device__ __forceinline__ float silu_f(float x) { return x * sigmoid_f(x); }
; #define PG8_BAR __builtin_amdgcn_s_barrier()
;     __device__ __forceinline__ void operator()(const f32x4 (&acc)[2][2][4][2], const Unit& u, int wr, int wc, int fr, int fq) const {
;         const int row0 = u.pm * BM + wr * 64 + fr; const int col0 = u.pn * HALF + wc * 32 + 8 * fq;
; #pragma unroll
;         for (int ai = 0; ai < 2; ++ai)
; #pragma unroll
;             for (int m = 0; m < 4; ++m) {
;                 bf16_t* rowp = O + (size_t)(row0 + ai * HALF + m * 16) * ldc + col0;
;                 const f32x4 g0 = acc[ai][0][m][0], g1 = acc[ai][0][m][1], u0 = acc[ai][1][m][0], u1 = acc[ai][1][m][1];
;                 u32x4 w;
;                 w.x = cvt_pk_bf16(silu_f(g0[0]) * u0[0], silu_f(g0[1]) * u0[1]); w.y = cvt_pk_bf16(silu_f(g0[2]) * u0[2], silu_f(g0[3]) * u0[3]);
;                 w.z = cvt_pk_bf16(silu_f(g1[0]) * u1[0], silu_f(g1[1]) * u1[1]); w.w = cvt_pk_bf16(silu_f(g1[2]) * u1[2], silu_f(g1[3]) * u1[3]);
;                 *(u32x4*)rowp = w;
; template <class Epi, class Sched, bool ALIGN_EPI = false, bool SP2 = false>
; __device__ __forceinline__ void gemm_phase(PG8_LAS unsigned char* lds, const Gemm g, const Sched& S, const Epi& E) {
;     ...
;         if constexpr (!Epi::AFTER_DRAIN) { E(acc, cur, wr, wc, fr, fq); S.done(cur); }
;         if (!has_next) break;
; #pragma unroll
;         for (int a = 0; a < 2; ++a)
; #pragma unroll
;             for (int b = 0; b < 2; ++b)
; #pragma unroll
;                 for (int m = 0; m < 4; ++m)
; #pragma unroll
;                     for (int n = 0; n < 2; ++n) acc[a][b][m][n] = (f32x4){0.f, 0.f, 0.f, 0.f};
;         cur = nxt; cA = nA; cB = nB; ++ui;
;         if constexpr (ALIGN_EPI) { if (wr == 1) PG8_BAR; }
	v_pk_add_f32 v[248:249], v[248:249], s[100:101] op_sel_hi:[1,0]
	v_rcp_f32_e32 v242, v242
	v_rcp_f32_e32 v243, v243
	v_rcp_f32_e32 v244, v244
	v_rcp_f32_e32 v245, v245
	v_rcp_f32_e32 v246, v246
	v_rcp_f32_e32 v247, v247
	v_rcp_f32_e32 v248, v248
	v_rcp_f32_e32 v249, v249
	v_pk_mul_f32 v[242:243], v[60:61], v[242:243]
	v_pk_mul_f32 v[244:245], v[62:63], v[244:245]
	v_pk_mul_f32 v[246:247], v[56:57], v[246:247]
	v_pk_mul_f32 v[248:249], v[58:59], v[248:249]
	v_pk_mul_f32 v[242:243], v[242:243], v[52:53]
	v_pk_mul_f32 v[244:245], v[244:245], v[54:55]
	v_pk_mul_f32 v[246:247], v[246:247], v[48:49]
	v_pk_mul_f32 v[248:249], v[248:249], v[50:51]
	v_cvt_pk_bf16_f32 v52, v242, v243
	v_cvt_pk_bf16_f32 v53, v244, v245
	v_cvt_pk_bf16_f32 v54, v246, v247
	v_cvt_pk_bf16_f32 v55, v248, v249
	global_store_dwordx4 v[64:65], v[52:55], off
	v_add_u32_e32 v48, 0x90, v154
	v_mad_i64_i32 v[48:49], s[0:1], v48, s58, v[144:145]
	v_lshl_add_u64 v[48:49], v[48:49], 0, v[146:147]
	v_pk_mul_f32 v[242:243], v[44:45], s[98:99] op_sel_hi:[1,0]
	v_pk_mul_f32 v[244:245], v[46:47], s[98:99] op_sel_hi:[1,0]
	v_pk_mul_f32 v[246:247], v[40:41], s[98:99] op_sel_hi:[1,0]
	v_pk_mul_f32 v[248:249], v[42:43], s[98:99] op_sel_hi:[1,0]
	v_exp_f32_e32 v242, v242
	v_exp_f32_e32 v243, v243
	v_exp_f32_e32 v244, v244
	v_exp_f32_e32 v245, v245
	v_exp_f32_e32 v246, v246
	v_exp_f32_e32 v247, v247
	v_exp_f32_e32 v248, v248
	v_exp_f32_e32 v249, v249
	v_pk_add_f32 v[242:243], v[242:243], s[100:101] op_sel_hi:[1,0]
	v_pk_add_f32 v[244:245], v[244:245], s[100:101] op_sel_hi:[1,0]
	v_pk_add_f32 v[246:247], v[246:247], s[100:101] op_sel_hi:[1,0]
	v_pk_add_f32 v[248:249], v[248:249], s[100:101] op_sel_hi:[1,0]
	v_rcp_f32_e32 v242, v242
	v_rcp_f32_e32 v243, v243
	v_rcp_f32_e32 v244, v244
	v_rcp_f32_e32 v245, v245
	v_rcp_f32_e32 v246, v246
	v_rcp_f32_e32 v247, v247
	v_rcp_f32_e32 v248, v248
	v_rcp_f32_e32 v249, v249
	v_pk_mul_f32 v[242:243], v[44:45], v[242:243]
	v_pk_mul_f32 v[244:245], v[46:47], v[244:245]
	v_pk_mul_f32 v[246:247], v[40:41], v[246:247]
	v_pk_mul_f32 v[248:249], v[42:43], v[248:249]
	v_pk_mul_f32 v[242:243], v[242:243], v[36:37]
	v_pk_mul_f32 v[244:245], v[244:245], v[38:39]
	v_pk_mul_f32 v[246:247], v[246:247], v[32:33]
	v_pk_mul_f32 v[248:249], v[248:249], v[34:35]
	v_cvt_pk_bf16_f32 v36, v242, v243
	v_cvt_pk_bf16_f32 v37, v244, v245
	v_cvt_pk_bf16_f32 v38, v246, v247
	v_cvt_pk_bf16_f32 v39, v248, v249
	global_store_dwordx4 v[48:49], v[36:39], off
	v_add_u32_e32 v32, 0xa0, v154
	v_mad_i64_i32 v[32:33], s[0:1], v32, s58, v[144:145]
	v_lshl_add_u64 v[32:33], v[32:33], 0, v[146:147]
	v_pk_mul_f32 v[242:243], v[28:29], s[98:99] op_sel_hi:[1,0]
	v_pk_mul_f32 v[244:245], v[30:31], s[98:99] op_sel_hi:[1,0]
	v_pk_mul_f32 v[246:247], v[24:25], s[98:99] op_sel_hi:[1,0]
	v_pk_mul_f32 v[248:249], v[26:27], s[98:99] op_sel_hi:[1,0]
	v_exp_f32_e32 v242, v242
	v_exp_f32_e32 v243, v243
	v_exp_f32_e32 v244, v244
	v_exp_f32_e32 v245, v245
	v_exp_f32_e32 v246, v246
	v_exp_f32_e32 v247, v247
	v_exp_f32_e32 v248, v248
	v_exp_f32_e32 v249, v249
	v_pk_add_f32 v[242:243], v[242:243], s[100:101] op_sel_hi:[1,0]
	v_pk_add_f32 v[244:245], v[244:245], s[100:101] op_sel_hi:[1,0]
	v_pk_add_f32 v[246:247], v[246:247], s[100:101] op_sel_hi:[1,0]
	v_pk_add_f32 v[248:249], v[248:249], s[100:101] op_sel_hi:[1,0]
	v_rcp_f32_e32 v242, v242
	v_rcp_f32_e32 v243, v243
	v_rcp_f32_e32 v244, v244
	v_rcp_f32_e32 v245, v245
	v_rcp_f32_e32 v246, v246
	v_rcp_f32_e32 v247, v247
	v_rcp_f32_e32 v248, v248
	v_rcp_f32_e32 v249, v249
	v_pk_mul_f32 v[242:243], v[28:29], v[242:243]
	v_pk_mul_f32 v[244:245], v[30:31], v[244:245]
	v_pk_mul_f32 v[246:247], v[24:25], v[246:247]
	v_pk_mul_f32 v[248:249], v[26:27], v[248:249]
	v_pk_mul_f32 v[242:243], v[242:243], v[20:21]
	v_pk_mul_f32 v[244:245], v[244:245], v[22:23]
	v_pk_mul_f32 v[246:247], v[246:247], v[16:17]
	v_pk_mul_f32 v[248:249], v[248:249], v[18:19]
	v_cvt_pk_bf16_f32 v20, v242, v243
	v_cvt_pk_bf16_f32 v21, v244, v245
	v_cvt_pk_bf16_f32 v22, v246, v247
	v_cvt_pk_bf16_f32 v23, v248, v249
	global_store_dwordx4 v[32:33], v[20:23], off
	v_add_u32_e32 v16, 0xb0, v154
	v_mad_i64_i32 v[16:17], s[0:1], v16, s58, v[144:145]
	v_lshl_add_u64 v[16:17], v[16:17], 0, v[146:147]
	s_andn2_b64 vcc, exec, s[4:5]
	s_mov_b64 s[4:5], -1
	v_pk_mul_f32 v[242:243], v[12:13], s[98:99] op_sel_hi:[1,0]
	v_pk_mul_f32 v[244:245], v[14:15], s[98:99] op_sel_hi:[1,0]
	v_pk_mul_f32 v[246:247], v[8:9], s[98:99] op_sel_hi:[1,0]
	v_pk_mul_f32 v[248:249], v[10:11], s[98:99] op_sel_hi:[1,0]
	v_exp_f32_e32 v242, v242
	v_exp_f32_e32 v243, v243
	v_exp_f32_e32 v244, v244
	v_exp_f32_e32 v245, v245
	v_exp_f32_e32 v246, v246
	v_exp_f32_e32 v247, v247
	v_exp_f32_e32 v248, v248
	v_exp_f32_e32 v249, v249
	v_pk_add_f32 v[242:243], v[242:243], s[100:101] op_sel_hi:[1,0]
	v_pk_add_f32 v[244:245], v[244:245], s[100:101] op_sel_hi:[1,0]
	v_pk_add_f32 v[246:247], v[246:247], s[100:101] op_sel_hi:[1,0]
	v_pk_add_f32 v[248:249], v[248:249], s[100:101] op_sel_hi:[1,0]
	v_rcp_f32_e32 v242, v242
	v_rcp_f32_e32 v243, v243
	v_rcp_f32_e32 v244, v244
	v_rcp_f32_e32 v245, v245
	v_rcp_f32_e32 v246, v246
	v_rcp_f32_e32 v247, v247
	v_rcp_f32_e32 v248, v248
	v_rcp_f32_e32 v249, v249
	v_pk_mul_f32 v[242:243], v[12:13], v[242:243]
	v_pk_mul_f32 v[244:245], v[14:15], v[244:245]
	v_pk_mul_f32 v[246:247], v[8:9], v[246:247]
	v_pk_mul_f32 v[248:249], v[10:11], v[248:249]
	v_pk_mul_f32 v[242:243], v[242:243], v[4:5]
	v_pk_mul_f32 v[244:245], v[244:245], v[6:7]
	v_pk_mul_f32 v[246:247], v[246:247], v[0:1]
	v_pk_mul_f32 v[248:249], v[248:249], v[2:3]
	v_cvt_pk_bf16_f32 v4, v242, v243
	v_cvt_pk_bf16_f32 v5, v244, v245
	v_cvt_pk_bf16_f32 v6, v246, v247
	v_cvt_pk_bf16_f32 v7, v248, v249
	global_store_dwordx4 v[16:17], v[4:7], off
	s_cbranch_vccnz .LBB0_208
	s_andn2_b64 vcc, exec, s[8:9]
	s_cbranch_vccnz .LBB0_207
	s_barrier
	s_branch .LBB0_207

; #define PG8_STAGE(bufoff, gbase, voff) do { _Pragma("unroll") for (int _i = 0; _i < 2; ++_i) \
;         __builtin_amdgcn_global_load_lds((const unsigned*)((const char*)(gbase) + (voff)[_i]), (PG8_LAS unsigned*)(lds + (bufoff) + ldsw + _i * 8192), 16, 0, 0); } while (0)
; #define PG8_WAIT_V(n) asm volatile("s_waitcnt vmcnt(" #n ")" ::: "memory")
; #define PG8_BAR __builtin_amdgcn_s_barrier()
; template <class Epi, class Sched, bool ALIGN_EPI = false, bool SP2 = false>
; __device__ __forceinline__ void gemm_phase(PG8_LAS unsigned char* lds, const Gemm g, const Sched& S, const Epi& E) {
;     ...
;     for (int i = 0; i < 2; ++i) { int R, C; stage_rc(tid * 16 + i * 8192, R, C); const int Rb = Epi::PERM ? ((R & ~31) + perm32(R & 31)) : R;
;         voffA[i] = (unsigned)(R * K + C) * 2u; voffB[i] = (unsigned)(Rb * K + C) * 2u; }
;     ...
;     const char* cA = (const char*)g.A + (size_t)cur.pm * tstep; const char* cB = (const char*)g.Bt + (size_t)cur.pn * tstep;
;     S.a_ready(cur);
;     if constexpr (SP2) {
;         PG8_STAGE(PG8_SB(0, 0), cB, voffB); PG8_STAGE(PG8_SB(0, 1), cB + hstep, voffB); PG8_STAGE(PG8_SA(0, 0), cA, voffA); PG8_STAGE(PG8_SA(0, 1), cA + hstep, voffA);
;         if (wr == 1) PG8_BAR;
;         PG8_WAIT_V(2); PG8_BAR;
;         PG8_STAGE(PG8_SB(1, 0), cB + kstep, voffB); PG8_STAGE(PG8_SA(1, 0), cA + kstep, voffA); PG8_STAGE(PG8_SB(1, 1), cB + hstep + kstep, voffB);
.LBB0_485:
	s_andn2_b64 vcc, exec, s[14:15]
	s_cbranch_vccnz .LBB0_533
	v_ashrrev_i32_e32 v1, 31, v8
	v_lshrrev_b32_e32 v1, 26, v1
	v_add_u32_e32 v1, v8, v1
	v_ashrrev_i32_e32 v9, 6, v1
	v_bfe_i32 v1, v8, 27, 1
	v_lshlrev_b32_e32 v0, 4, v8
	v_lshrrev_b32_e32 v1, 22, v1
	v_add_u32_e32 v1, v0, v1
	v_and_b32_e32 v1, 0xfffffc00, v1
	v_sub_u32_e32 v1, v0, v1
	v_lshrrev_b32_e32 v2, 4, v1
	v_bitop3_b32 v2, v2, v1, 32 bitop3:0x6c
	v_ashrrev_i32_e32 v1, 31, v1
	v_lshrrev_b32_e32 v1, 26, v1
	v_add_u32_e32 v1, v2, v1
	v_ashrrev_i32_e32 v10, 6, v1
	s_load_dwordx2 s[0:1], s[10:11], 0x110
	s_load_dwordx2 s[14:15], s[12:13], 0x110
	v_lshlrev_b32_e32 v3, 3, v9
	v_mul_i32_i24_e32 v4, 64, v10
	v_and_b32_e32 v3, -16, v3
	v_sub_u32_e32 v2, v2, v4
	v_mov_b32_e32 v4, 1
	v_add_u32_e32 v1, v10, v3
	v_lshlrev_b32_e32 v3, 5, v9
	v_ashrrev_i16_sdwa v2, v4, sext(v2) dst_sel:DWORD dst_unused:UNUSED_PAD src0_sel:DWORD src1_sel:BYTE_0
	v_and_b32_e32 v3, 32, v3
	v_bfe_i32 v11, v2, 0, 16
	s_waitcnt lgkmcnt(0)
	s_add_u32 s38, s0, 0x3000000
	v_and_b32_e32 v6, 3, v10
	s_mov_b32 s0, 0x1fffe0
	v_add_lshl_u32 v3, v3, v11, 1
	v_add_u32_e32 v0, 0x2000, v0
	v_lshlrev_b32_e32 v2, 1, v1
	v_lshrrev_b32_e32 v5, 2, v1
	v_and_or_b32 v6, v1, s0, v6
	v_lshl_add_u32 v128, v1, 11, v3
	v_ashrrev_i32_e32 v1, 31, v0
	v_lshrrev_b32_e32 v1, 22, v1
	v_add_u32_e32 v1, v0, v1
	v_ashrrev_i32_e32 v12, 10, v1
	v_mul_i32_i24_e32 v1, 0x400, v12
	v_sub_u32_e32 v0, v0, v1
	v_and_b32_e32 v2, 24, v2
	v_and_b32_e32 v5, 4, v5
	v_lshrrev_b32_e32 v1, 4, v0
	v_or3_b32 v2, v6, v5, v2
	v_bitop3_b32 v0, v1, v0, 32 bitop3:0x6c
	v_lshl_add_u32 v130, v2, 11, v3
	v_ashrrev_i32_e32 v2, 31, v0
	v_lshrrev_b32_e32 v2, 26, v2
	v_add_u32_e32 v2, v0, v2
	s_addc_u32 s39, s1, 0
	v_lshlrev_b32_e32 v1, 3, v12
	v_ashrrev_i32_e32 v13, 6, v2
	v_and_b32_e32 v2, 0xc0, v2
	s_add_u32 s40, s14, 0x1200000
	v_and_b32_e32 v1, -16, v1
	v_sub_u32_e32 v0, v0, v2
	s_addc_u32 s41, s15, 0
	v_add_u32_e32 v1, v13, v1
	v_ashrrev_i16_sdwa v0, v4, sext(v0) dst_sel:DWORD dst_unused:UNUSED_PAD src0_sel:DWORD src1_sel:BYTE_0
	v_and_b32_e32 v4, 3, v13
	s_ashr_i32 s14, s16, 6
	s_ashr_i32 s27, s26, 31
	s_ashr_i32 s29, s28, 31
	s_ashr_i32 s17, s16, 8
	v_and_or_b32 v4, v1, s0, v4
	s_lshl_b32 s42, s14, 10
	s_lshl_b64 s[0:1], s[26:27], 19
	s_lshl_b64 s[10:11], s[28:29], 19
	s_add_u32 s34, s40, s10
	v_lshlrev_b32_e32 v3, 5, v12
	v_bfe_i32 v14, v0, 0, 16
	v_lshlrev_b32_e32 v0, 1, v1
	v_lshrrev_b32_e32 v2, 2, v1
	s_addc_u32 s35, s41, s11
	s_add_i32 s43, s42, 0
	v_and_b32_e32 v3, 32, v3
	v_and_b32_e32 v0, 24, v0
	v_and_b32_e32 v2, 4, v2
	s_add_i32 m0, s43, 0x10000
	v_or3_b32 v0, v4, v2, v0
	v_add_lshl_u32 v2, v3, v14, 1
	v_bfe_u32 v239, v8, 3, 3
	v_and_b32_e32 v240, 7, v8
	v_xor_b32_e32 v240, v240, v239
	v_lshlrev_b32_e32 v240, 4, v240
	v_lshrrev_b32_e32 v241, 6, v8
	v_lshl_add_u32 v242, v241, 3, v239
	v_mov_b32_e32 v243, 0x800
	v_mad_u32_u24 v128, v242, v243, v240
	v_add_u32_e32 v132, 0x20000, v128
	v_lshrrev_b32_e32 v244, 2, v241
	v_lshlrev_b32_e32 v244, 5, v244
	v_and_b32_e32 v245, 1, v241
	v_lshrrev_b32_e32 v246, 2, v239
	v_lshl_add_u32 v245, v245, 1, v246
	v_lshl_add_u32 v244, v245, 3, v244
	v_bfe_u32 v245, v241, 1, 1
	v_lshl_add_u32 v244, v245, 2, v244
	v_and_b32_e32 v245, 3, v239
	v_add_u32_e32 v244, v244, v245
	v_mad_u32_u24 v130, v244, v243, v240
	v_add_u32_e32 v134, 0x20000, v130
	global_load_lds_dwordx4 v130, s[34:35]
	s_add_i32 m0, s43, 0x12000
	s_add_u32 s10, s34, 0x40000
	global_load_lds_dwordx4 v134, s[34:35]
	s_addc_u32 s11, s35, 0
	s_add_i32 m0, s43, 0x14000
	global_load_lds_dwordx4 v130, s[10:11]
	s_add_i32 m0, s43, 0x16000
	s_add_u32 s30, s38, s0
	s_addc_u32 s31, s39, s1
	s_add_i32 s47, s43, 0x2000
	global_load_lds_dwordx4 v134, s[10:11]
	s_mov_b32 m0, s43
	s_add_u32 s0, s30, 0x40000
	global_load_lds_dwordx4 v128, s[30:31]
	s_mov_b32 m0, s47
	s_addc_u32 s1, s31, 0
	s_add_i32 s52, s43, 0x4000
	global_load_lds_dwordx4 v132, s[30:31]
	s_mov_b32 m0, s52
	s_add_i32 s53, s43, 0x6000
	global_load_lds_dwordx4 v128, s[0:1]
	s_mov_b32 m0, s53
	s_load_dwordx2 s[8:9], s[8:9], 0x110
	global_load_lds_dwordx4 v132, s[0:1]
	v_mov_b32_e32 v131, 0
	v_mov_b32_e32 v135, v131
	v_mov_b32_e32 v129, v131
	v_mov_b32_e32 v133, v131
	s_cmp_eq_u32 s17, 1
	s_movk_i32 s54, 0x400
	s_mov_b32 s55, 0
	v_lshl_add_u64 v[6:7], s[34:35], 0, v[130:131]
	v_lshl_add_u64 v[4:5], s[34:35], 0, v[134:135]
	v_lshl_add_u64 v[0:1], s[30:31], 0, v[128:129]
	s_cselect_b64 s[10:11], -1, 0
	s_cmp_lg_u32 s17, 1
	v_lshl_add_u64 v[2:3], s[30:31], 0, v[132:133]
	s_cbranch_scc1 .LBB0_488
	s_barrier
; #define PG8_STAGE(bufoff, gbase, voff) do { _Pragma("unroll") for (int _i = 0; _i < 2; ++_i) \
;         __builtin_amdgcn_global_load_lds((const unsigned*)((const char*)(gbase) + (voff)[_i]), (PG8_LAS unsigned*)(lds + (bufoff) + ldsw + _i * 8192), 16, 0, 0); } while (0)
; #define PG8_WAIT_V(n) asm volatile("s_waitcnt vmcnt(" #n ")" ::: "memory")
; #define PG8_BAR __builtin_amdgcn_s_barrier()
; template <class Epi, class Sched, bool ALIGN_EPI = false, bool SP2 = false>
; __device__ __forceinline__ void gemm_phase(PG8_LAS unsigned char* lds, const Gemm g, const Sched& S, const Epi& E) {
;     ...
;     for (int i = 0; i < 2; ++i) { int R, C; stage_rc(tid * 16 + i * 8192, R, C); const int Rb = Epi::PERM ? ((R & ~31) + perm32(R & 31)) : R;
;         voffA[i] = (unsigned)(R * K + C) * 2u; voffB[i] = (unsigned)(Rb * K + C) * 2u; }
;     const size_t kstep = (size_t)(BK * 2);
;     const size_t hstep = (size_t)HALF * K * 2;
;     const size_t tstep = 2 * hstep;
;     const unsigned ldsw = (unsigned)wid * 1024u;
;     const int aoff = lds_byte(wr * 64 + fr, fq * 8), boff = lds_byte(wc * 32 + fr, fq * 8);
;     ...
;         PG8_STAGE(PG8_SB(1, 0), cB + kstep, voffB); PG8_STAGE(PG8_SA(1, 0), cA + kstep, voffA); PG8_STAGE(PG8_SB(1, 1), cB + hstep + kstep, voffB);
;         PG8_WAIT_V(6); PG8_BAR;
.LBB0_488:
	s_waitcnt lgkmcnt(0)
	s_add_u32 s12, s8, 0xb200000
	s_addc_u32 s13, s9, 0
	s_lshl_b32 s0, s14, 5
	s_mov_b64 s[14:15], 0x80
	s_and_b32 s8, s0, 0x60
	s_add_i32 m0, s43, 0x18000
	v_lshl_add_u64 v[6:7], v[6:7], 0, s[14:15]
	s_lshl_b32 s3, s17, 13
	s_lshl_b32 s9, s8, 7
	s_waitcnt vmcnt(2)
	s_barrier
	global_load_lds_dwordx4 v[6:7], off
	v_lshl_add_u64 v[4:5], v[4:5], 0, s[14:15]
	s_add_i32 m0, s43, 0x1a000
	s_add_i32 s56, s43, 0x8000
	s_add_i32 s57, s43, 0xa000
	global_load_lds_dwordx4 v[4:5], off
	v_lshl_add_u64 v[0:1], v[0:1], 0, s[14:15]
	s_mov_b32 m0, s56
	s_add_u32 s0, s34, 0x40080
	global_load_lds_dwordx4 v[0:1], off
	v_lshl_add_u64 v[0:1], v[2:3], 0, s[14:15]
	s_mov_b32 m0, s57
	s_addc_u32 s1, s35, 0
	global_load_lds_dwordx4 v[0:1], off
	s_add_i32 m0, s43, 0x1c000
	v_lshl_add_u64 v[0:1], s[0:1], 0, v[130:131]
	global_load_lds_dwordx4 v[0:1], off
	v_lshl_add_u64 v[0:1], s[0:1], 0, v[134:135]
	s_add_i32 m0, s43, 0x1e000
	s_cmpk_lt_u32 s16, 0x100
	global_load_lds_dwordx4 v[0:1], off
	v_lshrrev_b32_e32 v1, 1, v8
	v_and_b32_e32 v1, 24, v1
	v_and_b32_e32 v0, 15, v8
	v_lshlrev_b32_e32 v2, 1, v1
	v_lshl_or_b32 v146, s17, 6, v0
	v_lshl_or_b32 v0, v0, 6, v2
	v_lshlrev_b32_e32 v2, 2, v8
	v_and_b32_e32 v2, 32, v2
	v_bitop3_b32 v3, v0, s3, v2 bitop3:0xde
	v_bitop3_b32 v147, v0, s9, v2 bitop3:0xde
	v_and_b32_e32 v239, 15, v8
	v_and_b32_e32 v240, 7, v239
	v_lshrrev_b32_e32 v239, 3, v239
	v_lshlrev_b32_e32 v239, 10, v239
	v_lshl_add_u32 v239, v240, 7, v239
	v_bfe_u32 v241, v8, 4, 2
	v_xor_b32_e32 v242, v241, v240
	v_or_b32_e32 v241, 4, v241
	v_xor_b32_e32 v243, v241, v240
	v_lshl_add_u32 v242, v242, 4, v239
	v_lshl_add_u32 v243, v243, 4, v239
	v_lshrrev_b32_e32 v244, 8, v8
	v_lshlrev_b32_e32 v244, 13, v244
	v_add_u32_e32 v3, v244, v242
	v_add_u32_e32 v233, v244, v243
	v_bfe_u32 v244, v8, 6, 2
	v_lshlrev_b32_e32 v244, 12, v244
	v_add_u32_e32 v147, v244, v242
	v_add_u32_e32 v234, v244, v243
	v_lshlrev_b32_e32 v0, 14, v9
	v_and_b32_e32 v0, 0xffff8000, v0
	v_or_b32_e32 v148, s8, v1
	v_lshl_add_u32 v0, v10, 11, v0
	v_and_b32_e32 v1, 1, v9
	v_lshl_or_b32 v0, v1, 6, v0
	v_lshl_add_u32 v136, v11, 1, v0
	v_mov_b32_e32 v136, v128
	v_lshlrev_b32_e32 v0, 14, v12
	v_and_b32_e32 v0, 0xffff8000, v0
	s_waitcnt vmcnt(6)
	v_lshl_add_u32 v0, v13, 11, v0
	v_and_b32_e32 v1, 1, v12
	s_cselect_b64 s[16:17], -1, 0
	v_lshl_or_b32 v0, v1, 6, v0
	s_add_i32 s62, 0, 0x10000
	s_add_i32 s63, 0, 0x14000
	s_ashr_i32 s58, s94, 31
	s_mov_b32 s59, s94
	s_ashr_i32 s60, s33, 31
	v_mov_b32_e32 v137, v131
	v_lshl_add_u32 v138, v14, 1, v0
	v_mov_b32_e32 v138, v132
	v_mov_b32_e32 v139, v131
	v_mov_b64_e32 v[140:141], 0x300
	v_mov_b64_e32 v[142:143], 0x2ff
	s_movk_i32 s61, 0x61
	v_add_u32_e32 v149, s62, v147
	v_add_u32_e32 v235, s62, v234
	v_add_u32_e32 v150, s63, v147
	v_add_u32_e32 v236, s63, v234
	v_add_u32_e32 v151, 0, v3
	s_movk_i32 s64, 0xc00
	s_barrier
	s_branch .LBB0_491

; #define PG8_STAGE(bufoff, gbase, voff) do { _Pragma("unroll") for (int _i = 0; _i < 2; ++_i) \
;         __builtin_amdgcn_global_load_lds((const unsigned*)((const char*)(gbase) + (voff)[_i]), (PG8_LAS unsigned*)(lds + (bufoff) + ldsw + _i * 8192), 16, 0, 0); } while (0)
; #define PG8_LDA(dst, b, h) do { _Pragma("unroll") for (int m = 0; m < 4; ++m) _Pragma("unroll") for (int k = 0; k < 2; ++k) dst[m][k] = *(const PG8_LAS bf16x8*)(lds + PG8_SA(b, h) + aoff + m * 2048 + k * 1024); } while (0)
; #define PG8_LDB(dst, b, h) do { _Pragma("unroll") for (int n = 0; n < 2; ++n) _Pragma("unroll") for (int k = 0; k < 2; ++k) dst[n][k] = *(const PG8_LAS bf16x8*)(lds + PG8_SB(b, h) + boff + n * 2048 + k * 1024); } while (0)
; #define PG8_MMA(ai, bj, At, Bt) do { __builtin_amdgcn_s_setprio(1); _Pragma("unroll") for (int m = 0; m < 4; ++m) _Pragma("unroll") for (int n = 0; n < 2; ++n) _Pragma("unroll") for (int k = 0; k < 2; ++k) \
;         acc[ai][bj][m][n] = __builtin_amdgcn_mfma_f32_16x16x32_bf16(Bt[n][k], At[m][k], acc[ai][bj][m][n], 0, 0, 0); __builtin_amdgcn_s_setprio(0); } while (0)
; #define PG8_WAIT_V(n) asm volatile("s_waitcnt vmcnt(" #n ")" ::: "memory")
; #define PG8_WAIT_L(n) asm volatile("s_waitcnt lgkmcnt(" #n ")" ::: "memory")
; #define PG8_BAR __builtin_amdgcn_s_barrier()
; #define PG8_SCHED __builtin_amdgcn_sched_barrier(0)
; template <class Epi, class Sched, bool ALIGN_EPI = false, bool SP2 = false>
; __device__ __forceinline__ void gemm_phase(PG8_LAS unsigned char* lds, const Gemm g, const Sched& S, const Epi& E) {
;     ...
;             PG8_LDB(B0, 0, 0); PG8_LDB(B1, 0, 1); PG8_SCHED; PG8_LDA(At, 0, 0); PG8_STAGE(PG8_SA(1, 1), a1 + hstep, voffA);
;             PG8_WAIT_V(8); PG8_WAIT_L(0); PG8_BAR; PG8_MMA(0, 0, At, B0); PG8_MMA(0, 1, At, B1); PG8_BAR; PG8_SCHED;
;             PG8_LDA(At, 0, 1); PG8_STAGE(PG8_SB(0, 0), b2, voffB); PG8_STAGE(PG8_SB(0, 1), b2 + hstep, voffB); PG8_STAGE(PG8_SA(0, 0), a2, voffA);
;             PG8_WAIT_V(8); PG8_WAIT_L(0); PG8_BAR; PG8_MMA(1, 0, At, B0); PG8_MMA(1, 1, At, B1); PG8_BAR; PG8_SCHED;
.LBB0_494:
	ds_read_b128 v[152:155], v149
	ds_read_b128 v[156:159], v235
	ds_read_b128 v[160:163], v149 offset:2048
	ds_read_b128 v[164:167], v235 offset:2048
	ds_read_b128 v[168:171], v150
	ds_read_b128 v[172:175], v236
	ds_read_b128 v[176:179], v150 offset:2048
	ds_read_b128 v[190:193], v236 offset:2048
	s_add_u32 s0, s30, 0xfffc0080
	s_addc_u32 s1, s31, -1
	s_cmp_eq_u32 s67, 12
	s_cselect_b32 s37, s21, s1
	s_cselect_b32 s36, s27, s0
	s_cselect_b32 s35, s19, s66
	s_cselect_b32 s34, s29, s65
	v_lshl_add_u64 v[144:145], s[30:31], 0, v[136:137]
	s_add_i32 m0, s43, 0xc000
	ds_read_b128 v[194:197], v151
	ds_read_b128 v[198:201], v233
	ds_read_b128 v[202:205], v151 offset:2048
	ds_read_b128 v[206:209], v233 offset:2048
	ds_read_b128 v[210:213], v151 offset:4096
	ds_read_b128 v[214:217], v233 offset:4096
	ds_read_b128 v[218:221], v151 offset:6144
	ds_read_b128 v[222:225], v233 offset:6144
	global_load_lds_dwordx4 v[144:145], off
	v_lshl_add_u64 v[144:145], s[30:31], 0, v[138:139]
	s_add_i32 m0, s43, 0xe000
	s_nop 0
	global_load_lds_dwordx4 v[144:145], off
	s_waitcnt vmcnt(8)
	s_waitcnt lgkmcnt(0)
	s_barrier
	s_setprio 1
	s_waitcnt lgkmcnt(0)
	v_mfma_f32_16x16x32_bf16 v[124:127], v[152:155], v[194:197], v[124:127]
	v_mfma_f32_16x16x32_bf16 v[120:123], v[160:163], v[194:197], v[120:123]
	v_mfma_f32_16x16x32_bf16 v[116:119], v[152:155], v[202:205], v[116:119]
	v_mfma_f32_16x16x32_bf16 v[112:115], v[160:163], v[202:205], v[112:115]
	v_mfma_f32_16x16x32_bf16 v[108:111], v[152:155], v[210:213], v[108:111]
	v_mfma_f32_16x16x32_bf16 v[104:107], v[160:163], v[210:213], v[104:107]
	v_mfma_f32_16x16x32_bf16 v[100:103], v[152:155], v[218:221], v[100:103]
	v_mfma_f32_16x16x32_bf16 v[96:99], v[160:163], v[218:221], v[96:99]
	v_mfma_f32_16x16x32_bf16 v[124:127], v[156:159], v[198:201], v[124:127]
	v_mfma_f32_16x16x32_bf16 v[120:123], v[164:167], v[198:201], v[120:123]
	v_mfma_f32_16x16x32_bf16 v[116:119], v[156:159], v[206:209], v[116:119]
	v_mfma_f32_16x16x32_bf16 v[112:115], v[164:167], v[206:209], v[112:115]
	v_mfma_f32_16x16x32_bf16 v[108:111], v[156:159], v[214:217], v[108:111]
	v_mfma_f32_16x16x32_bf16 v[104:107], v[164:167], v[214:217], v[104:107]
	v_mfma_f32_16x16x32_bf16 v[100:103], v[156:159], v[222:225], v[100:103]
	v_mfma_f32_16x16x32_bf16 v[96:99], v[164:167], v[222:225], v[96:99]
	s_setprio 0
	s_setprio 1
	v_mfma_f32_16x16x32_bf16 v[60:63], v[168:171], v[194:197], v[60:63]
	v_mfma_f32_16x16x32_bf16 v[56:59], v[176:179], v[194:197], v[56:59]
	v_mfma_f32_16x16x32_bf16 v[52:55], v[168:171], v[202:205], v[52:55]
	v_mfma_f32_16x16x32_bf16 v[48:51], v[176:179], v[202:205], v[48:51]
	v_mfma_f32_16x16x32_bf16 v[44:47], v[168:171], v[210:213], v[44:47]
	v_mfma_f32_16x16x32_bf16 v[40:43], v[176:179], v[210:213], v[40:43]
	v_mfma_f32_16x16x32_bf16 v[36:39], v[168:171], v[218:221], v[36:39]
	v_mfma_f32_16x16x32_bf16 v[32:35], v[176:179], v[218:221], v[32:35]
	v_mfma_f32_16x16x32_bf16 v[60:63], v[172:175], v[198:201], v[60:63]
	v_mfma_f32_16x16x32_bf16 v[56:59], v[190:193], v[198:201], v[56:59]
	v_mfma_f32_16x16x32_bf16 v[52:55], v[172:175], v[206:209], v[52:55]
	v_mfma_f32_16x16x32_bf16 v[48:51], v[190:193], v[206:209], v[48:51]
	v_mfma_f32_16x16x32_bf16 v[44:47], v[172:175], v[214:217], v[44:47]
	v_mfma_f32_16x16x32_bf16 v[40:43], v[190:193], v[214:217], v[40:43]
	v_mfma_f32_16x16x32_bf16 v[36:39], v[172:175], v[222:225], v[36:39]
	v_mfma_f32_16x16x32_bf16 v[32:35], v[190:193], v[222:225], v[32:35]
	s_setprio 0
	s_barrier
	s_add_i32 s0, s62, s42
	v_lshl_add_u64 v[144:145], s[34:35], 0, v[130:131]
	s_mov_b32 m0, s0
	ds_read_b128 v[194:197], v151 offset:16384
	ds_read_b128 v[198:201], v233 offset:16384
	ds_read_b128 v[202:205], v151 offset:18432
	ds_read_b128 v[206:209], v233 offset:18432
	ds_read_b128 v[210:213], v151 offset:20480
	ds_read_b128 v[214:217], v233 offset:20480
	ds_read_b128 v[218:221], v151 offset:22528
	ds_read_b128 v[222:225], v233 offset:22528
	global_load_lds_dwordx4 v[144:145], off
	s_add_i32 m0, s0, 0x2000
	s_add_u32 s0, s34, 0x40000
	v_lshl_add_u64 v[180:181], s[34:35], 0, v[134:135]
	s_addc_u32 s1, s35, 0
	s_add_i32 s3, s63, s42
	global_load_lds_dwordx4 v[180:181], off
	v_lshl_add_u64 v[226:227], s[0:1], 0, v[130:131]
	s_mov_b32 m0, s3
	v_lshl_add_u64 v[228:229], s[36:37], 0, v[132:133]
	global_load_lds_dwordx4 v[226:227], off
	v_lshl_add_u64 v[226:227], s[0:1], 0, v[134:135]
	s_add_i32 m0, s3, 0x2000
	s_nop 0
	global_load_lds_dwordx4 v[226:227], off
	v_lshl_add_u64 v[226:227], s[36:37], 0, v[128:129]
	s_mov_b32 m0, s43
	s_nop 0
	global_load_lds_dwordx4 v[226:227], off
	s_mov_b32 m0, s47
	s_nop 0
	global_load_lds_dwordx4 v[228:229], off
	s_waitcnt vmcnt(8)
	s_waitcnt lgkmcnt(0)
	s_barrier
; #define PG8_STAGE(bufoff, gbase, voff) do { _Pragma("unroll") for (int _i = 0; _i < 2; ++_i) \
;         __builtin_amdgcn_global_load_lds((const unsigned*)((const char*)(gbase) + (voff)[_i]), (PG8_LAS unsigned*)(lds + (bufoff) + ldsw + _i * 8192), 16, 0, 0); } while (0)
; #define PG8_LDA(dst, b, h) do { _Pragma("unroll") for (int m = 0; m < 4; ++m) _Pragma("unroll") for (int k = 0; k < 2; ++k) dst[m][k] = *(const PG8_LAS bf16x8*)(lds + PG8_SA(b, h) + aoff + m * 2048 + k * 1024); } while (0)
; #define PG8_LDB(dst, b, h) do { _Pragma("unroll") for (int n = 0; n < 2; ++n) _Pragma("unroll") for (int k = 0; k < 2; ++k) dst[n][k] = *(const PG8_LAS bf16x8*)(lds + PG8_SB(b, h) + boff + n * 2048 + k * 1024); } while (0)
; #define PG8_MMA(ai, bj, At, Bt) do { __builtin_amdgcn_s_setprio(1); _Pragma("unroll") for (int m = 0; m < 4; ++m) _Pragma("unroll") for (int n = 0; n < 2; ++n) _Pragma("unroll") for (int k = 0; k < 2; ++k) \
;         acc[ai][bj][m][n] = __builtin_amdgcn_mfma_f32_16x16x32_bf16(Bt[n][k], At[m][k], acc[ai][bj][m][n], 0, 0, 0); __builtin_amdgcn_s_setprio(0); } while (0)
; #define PG8_WAIT_V(n) asm volatile("s_waitcnt vmcnt(" #n ")" ::: "memory")
; #define PG8_WAIT_L(n) asm volatile("s_waitcnt lgkmcnt(" #n ")" ::: "memory")
; #define PG8_BAR __builtin_amdgcn_s_barrier()
; #define PG8_SCHED __builtin_amdgcn_sched_barrier(0)
; template <class Epi, class Sched, bool ALIGN_EPI = false, bool SP2 = false>
; __device__ __forceinline__ void gemm_phase(PG8_LAS unsigned char* lds, const Gemm g, const Sched& S, const Epi& E) {
;     ...
;             PG8_WAIT_V(8); PG8_WAIT_L(0); PG8_BAR; PG8_MMA(1, 0, At, B0); PG8_MMA(1, 1, At, B1); PG8_BAR; PG8_SCHED;
;             PG8_LDB(B0, 1, 0); PG8_LDB(B1, 1, 1); PG8_SCHED; PG8_LDA(At, 1, 0); PG8_STAGE(PG8_SA(0, 1), a2 + hstep, voffA);
;             PG8_WAIT_V(8); PG8_WAIT_L(0); PG8_BAR; PG8_MMA(0, 0, At, B0); PG8_MMA(0, 1, At, B1); PG8_BAR; PG8_SCHED;
	s_setprio 1
	s_waitcnt lgkmcnt(0)
	v_mfma_f32_16x16x32_bf16 v[92:95], v[152:155], v[194:197], v[92:95]
	v_mfma_f32_16x16x32_bf16 v[88:91], v[160:163], v[194:197], v[88:91]
	v_mfma_f32_16x16x32_bf16 v[84:87], v[152:155], v[202:205], v[84:87]
	v_mfma_f32_16x16x32_bf16 v[80:83], v[160:163], v[202:205], v[80:83]
	v_mfma_f32_16x16x32_bf16 v[76:79], v[152:155], v[210:213], v[76:79]
	v_mfma_f32_16x16x32_bf16 v[72:75], v[160:163], v[210:213], v[72:75]
	v_mfma_f32_16x16x32_bf16 v[68:71], v[152:155], v[218:221], v[68:71]
	v_mfma_f32_16x16x32_bf16 v[64:67], v[160:163], v[218:221], v[64:67]
	v_mfma_f32_16x16x32_bf16 v[92:95], v[156:159], v[198:201], v[92:95]
	v_mfma_f32_16x16x32_bf16 v[88:91], v[164:167], v[198:201], v[88:91]
	v_mfma_f32_16x16x32_bf16 v[84:87], v[156:159], v[206:209], v[84:87]
	v_mfma_f32_16x16x32_bf16 v[80:83], v[164:167], v[206:209], v[80:83]
	v_mfma_f32_16x16x32_bf16 v[76:79], v[156:159], v[214:217], v[76:79]
	v_mfma_f32_16x16x32_bf16 v[72:75], v[164:167], v[214:217], v[72:75]
	v_mfma_f32_16x16x32_bf16 v[68:71], v[156:159], v[222:225], v[68:71]
	v_mfma_f32_16x16x32_bf16 v[64:67], v[164:167], v[222:225], v[64:67]
	s_setprio 0
	s_setprio 1
	v_mfma_f32_16x16x32_bf16 v[28:31], v[168:171], v[194:197], v[28:31]
	v_mfma_f32_16x16x32_bf16 v[24:27], v[176:179], v[194:197], v[24:27]
	v_mfma_f32_16x16x32_bf16 v[20:23], v[168:171], v[202:205], v[20:23]
	v_mfma_f32_16x16x32_bf16 v[16:19], v[176:179], v[202:205], v[16:19]
	v_mfma_f32_16x16x32_bf16 v[12:15], v[168:171], v[210:213], v[12:15]
	v_mfma_f32_16x16x32_bf16 v[8:11], v[176:179], v[210:213], v[8:11]
	v_mfma_f32_16x16x32_bf16 v[4:7], v[168:171], v[218:221], v[4:7]
	v_mfma_f32_16x16x32_bf16 v[0:3], v[176:179], v[218:221], v[0:3]
	v_mfma_f32_16x16x32_bf16 v[28:31], v[172:175], v[198:201], v[28:31]
	v_mfma_f32_16x16x32_bf16 v[24:27], v[190:193], v[198:201], v[24:27]
	v_mfma_f32_16x16x32_bf16 v[20:23], v[172:175], v[206:209], v[20:23]
	v_mfma_f32_16x16x32_bf16 v[16:19], v[190:193], v[206:209], v[16:19]
	v_mfma_f32_16x16x32_bf16 v[12:15], v[172:175], v[214:217], v[12:15]
	v_mfma_f32_16x16x32_bf16 v[8:11], v[190:193], v[214:217], v[8:11]
	v_mfma_f32_16x16x32_bf16 v[4:7], v[172:175], v[222:225], v[4:7]
	v_mfma_f32_16x16x32_bf16 v[0:3], v[190:193], v[222:225], v[0:3]
	s_setprio 0
	s_barrier
	s_add_i32 s3, 0, 0x18000
	s_add_i32 s45, 0, 0x1c000
	v_add_u32_e32 v164, s3, v147
	v_add_u32_e32 v237, s3, v234
	v_add_u32_e32 v189, s45, v147
	v_add_u32_e32 v238, s45, v234
	ds_read_b128 v[152:155], v164
	ds_read_b128 v[156:159], v237
	ds_read_b128 v[160:163], v164 offset:2048
	ds_read_b128 v[164:167], v237 offset:2048
	ds_read_b128 v[168:171], v189
	ds_read_b128 v[172:175], v238
	ds_read_b128 v[176:179], v189 offset:2048
	ds_read_b128 v[190:193], v238 offset:2048
	s_add_u32 s0, s36, 0x40000
	s_addc_u32 s1, s37, 0
	s_mov_b32 m0, s52
	v_lshl_add_u64 v[230:231], s[0:1], 0, v[128:129]
	ds_read_b128 v[194:197], v151 offset:32768
	ds_read_b128 v[198:201], v233 offset:32768
	ds_read_b128 v[202:205], v151 offset:34816
	ds_read_b128 v[206:209], v233 offset:34816
	ds_read_b128 v[210:213], v151 offset:36864
	ds_read_b128 v[214:217], v233 offset:36864
	ds_read_b128 v[218:221], v151 offset:38912
	ds_read_b128 v[222:225], v233 offset:38912
	global_load_lds_dwordx4 v[230:231], off
	v_lshl_add_u64 v[230:231], s[0:1], 0, v[132:133]
	s_mov_b32 m0, s53
	s_nop 0
	global_load_lds_dwordx4 v[230:231], off
	s_waitcnt vmcnt(8)
	s_waitcnt lgkmcnt(0)
	s_barrier
	s_setprio 1
	s_waitcnt lgkmcnt(0)
	v_mfma_f32_16x16x32_bf16 v[124:127], v[152:155], v[194:197], v[124:127]
	v_mfma_f32_16x16x32_bf16 v[120:123], v[160:163], v[194:197], v[120:123]
	v_mfma_f32_16x16x32_bf16 v[116:119], v[152:155], v[202:205], v[116:119]
	v_mfma_f32_16x16x32_bf16 v[112:115], v[160:163], v[202:205], v[112:115]
	v_mfma_f32_16x16x32_bf16 v[108:111], v[152:155], v[210:213], v[108:111]
	v_mfma_f32_16x16x32_bf16 v[104:107], v[160:163], v[210:213], v[104:107]
	v_mfma_f32_16x16x32_bf16 v[100:103], v[152:155], v[218:221], v[100:103]
	v_mfma_f32_16x16x32_bf16 v[96:99], v[160:163], v[218:221], v[96:99]
	v_mfma_f32_16x16x32_bf16 v[124:127], v[156:159], v[198:201], v[124:127]
	v_mfma_f32_16x16x32_bf16 v[120:123], v[164:167], v[198:201], v[120:123]
	v_mfma_f32_16x16x32_bf16 v[116:119], v[156:159], v[206:209], v[116:119]
	v_mfma_f32_16x16x32_bf16 v[112:115], v[164:167], v[206:209], v[112:115]
	v_mfma_f32_16x16x32_bf16 v[108:111], v[156:159], v[214:217], v[108:111]
	v_mfma_f32_16x16x32_bf16 v[104:107], v[164:167], v[214:217], v[104:107]
	v_mfma_f32_16x16x32_bf16 v[100:103], v[156:159], v[222:225], v[100:103]
	v_mfma_f32_16x16x32_bf16 v[96:99], v[164:167], v[222:225], v[96:99]
	s_setprio 0
	s_setprio 1
	v_mfma_f32_16x16x32_bf16 v[60:63], v[168:171], v[194:197], v[60:63]
	v_mfma_f32_16x16x32_bf16 v[56:59], v[176:179], v[194:197], v[56:59]
	v_mfma_f32_16x16x32_bf16 v[52:55], v[168:171], v[202:205], v[52:55]
	v_mfma_f32_16x16x32_bf16 v[48:51], v[176:179], v[202:205], v[48:51]
	v_mfma_f32_16x16x32_bf16 v[44:47], v[168:171], v[210:213], v[44:47]
	v_mfma_f32_16x16x32_bf16 v[40:43], v[176:179], v[210:213], v[40:43]
	v_mfma_f32_16x16x32_bf16 v[36:39], v[168:171], v[218:221], v[36:39]
	v_mfma_f32_16x16x32_bf16 v[32:35], v[176:179], v[218:221], v[32:35]
	v_mfma_f32_16x16x32_bf16 v[60:63], v[172:175], v[198:201], v[60:63]
	v_mfma_f32_16x16x32_bf16 v[56:59], v[190:193], v[198:201], v[56:59]
	v_mfma_f32_16x16x32_bf16 v[52:55], v[172:175], v[206:209], v[52:55]
	v_mfma_f32_16x16x32_bf16 v[48:51], v[190:193], v[206:209], v[48:51]
	v_mfma_f32_16x16x32_bf16 v[44:47], v[172:175], v[214:217], v[44:47]
	v_mfma_f32_16x16x32_bf16 v[40:43], v[190:193], v[214:217], v[40:43]
	v_mfma_f32_16x16x32_bf16 v[36:39], v[172:175], v[222:225], v[36:39]
	v_mfma_f32_16x16x32_bf16 v[32:35], v[190:193], v[222:225], v[32:35]
	s_setprio 0
	s_barrier
; __device__ __forceinline__ float gelu_t(float x) { const float u = 1.5957691216057308f * (x + 0.044715f * x * x * x); return x * sigmoid_f(u); }
; #define PG8_STAGE(bufoff, gbase, voff) do { _Pragma("unroll") for (int _i = 0; _i < 2; ++_i) \
;         __builtin_amdgcn_global_load_lds((const unsigned*)((const char*)(gbase) + (voff)[_i]), (PG8_LAS unsigned*)(lds + (bufoff) + ldsw + _i * 8192), 16, 0, 0); } while (0)
; #define PG8_LDA(dst, b, h) do { _Pragma("unroll") for (int m = 0; m < 4; ++m) _Pragma("unroll") for (int k = 0; k < 2; ++k) dst[m][k] = *(const PG8_LAS bf16x8*)(lds + PG8_SA(b, h) + aoff + m * 2048 + k * 1024); } while (0)
; #define PG8_WAIT_V(n) asm volatile("s_waitcnt vmcnt(" #n ")" ::: "memory")
; #define PG8_WAIT_L(n) asm volatile("s_waitcnt lgkmcnt(" #n ")" ::: "memory")
; #define PG8_BAR __builtin_amdgcn_s_barrier()
; #define PG8_SCHED __builtin_amdgcn_sched_barrier(0)
;     __device__ __forceinline__ void operator()(const f32x4 (&acc)[2][2][4][2], const Unit& u, int wr, int wc, int fr, int fq) const {
;         const int row0 = u.pm * BM + wr * 64 + fr; const int col0 = u.pn * BM + wc * 32 + 8 * fq;
; #pragma unroll
;         for (int bj = 0; bj < 2; ++bj) {
;             const int col = col0 + bj * HALF;
;             f32x4 b0 = (f32x4){0.f, 0.f, 0.f, 0.f}, b1 = b0;
;             if (MODE == 2) { b0 = *(const f32x4*)(bias + col); b1 = *(const f32x4*)(bias + col + 4); }
;             const bool act = (MODE == 1) && (col < act_cols);
; #pragma unroll
;             for (int ai = 0; ai < 2; ++ai)
; #pragma unroll
;                 for (int m = 0; m < 4; ++m) {
;                     const size_t row = (size_t)(row0 + ai * HALF + m * 16);
;                     f32x4 v0 = acc[ai][bj][m][0], v1 = acc[ai][bj][m][1];
;                     if (MODE == 1) { if (act) {
; #pragma unroll
;                         for (int j = 0; j < 4; ++j) { v0[j] = gelu_t(v0[j]); v1[j] = gelu_t(v1[j]); } } }
; template <class Epi, class Sched, bool ALIGN_EPI = false, bool SP2 = false>
; __device__ __forceinline__ void gemm_phase(PG8_LAS unsigned char* lds, const Gemm g, const Sched& S, const Epi& E) {
;     ...
;             PG8_LDA(At, 1, 1); PG8_STAGE(PG8_SB(1, 0), b3, voffB); PG8_STAGE(PG8_SB(1, 1), b3 + hstep, voffB); PG8_STAGE(PG8_SA(1, 0), a3, voffA);
;             PG8_WAIT_V(8); PG8_WAIT_L(0); PG8_BAR; PG8_MMA(1, 0, At, B0); PG8_MMA(1, 1, At, B1); PG8_BAR; PG8_SCHED;
	s_add_i32 s0, s3, s42
	v_lshl_add_u64 v[144:145], v[144:145], 0, s[14:15]
	s_mov_b32 m0, s0
	ds_read_b128 v[194:197], v151 offset:49152
	ds_read_b128 v[198:201], v233 offset:49152
	ds_read_b128 v[202:205], v151 offset:51200
	ds_read_b128 v[206:209], v233 offset:51200
	ds_read_b128 v[210:213], v151 offset:53248
	ds_read_b128 v[214:217], v233 offset:53248
	ds_read_b128 v[218:221], v151 offset:55296
	ds_read_b128 v[222:225], v233 offset:55296
	global_load_lds_dwordx4 v[144:145], off
	s_add_i32 m0, s0, 0x2000
	s_add_u32 s0, s34, 0x40080
	v_lshl_add_u64 v[144:145], v[180:181], 0, s[14:15]
	s_addc_u32 s1, s35, 0
	s_add_i32 s3, s45, s42
	global_load_lds_dwordx4 v[144:145], off
	v_lshl_add_u64 v[144:145], s[0:1], 0, v[130:131]
	s_mov_b32 m0, s3
	s_nop 0
	global_load_lds_dwordx4 v[144:145], off
	v_lshl_add_u64 v[144:145], s[0:1], 0, v[134:135]
	s_add_i32 m0, s3, 0x2000
	s_nop 0
	global_load_lds_dwordx4 v[144:145], off
	v_lshl_add_u64 v[144:145], v[226:227], 0, s[14:15]
	s_mov_b32 m0, s56
	s_nop 0
	global_load_lds_dwordx4 v[144:145], off
	v_lshl_add_u64 v[144:145], v[228:229], 0, s[14:15]
	s_mov_b32 m0, s57
	s_nop 0
	global_load_lds_dwordx4 v[144:145], off
	s_waitcnt vmcnt(8)
	s_waitcnt lgkmcnt(0)
	s_barrier
	s_setprio 1
	s_waitcnt lgkmcnt(0)
	v_mfma_f32_16x16x32_bf16 v[92:95], v[152:155], v[194:197], v[92:95]
	v_mfma_f32_16x16x32_bf16 v[88:91], v[160:163], v[194:197], v[88:91]
	v_mfma_f32_16x16x32_bf16 v[84:87], v[152:155], v[202:205], v[84:87]
	v_mfma_f32_16x16x32_bf16 v[80:83], v[160:163], v[202:205], v[80:83]
	v_mfma_f32_16x16x32_bf16 v[76:79], v[152:155], v[210:213], v[76:79]
	v_mfma_f32_16x16x32_bf16 v[72:75], v[160:163], v[210:213], v[72:75]
	v_mfma_f32_16x16x32_bf16 v[68:71], v[152:155], v[218:221], v[68:71]
	v_mfma_f32_16x16x32_bf16 v[64:67], v[160:163], v[218:221], v[64:67]
	v_mfma_f32_16x16x32_bf16 v[92:95], v[156:159], v[198:201], v[92:95]
	v_mfma_f32_16x16x32_bf16 v[88:91], v[164:167], v[198:201], v[88:91]
	v_mfma_f32_16x16x32_bf16 v[84:87], v[156:159], v[206:209], v[84:87]
	v_mfma_f32_16x16x32_bf16 v[80:83], v[164:167], v[206:209], v[80:83]
	v_mfma_f32_16x16x32_bf16 v[76:79], v[156:159], v[214:217], v[76:79]
	v_mfma_f32_16x16x32_bf16 v[72:75], v[164:167], v[214:217], v[72:75]
	v_mfma_f32_16x16x32_bf16 v[68:71], v[156:159], v[222:225], v[68:71]
	v_mfma_f32_16x16x32_bf16 v[64:67], v[164:167], v[222:225], v[64:67]
	s_setprio 0
	s_setprio 1
	v_mfma_f32_16x16x32_bf16 v[28:31], v[168:171], v[194:197], v[28:31]
	v_mfma_f32_16x16x32_bf16 v[24:27], v[176:179], v[194:197], v[24:27]
	v_mfma_f32_16x16x32_bf16 v[20:23], v[168:171], v[202:205], v[20:23]
	v_mfma_f32_16x16x32_bf16 v[16:19], v[176:179], v[202:205], v[16:19]
	v_mfma_f32_16x16x32_bf16 v[12:15], v[168:171], v[210:213], v[12:15]
	v_mfma_f32_16x16x32_bf16 v[8:11], v[176:179], v[210:213], v[8:11]
	v_mfma_f32_16x16x32_bf16 v[4:7], v[168:171], v[218:221], v[4:7]
	v_mfma_f32_16x16x32_bf16 v[0:3], v[176:179], v[218:221], v[0:3]
	v_mfma_f32_16x16x32_bf16 v[28:31], v[172:175], v[198:201], v[28:31]
	v_mfma_f32_16x16x32_bf16 v[24:27], v[190:193], v[198:201], v[24:27]
	v_mfma_f32_16x16x32_bf16 v[20:23], v[172:175], v[206:209], v[20:23]
	v_mfma_f32_16x16x32_bf16 v[16:19], v[190:193], v[206:209], v[16:19]
	v_mfma_f32_16x16x32_bf16 v[12:15], v[172:175], v[214:217], v[12:15]
	v_mfma_f32_16x16x32_bf16 v[8:11], v[190:193], v[214:217], v[8:11]
	v_mfma_f32_16x16x32_bf16 v[4:7], v[172:175], v[222:225], v[4:7]
	v_mfma_f32_16x16x32_bf16 v[0:3], v[190:193], v[222:225], v[0:3]
	s_setprio 0
	s_barrier
	s_add_i32 s67, s67, 2
	s_add_u32 s30, s30, 0x100
	s_addc_u32 s31, s31, 0
	s_add_u32 s65, s65, 0x100
	s_addc_u32 s66, s66, 0
	s_cmp_gt_u32 s67, 13
	s_cbranch_scc0 .LBB0_494
	s_and_b64 vcc, exec, s[16:17]
	s_cbranch_vccz .LBB0_497
	s_barrier
.LBB0_497:
	s_mov_b32 s98, 0xbfb8aa3b
	s_mov_b32 s100, 1.0
	v_mov_b32_e32 v242, 0x3d372713
	v_mov_b32_e32 v244, 0x3fcc422a
	v_lshl_or_b32 v144, s28, 8, v148
	v_cmp_gt_i32_e32 vcc, s54, v144
	s_and_saveexec_b64 s[28:29], vcc
	s_cbranch_execz .LBB0_499
	v_pk_mul_f32 v[246:247], v[126:127], v[242:243] op_sel_hi:[1,0]
	v_pk_mul_f32 v[248:249], v[124:125], v[242:243] op_sel_hi:[1,0]
	v_pk_mul_f32 v[250:251], v[122:123], v[242:243] op_sel_hi:[1,0]
	v_pk_mul_f32 v[252:253], v[120:121], v[242:243] op_sel_hi:[1,0]
	v_pk_mul_f32 v[246:247], v[126:127], v[246:247]
	v_pk_mul_f32 v[248:249], v[124:125], v[248:249]
	v_pk_mul_f32 v[250:251], v[122:123], v[250:251]
	v_pk_mul_f32 v[252:253], v[120:121], v[252:253]
	v_pk_fma_f32 v[246:247], v[126:127], v[246:247], v[126:127]
	v_pk_fma_f32 v[248:249], v[124:125], v[248:249], v[124:125]
	v_pk_fma_f32 v[250:251], v[122:123], v[250:251], v[122:123]
	v_pk_fma_f32 v[252:253], v[120:121], v[252:253], v[120:121]
	v_pk_mul_f32 v[246:247], v[246:247], v[244:245] op_sel_hi:[1,0]
	v_pk_mul_f32 v[248:249], v[248:249], v[244:245] op_sel_hi:[1,0]
	v_pk_mul_f32 v[250:251], v[250:251], v[244:245] op_sel_hi:[1,0]
	v_pk_mul_f32 v[252:253], v[252:253], v[244:245] op_sel_hi:[1,0]
	v_pk_mul_f32 v[246:247], v[246:247], s[98:99] op_sel_hi:[1,0]
	v_pk_mul_f32 v[248:249], v[248:249], s[98:99] op_sel_hi:[1,0]
	v_pk_mul_f32 v[250:251], v[250:251], s[98:99] op_sel_hi:[1,0]
	v_pk_mul_f32 v[252:253], v[252:253], s[98:99] op_sel_hi:[1,0]
	v_exp_f32_e32 v246, v246
	v_exp_f32_e32 v247, v247
	v_exp_f32_e32 v248, v248
	v_exp_f32_e32 v249, v249
	v_exp_f32_e32 v250, v250
	v_exp_f32_e32 v251, v251
	v_exp_f32_e32 v252, v252
	v_exp_f32_e32 v253, v253
	v_pk_add_f32 v[246:247], v[246:247], s[100:101] op_sel_hi:[1,0]
	v_pk_add_f32 v[248:249], v[248:249], s[100:101] op_sel_hi:[1,0]
	v_pk_add_f32 v[250:251], v[250:251], s[100:101] op_sel_hi:[1,0]
	v_pk_add_f32 v[252:253], v[252:253], s[100:101] op_sel_hi:[1,0]
	v_rcp_f32_e32 v246, v246
	v_rcp_f32_e32 v247, v247
	v_rcp_f32_e32 v248, v248
	v_rcp_f32_e32 v249, v249
	v_rcp_f32_e32 v250, v250
	v_rcp_f32_e32 v251, v251
	v_rcp_f32_e32 v252, v252
	v_rcp_f32_e32 v253, v253
	v_pk_mul_f32 v[126:127], v[126:127], v[246:247]
	v_pk_mul_f32 v[124:125], v[124:125], v[248:249]
	v_pk_mul_f32 v[122:123], v[122:123], v[250:251]
	v_pk_mul_f32 v[120:121], v[120:121], v[252:253]
; __device__ __forceinline__ unsigned cvt_pk_bf16(float lo, float hi) { unsigned r; asm volatile("v_cvt_pk_bf16_f32 %0, %1, %2" : "=v"(r) : "v"(lo), "v"(hi)); return r; }
; __device__ __forceinline__ float bf_lo(unsigned w) { return __uint_as_float(w << 16); }
; __device__ __forceinline__ float bf_hi(unsigned w) { return __uint_as_float(w & 0xffff0000u); }
; __device__ __forceinline__ float sigmoid_f(float x) { return __builtin_amdgcn_rcpf(1.0f + __expf(-x)); }
;     __device__ __forceinline__ void operator()(const f32x4 (&acc)[2][2][4][2], const Unit& u, int wr, int wc, int fr, int fq) const {
;         const int row0 = u.pm * BM + wr * 64 + fr; const int col0 = u.pn * BM + wc * 32 + 8 * fq;
; #pragma unroll
;         for (int bj = 0; bj < 2; ++bj) {
;             const int col = col0 + bj * HALF;
;             f32x4 b0 = (f32x4){0.f, 0.f, 0.f, 0.f}, b1 = b0;
;             if (MODE == 2) { b0 = *(const f32x4*)(bias + col); b1 = *(const f32x4*)(bias + col + 4); }
;             const bool act = (MODE == 1) && (col < act_cols);
; #pragma unroll
;             for (int ai = 0; ai < 2; ++ai)
; #pragma unroll
;                 for (int m = 0; m < 4; ++m) {
;                     const size_t row = (size_t)(row0 + ai * HALF + m * 16);
;                     f32x4 v0 = acc[ai][bj][m][0], v1 = acc[ai][bj][m][1];
;                     if (MODE == 1) { if (act) {
; #pragma unroll
;                         for (int j = 0; j < 4; ++j) { v0[j] = gelu_t(v0[j]); v1[j] = gelu_t(v1[j]); } } }
;                     if (MODE == 2) {
;                         const u32x4 y = *(const u32x4*)(Y + row * ldy + col);
;                         v0 = v0 + b0; v1 = v1 + b1;
;                         v0[0] = bf_lo(y.x) * sigmoid_f(v0[0]); v0[1] = bf_hi(y.x) * sigmoid_f(v0[1]); v0[2] = bf_lo(y.y) * sigmoid_f(v0[2]); v0[3] = bf_hi(y.y) * sigmoid_f(v0[3]);
;                         v1[0] = bf_lo(y.z) * sigmoid_f(v1[0]); v1[1] = bf_hi(y.z) * sigmoid_f(v1[1]); v1[2] = bf_lo(y.w) * sigmoid_f(v1[2]); v1[3] = bf_hi(y.w) * sigmoid_f(v1[3]);
;                     }
;                     u32x4 w; w.x = cvt_pk_bf16(v0[0], v0[1]); w.y = cvt_pk_bf16(v0[2], v0[3]); w.z = cvt_pk_bf16(v1[0], v1[1]); w.w = cvt_pk_bf16(v1[2], v1[3]);
;                     *(u32x4*)(O + row * ldc + col) = w;
;                 }
.LBB0_499:
	s_or_b64 exec, exec, s[28:29]
	v_lshl_add_u32 v152, s26, 8, v146
	v_cvt_pk_bf16_f32 v124, v124, v125
	v_cvt_pk_bf16_f32 v125, v126, v127
	v_cvt_pk_bf16_f32 v126, v120, v121
	v_mov_b64_e32 v[120:121], s[12:13]
	v_ashrrev_i32_e32 v145, 31, v144
	v_mad_i64_i32 v[120:121], s[0:1], v152, s64, v[120:121]
	v_lshl_add_u64 v[120:121], v[144:145], 1, v[120:121]
	v_cvt_pk_bf16_f32 v127, v122, v123
	global_store_dwordx4 v[120:121], v[124:127], off
	s_and_saveexec_b64 s[26:27], vcc
	s_cbranch_execz .LBB0_501
	v_pk_mul_f32 v[246:247], v[116:117], v[242:243] op_sel_hi:[1,0]
	v_pk_mul_f32 v[248:249], v[118:119], v[242:243] op_sel_hi:[1,0]
	v_pk_mul_f32 v[250:251], v[114:115], v[242:243] op_sel_hi:[1,0]
	v_pk_mul_f32 v[252:253], v[112:113], v[242:243] op_sel_hi:[1,0]
	v_pk_mul_f32 v[246:247], v[116:117], v[246:247]
	v_pk_mul_f32 v[248:249], v[118:119], v[248:249]
	v_pk_mul_f32 v[250:251], v[114:115], v[250:251]
	v_pk_mul_f32 v[252:253], v[112:113], v[252:253]
	v_pk_fma_f32 v[246:247], v[116:117], v[246:247], v[116:117]
	v_pk_fma_f32 v[248:249], v[118:119], v[248:249], v[118:119]
	v_pk_fma_f32 v[250:251], v[114:115], v[250:251], v[114:115]
	v_pk_fma_f32 v[252:253], v[112:113], v[252:253], v[112:113]
	v_pk_mul_f32 v[246:247], v[246:247], v[244:245] op_sel_hi:[1,0]
	v_pk_mul_f32 v[248:249], v[248:249], v[244:245] op_sel_hi:[1,0]
	v_pk_mul_f32 v[250:251], v[250:251], v[244:245] op_sel_hi:[1,0]
	v_pk_mul_f32 v[252:253], v[252:253], v[244:245] op_sel_hi:[1,0]
	v_pk_mul_f32 v[246:247], v[246:247], s[98:99] op_sel_hi:[1,0]
	v_pk_mul_f32 v[248:249], v[248:249], s[98:99] op_sel_hi:[1,0]
	v_pk_mul_f32 v[250:251], v[250:251], s[98:99] op_sel_hi:[1,0]
	v_pk_mul_f32 v[252:253], v[252:253], s[98:99] op_sel_hi:[1,0]
	v_exp_f32_e32 v246, v246
	v_exp_f32_e32 v247, v247
	v_exp_f32_e32 v248, v248
	v_exp_f32_e32 v249, v249
	v_exp_f32_e32 v250, v250
	v_exp_f32_e32 v251, v251
	v_exp_f32_e32 v252, v252
	v_exp_f32_e32 v253, v253
	v_pk_add_f32 v[246:247], v[246:247], s[100:101] op_sel_hi:[1,0]
	v_pk_add_f32 v[248:249], v[248:249], s[100:101] op_sel_hi:[1,0]
	v_pk_add_f32 v[250:251], v[250:251], s[100:101] op_sel_hi:[1,0]
	v_pk_add_f32 v[252:253], v[252:253], s[100:101] op_sel_hi:[1,0]
	v_rcp_f32_e32 v246, v246
	v_rcp_f32_e32 v247, v247
	v_rcp_f32_e32 v248, v248
	v_rcp_f32_e32 v249, v249
	v_rcp_f32_e32 v250, v250
	v_rcp_f32_e32 v251, v251
	v_rcp_f32_e32 v252, v252
	v_rcp_f32_e32 v253, v253
	v_pk_mul_f32 v[116:117], v[116:117], v[246:247]
	v_pk_mul_f32 v[118:119], v[118:119], v[248:249]
	v_pk_mul_f32 v[114:115], v[114:115], v[250:251]
	v_pk_mul_f32 v[112:113], v[112:113], v[252:253]
.LBB0_501:
	s_or_b64 exec, exec, s[26:27]
	v_or_b32_e32 v122, 16, v152
	v_cvt_pk_bf16_f32 v116, v116, v117
	v_cvt_pk_bf16_f32 v117, v118, v119
	v_cvt_pk_bf16_f32 v118, v112, v113
	v_mov_b64_e32 v[112:113], s[12:13]
	v_mad_i64_i32 v[112:113], s[0:1], v122, s64, v[112:113]
	v_lshl_add_u64 v[112:113], v[144:145], 1, v[112:113]
	v_cvt_pk_bf16_f32 v119, v114, v115
	global_store_dwordx4 v[112:113], v[116:119], off
	s_and_saveexec_b64 s[26:27], vcc
	s_cbranch_execz .LBB0_503
	v_pk_mul_f32 v[246:247], v[108:109], v[242:243] op_sel_hi:[1,0]
	v_pk_mul_f32 v[248:249], v[110:111], v[242:243] op_sel_hi:[1,0]
	v_pk_mul_f32 v[250:251], v[106:107], v[242:243] op_sel_hi:[1,0]
	v_pk_mul_f32 v[252:253], v[104:105], v[242:243] op_sel_hi:[1,0]
	v_pk_mul_f32 v[246:247], v[108:109], v[246:247]
	v_pk_mul_f32 v[248:249], v[110:111], v[248:249]
	v_pk_mul_f32 v[250:251], v[106:107], v[250:251]
	v_pk_mul_f32 v[252:253], v[104:105], v[252:253]
	v_pk_fma_f32 v[246:247], v[108:109], v[246:247], v[108:109]
	v_pk_fma_f32 v[248:249], v[110:111], v[248:249], v[110:111]
	v_pk_fma_f32 v[250:251], v[106:107], v[250:251], v[106:107]
	v_pk_fma_f32 v[252:253], v[104:105], v[252:253], v[104:105]
	v_pk_mul_f32 v[246:247], v[246:247], v[244:245] op_sel_hi:[1,0]
	v_pk_mul_f32 v[248:249], v[248:249], v[244:245] op_sel_hi:[1,0]
	v_pk_mul_f32 v[250:251], v[250:251], v[244:245] op_sel_hi:[1,0]
	v_pk_mul_f32 v[252:253], v[252:253], v[244:245] op_sel_hi:[1,0]
	v_pk_mul_f32 v[246:247], v[246:247], s[98:99] op_sel_hi:[1,0]
	v_pk_mul_f32 v[248:249], v[248:249], s[98:99] op_sel_hi:[1,0]
	v_pk_mul_f32 v[250:251], v[250:251], s[98:99] op_sel_hi:[1,0]
	v_pk_mul_f32 v[252:253], v[252:253], s[98:99] op_sel_hi:[1,0]
	v_exp_f32_e32 v246, v246
	v_exp_f32_e32 v247, v247
	v_exp_f32_e32 v248, v248
	v_exp_f32_e32 v249, v249
	v_exp_f32_e32 v250, v250
	v_exp_f32_e32 v251, v251
	v_exp_f32_e32 v252, v252
	v_exp_f32_e32 v253, v253
	v_pk_add_f32 v[246:247], v[246:247], s[100:101] op_sel_hi:[1,0]
	v_pk_add_f32 v[248:249], v[248:249], s[100:101] op_sel_hi:[1,0]
	v_pk_add_f32 v[250:251], v[250:251], s[100:101] op_sel_hi:[1,0]
	v_pk_add_f32 v[252:253], v[252:253], s[100:101] op_sel_hi:[1,0]
	v_rcp_f32_e32 v246, v246
	v_rcp_f32_e32 v247, v247
	v_rcp_f32_e32 v248, v248
	v_rcp_f32_e32 v249, v249
	v_rcp_f32_e32 v250, v250
	v_rcp_f32_e32 v251, v251
	v_rcp_f32_e32 v252, v252
	v_rcp_f32_e32 v253, v253
	v_pk_mul_f32 v[108:109], v[108:109], v[246:247]
	v_pk_mul_f32 v[110:111], v[110:111], v[248:249]
	v_pk_mul_f32 v[106:107], v[106:107], v[250:251]
	v_pk_mul_f32 v[104:105], v[104:105], v[252:253]
; __device__ __forceinline__ unsigned cvt_pk_bf16(float lo, float hi) { unsigned r; asm volatile("v_cvt_pk_bf16_f32 %0, %1, %2" : "=v"(r) : "v"(lo), "v"(hi)); return r; }
; __device__ __forceinline__ float bf_lo(unsigned w) { return __uint_as_float(w << 16); }
; __device__ __forceinline__ float bf_hi(unsigned w) { return __uint_as_float(w & 0xffff0000u); }
; __device__ __forceinline__ float sigmoid_f(float x) { return __builtin_amdgcn_rcpf(1.0f + __expf(-x)); }
;     __device__ __forceinline__ void operator()(const f32x4 (&acc)[2][2][4][2], const Unit& u, int wr, int wc, int fr, int fq) const {
;         const int row0 = u.pm * BM + wr * 64 + fr; const int col0 = u.pn * BM + wc * 32 + 8 * fq;
; #pragma unroll
;         for (int bj = 0; bj < 2; ++bj) {
;             const int col = col0 + bj * HALF;
;             f32x4 b0 = (f32x4){0.f, 0.f, 0.f, 0.f}, b1 = b0;
;             if (MODE == 2) { b0 = *(const f32x4*)(bias + col); b1 = *(const f32x4*)(bias + col + 4); }
;             const bool act = (MODE == 1) && (col < act_cols);
; #pragma unroll
;             for (int ai = 0; ai < 2; ++ai)
; #pragma unroll
;                 for (int m = 0; m < 4; ++m) {
;                     const size_t row = (size_t)(row0 + ai * HALF + m * 16);
;                     f32x4 v0 = acc[ai][bj][m][0], v1 = acc[ai][bj][m][1];
;                     if (MODE == 1) { if (act) {
; #pragma unroll
;                         for (int j = 0; j < 4; ++j) { v0[j] = gelu_t(v0[j]); v1[j] = gelu_t(v1[j]); } } }
;                     if (MODE == 2) {
;                         const u32x4 y = *(const u32x4*)(Y + row * ldy + col);
;                         v0 = v0 + b0; v1 = v1 + b1;
;                         v0[0] = bf_lo(y.x) * sigmoid_f(v0[0]); v0[1] = bf_hi(y.x) * sigmoid_f(v0[1]); v0[2] = bf_lo(y.y) * sigmoid_f(v0[2]); v0[3] = bf_hi(y.y) * sigmoid_f(v0[3]);
;                         v1[0] = bf_lo(y.z) * sigmoid_f(v1[0]); v1[1] = bf_hi(y.z) * sigmoid_f(v1[1]); v1[2] = bf_lo(y.w) * sigmoid_f(v1[2]); v1[3] = bf_hi(y.w) * sigmoid_f(v1[3]);
;                     }
;                     u32x4 w; w.x = cvt_pk_bf16(v0[0], v0[1]); w.y = cvt_pk_bf16(v0[2], v0[3]); w.z = cvt_pk_bf16(v1[0], v1[1]); w.w = cvt_pk_bf16(v1[2], v1[3]);
;                     *(u32x4*)(O + row * ldc + col) = w;
;                 }
.LBB0_503:
	s_or_b64 exec, exec, s[26:27]
	v_or_b32_e32 v114, 32, v152
	v_cvt_pk_bf16_f32 v108, v108, v109
	v_cvt_pk_bf16_f32 v109, v110, v111
	v_cvt_pk_bf16_f32 v110, v104, v105
	v_mov_b64_e32 v[104:105], s[12:13]
	v_mad_i64_i32 v[104:105], s[0:1], v114, s64, v[104:105]
	v_lshl_add_u64 v[104:105], v[144:145], 1, v[104:105]
	v_cvt_pk_bf16_f32 v111, v106, v107
	global_store_dwordx4 v[104:105], v[108:111], off
	s_and_saveexec_b64 s[26:27], vcc
	s_cbranch_execz .LBB0_505
	v_pk_mul_f32 v[246:247], v[100:101], v[242:243] op_sel_hi:[1,0]
	v_pk_mul_f32 v[248:249], v[102:103], v[242:243] op_sel_hi:[1,0]
	v_pk_mul_f32 v[250:251], v[98:99], v[242:243] op_sel_hi:[1,0]
	v_pk_mul_f32 v[252:253], v[96:97], v[242:243] op_sel_hi:[1,0]
	v_pk_mul_f32 v[246:247], v[100:101], v[246:247]
	v_pk_mul_f32 v[248:249], v[102:103], v[248:249]
	v_pk_mul_f32 v[250:251], v[98:99], v[250:251]
	v_pk_mul_f32 v[252:253], v[96:97], v[252:253]
	v_pk_fma_f32 v[246:247], v[100:101], v[246:247], v[100:101]
	v_pk_fma_f32 v[248:249], v[102:103], v[248:249], v[102:103]
	v_pk_fma_f32 v[250:251], v[98:99], v[250:251], v[98:99]
	v_pk_fma_f32 v[252:253], v[96:97], v[252:253], v[96:97]
	v_pk_mul_f32 v[246:247], v[246:247], v[244:245] op_sel_hi:[1,0]
	v_pk_mul_f32 v[248:249], v[248:249], v[244:245] op_sel_hi:[1,0]
	v_pk_mul_f32 v[250:251], v[250:251], v[244:245] op_sel_hi:[1,0]
	v_pk_mul_f32 v[252:253], v[252:253], v[244:245] op_sel_hi:[1,0]
	v_pk_mul_f32 v[246:247], v[246:247], s[98:99] op_sel_hi:[1,0]
	v_pk_mul_f32 v[248:249], v[248:249], s[98:99] op_sel_hi:[1,0]
	v_pk_mul_f32 v[250:251], v[250:251], s[98:99] op_sel_hi:[1,0]
	v_pk_mul_f32 v[252:253], v[252:253], s[98:99] op_sel_hi:[1,0]
	v_exp_f32_e32 v246, v246
	v_exp_f32_e32 v247, v247
	v_exp_f32_e32 v248, v248
	v_exp_f32_e32 v249, v249
	v_exp_f32_e32 v250, v250
	v_exp_f32_e32 v251, v251
	v_exp_f32_e32 v252, v252
	v_exp_f32_e32 v253, v253
	v_pk_add_f32 v[246:247], v[246:247], s[100:101] op_sel_hi:[1,0]
	v_pk_add_f32 v[248:249], v[248:249], s[100:101] op_sel_hi:[1,0]
	v_pk_add_f32 v[250:251], v[250:251], s[100:101] op_sel_hi:[1,0]
	v_pk_add_f32 v[252:253], v[252:253], s[100:101] op_sel_hi:[1,0]
	v_rcp_f32_e32 v246, v246
	v_rcp_f32_e32 v247, v247
	v_rcp_f32_e32 v248, v248
	v_rcp_f32_e32 v249, v249
	v_rcp_f32_e32 v250, v250
	v_rcp_f32_e32 v251, v251
	v_rcp_f32_e32 v252, v252
	v_rcp_f32_e32 v253, v253
	v_pk_mul_f32 v[100:101], v[100:101], v[246:247]
	v_pk_mul_f32 v[102:103], v[102:103], v[248:249]
	v_pk_mul_f32 v[98:99], v[98:99], v[250:251]
	v_pk_mul_f32 v[96:97], v[96:97], v[252:253]
.LBB0_505:
	s_or_b64 exec, exec, s[26:27]
	v_or_b32_e32 v106, 48, v152
	v_cvt_pk_bf16_f32 v100, v100, v101
	v_cvt_pk_bf16_f32 v101, v102, v103
	v_cvt_pk_bf16_f32 v102, v96, v97
	v_mov_b64_e32 v[96:97], s[12:13]
	v_mad_i64_i32 v[96:97], s[0:1], v106, s64, v[96:97]
	v_lshl_add_u64 v[96:97], v[144:145], 1, v[96:97]
	v_cvt_pk_bf16_f32 v103, v98, v99
	global_store_dwordx4 v[96:97], v[100:103], off
	s_and_saveexec_b64 s[26:27], vcc
	s_cbranch_execz .LBB0_507
	v_pk_mul_f32 v[246:247], v[92:93], v[242:243] op_sel_hi:[1,0]
	v_pk_mul_f32 v[248:249], v[94:95], v[242:243] op_sel_hi:[1,0]
	v_pk_mul_f32 v[250:251], v[90:91], v[242:243] op_sel_hi:[1,0]
	v_pk_mul_f32 v[252:253], v[88:89], v[242:243] op_sel_hi:[1,0]
	v_pk_mul_f32 v[246:247], v[92:93], v[246:247]
	v_pk_mul_f32 v[248:249], v[94:95], v[248:249]
	v_pk_mul_f32 v[250:251], v[90:91], v[250:251]
	v_pk_mul_f32 v[252:253], v[88:89], v[252:253]
	v_pk_fma_f32 v[246:247], v[92:93], v[246:247], v[92:93]
	v_pk_fma_f32 v[248:249], v[94:95], v[248:249], v[94:95]
	v_pk_fma_f32 v[250:251], v[90:91], v[250:251], v[90:91]
	v_pk_fma_f32 v[252:253], v[88:89], v[252:253], v[88:89]
	v_pk_mul_f32 v[246:247], v[246:247], v[244:245] op_sel_hi:[1,0]
	v_pk_mul_f32 v[248:249], v[248:249], v[244:245] op_sel_hi:[1,0]
	v_pk_mul_f32 v[250:251], v[250:251], v[244:245] op_sel_hi:[1,0]
	v_pk_mul_f32 v[252:253], v[252:253], v[244:245] op_sel_hi:[1,0]
	v_pk_mul_f32 v[246:247], v[246:247], s[98:99] op_sel_hi:[1,0]
	v_pk_mul_f32 v[248:249], v[248:249], s[98:99] op_sel_hi:[1,0]
	v_pk_mul_f32 v[250:251], v[250:251], s[98:99] op_sel_hi:[1,0]
	v_pk_mul_f32 v[252:253], v[252:253], s[98:99] op_sel_hi:[1,0]
	v_exp_f32_e32 v246, v246
	v_exp_f32_e32 v247, v247
	v_exp_f32_e32 v248, v248
	v_exp_f32_e32 v249, v249
	v_exp_f32_e32 v250, v250
	v_exp_f32_e32 v251, v251
	v_exp_f32_e32 v252, v252
	v_exp_f32_e32 v253, v253
	v_pk_add_f32 v[246:247], v[246:247], s[100:101] op_sel_hi:[1,0]
	v_pk_add_f32 v[248:249], v[248:249], s[100:101] op_sel_hi:[1,0]
	v_pk_add_f32 v[250:251], v[250:251], s[100:101] op_sel_hi:[1,0]
	v_pk_add_f32 v[252:253], v[252:253], s[100:101] op_sel_hi:[1,0]
	v_rcp_f32_e32 v246, v246
	v_rcp_f32_e32 v247, v247
	v_rcp_f32_e32 v248, v248
	v_rcp_f32_e32 v249, v249
	v_rcp_f32_e32 v250, v250
	v_rcp_f32_e32 v251, v251
	v_rcp_f32_e32 v252, v252
	v_rcp_f32_e32 v253, v253
	v_pk_mul_f32 v[92:93], v[92:93], v[246:247]
	v_pk_mul_f32 v[94:95], v[94:95], v[248:249]
	v_pk_mul_f32 v[90:91], v[90:91], v[250:251]
	v_pk_mul_f32 v[88:89], v[88:89], v[252:253]
; __device__ __forceinline__ unsigned cvt_pk_bf16(float lo, float hi) { unsigned r; asm volatile("v_cvt_pk_bf16_f32 %0, %1, %2" : "=v"(r) : "v"(lo), "v"(hi)); return r; }
; __device__ __forceinline__ float bf_lo(unsigned w) { return __uint_as_float(w << 16); }
; __device__ __forceinline__ float bf_hi(unsigned w) { return __uint_as_float(w & 0xffff0000u); }
; __device__ __forceinline__ float sigmoid_f(float x) { return __builtin_amdgcn_rcpf(1.0f + __expf(-x)); }
;     __device__ __forceinline__ void operator()(const f32x4 (&acc)[2][2][4][2], const Unit& u, int wr, int wc, int fr, int fq) const {
;         const int row0 = u.pm * BM + wr * 64 + fr; const int col0 = u.pn * BM + wc * 32 + 8 * fq;
; #pragma unroll
;         for (int bj = 0; bj < 2; ++bj) {
;             const int col = col0 + bj * HALF;
;             f32x4 b0 = (f32x4){0.f, 0.f, 0.f, 0.f}, b1 = b0;
;             if (MODE == 2) { b0 = *(const f32x4*)(bias + col); b1 = *(const f32x4*)(bias + col + 4); }
;             const bool act = (MODE == 1) && (col < act_cols);
; #pragma unroll
;             for (int ai = 0; ai < 2; ++ai)
; #pragma unroll
;                 for (int m = 0; m < 4; ++m) {
;                     const size_t row = (size_t)(row0 + ai * HALF + m * 16);
;                     f32x4 v0 = acc[ai][bj][m][0], v1 = acc[ai][bj][m][1];
;                     if (MODE == 1) { if (act) {
; #pragma unroll
;                         for (int j = 0; j < 4; ++j) { v0[j] = gelu_t(v0[j]); v1[j] = gelu_t(v1[j]); } } }
;                     if (MODE == 2) {
;                         const u32x4 y = *(const u32x4*)(Y + row * ldy + col);
;                         v0 = v0 + b0; v1 = v1 + b1;
;                         v0[0] = bf_lo(y.x) * sigmoid_f(v0[0]); v0[1] = bf_hi(y.x) * sigmoid_f(v0[1]); v0[2] = bf_lo(y.y) * sigmoid_f(v0[2]); v0[3] = bf_hi(y.y) * sigmoid_f(v0[3]);
;                         v1[0] = bf_lo(y.z) * sigmoid_f(v1[0]); v1[1] = bf_hi(y.z) * sigmoid_f(v1[1]); v1[2] = bf_lo(y.w) * sigmoid_f(v1[2]); v1[3] = bf_hi(y.w) * sigmoid_f(v1[3]);
;                     }
;                     u32x4 w; w.x = cvt_pk_bf16(v0[0], v0[1]); w.y = cvt_pk_bf16(v0[2], v0[3]); w.z = cvt_pk_bf16(v1[0], v1[1]); w.w = cvt_pk_bf16(v1[2], v1[3]);
;                     *(u32x4*)(O + row * ldc + col) = w;
;                 }
.LBB0_507:
	s_or_b64 exec, exec, s[26:27]
	v_add_u32_e32 v98, 0x80, v152
	v_cvt_pk_bf16_f32 v92, v92, v93
	v_cvt_pk_bf16_f32 v93, v94, v95
	v_cvt_pk_bf16_f32 v94, v88, v89
	v_mov_b64_e32 v[88:89], s[12:13]
	v_mad_i64_i32 v[88:89], s[0:1], v98, s64, v[88:89]
	v_lshl_add_u64 v[88:89], v[144:145], 1, v[88:89]
	v_cvt_pk_bf16_f32 v95, v90, v91
	global_store_dwordx4 v[88:89], v[92:95], off
	s_and_saveexec_b64 s[26:27], vcc
	s_cbranch_execz .LBB0_509
	v_pk_mul_f32 v[246:247], v[84:85], v[242:243] op_sel_hi:[1,0]
	v_pk_mul_f32 v[248:249], v[86:87], v[242:243] op_sel_hi:[1,0]
	v_pk_mul_f32 v[250:251], v[82:83], v[242:243] op_sel_hi:[1,0]
	v_pk_mul_f32 v[252:253], v[80:81], v[242:243] op_sel_hi:[1,0]
	v_pk_mul_f32 v[246:247], v[84:85], v[246:247]
	v_pk_mul_f32 v[248:249], v[86:87], v[248:249]
	v_pk_mul_f32 v[250:251], v[82:83], v[250:251]
	v_pk_mul_f32 v[252:253], v[80:81], v[252:253]
	v_pk_fma_f32 v[246:247], v[84:85], v[246:247], v[84:85]
	v_pk_fma_f32 v[248:249], v[86:87], v[248:249], v[86:87]
	v_pk_fma_f32 v[250:251], v[82:83], v[250:251], v[82:83]
	v_pk_fma_f32 v[252:253], v[80:81], v[252:253], v[80:81]
	v_pk_mul_f32 v[246:247], v[246:247], v[244:245] op_sel_hi:[1,0]
	v_pk_mul_f32 v[248:249], v[248:249], v[244:245] op_sel_hi:[1,0]
	v_pk_mul_f32 v[250:251], v[250:251], v[244:245] op_sel_hi:[1,0]
	v_pk_mul_f32 v[252:253], v[252:253], v[244:245] op_sel_hi:[1,0]
	v_pk_mul_f32 v[246:247], v[246:247], s[98:99] op_sel_hi:[1,0]
	v_pk_mul_f32 v[248:249], v[248:249], s[98:99] op_sel_hi:[1,0]
	v_pk_mul_f32 v[250:251], v[250:251], s[98:99] op_sel_hi:[1,0]
	v_pk_mul_f32 v[252:253], v[252:253], s[98:99] op_sel_hi:[1,0]
	v_exp_f32_e32 v246, v246
	v_exp_f32_e32 v247, v247
	v_exp_f32_e32 v248, v248
	v_exp_f32_e32 v249, v249
	v_exp_f32_e32 v250, v250
	v_exp_f32_e32 v251, v251
	v_exp_f32_e32 v252, v252
	v_exp_f32_e32 v253, v253
	v_pk_add_f32 v[246:247], v[246:247], s[100:101] op_sel_hi:[1,0]
	v_pk_add_f32 v[248:249], v[248:249], s[100:101] op_sel_hi:[1,0]
	v_pk_add_f32 v[250:251], v[250:251], s[100:101] op_sel_hi:[1,0]
	v_pk_add_f32 v[252:253], v[252:253], s[100:101] op_sel_hi:[1,0]
	v_rcp_f32_e32 v246, v246
	v_rcp_f32_e32 v247, v247
	v_rcp_f32_e32 v248, v248
	v_rcp_f32_e32 v249, v249
	v_rcp_f32_e32 v250, v250
	v_rcp_f32_e32 v251, v251
	v_rcp_f32_e32 v252, v252
	v_rcp_f32_e32 v253, v253
	v_pk_mul_f32 v[84:85], v[84:85], v[246:247]
	v_pk_mul_f32 v[86:87], v[86:87], v[248:249]
	v_pk_mul_f32 v[82:83], v[82:83], v[250:251]
	v_pk_mul_f32 v[80:81], v[80:81], v[252:253]
.LBB0_509:
	s_or_b64 exec, exec, s[26:27]
	v_add_u32_e32 v90, 0x90, v152
	v_cvt_pk_bf16_f32 v84, v84, v85
	v_cvt_pk_bf16_f32 v85, v86, v87
	v_cvt_pk_bf16_f32 v86, v80, v81
	v_mov_b64_e32 v[80:81], s[12:13]
	v_mad_i64_i32 v[80:81], s[0:1], v90, s64, v[80:81]
	v_lshl_add_u64 v[80:81], v[144:145], 1, v[80:81]
	v_cvt_pk_bf16_f32 v87, v82, v83
	global_store_dwordx4 v[80:81], v[84:87], off
	s_and_saveexec_b64 s[26:27], vcc
	s_cbranch_execz .LBB0_511
	v_pk_mul_f32 v[246:247], v[76:77], v[242:243] op_sel_hi:[1,0]
	v_pk_mul_f32 v[248:249], v[78:79], v[242:243] op_sel_hi:[1,0]
	v_pk_mul_f32 v[250:251], v[74:75], v[242:243] op_sel_hi:[1,0]
	v_pk_mul_f32 v[252:253], v[72:73], v[242:243] op_sel_hi:[1,0]
	v_pk_mul_f32 v[246:247], v[76:77], v[246:247]
	v_pk_mul_f32 v[248:249], v[78:79], v[248:249]
	v_pk_mul_f32 v[250:251], v[74:75], v[250:251]
	v_pk_mul_f32 v[252:253], v[72:73], v[252:253]
	v_pk_fma_f32 v[246:247], v[76:77], v[246:247], v[76:77]
	v_pk_fma_f32 v[248:249], v[78:79], v[248:249], v[78:79]
	v_pk_fma_f32 v[250:251], v[74:75], v[250:251], v[74:75]
	v_pk_fma_f32 v[252:253], v[72:73], v[252:253], v[72:73]
	v_pk_mul_f32 v[246:247], v[246:247], v[244:245] op_sel_hi:[1,0]
	v_pk_mul_f32 v[248:249], v[248:249], v[244:245] op_sel_hi:[1,0]
	v_pk_mul_f32 v[250:251], v[250:251], v[244:245] op_sel_hi:[1,0]
	v_pk_mul_f32 v[252:253], v[252:253], v[244:245] op_sel_hi:[1,0]
	v_pk_mul_f32 v[246:247], v[246:247], s[98:99] op_sel_hi:[1,0]
	v_pk_mul_f32 v[248:249], v[248:249], s[98:99] op_sel_hi:[1,0]
	v_pk_mul_f32 v[250:251], v[250:251], s[98:99] op_sel_hi:[1,0]
	v_pk_mul_f32 v[252:253], v[252:253], s[98:99] op_sel_hi:[1,0]
	v_exp_f32_e32 v246, v246
	v_exp_f32_e32 v247, v247
	v_exp_f32_e32 v248, v248
	v_exp_f32_e32 v249, v249
	v_exp_f32_e32 v250, v250
	v_exp_f32_e32 v251, v251
	v_exp_f32_e32 v252, v252
	v_exp_f32_e32 v253, v253
	v_pk_add_f32 v[246:247], v[246:247], s[100:101] op_sel_hi:[1,0]
	v_pk_add_f32 v[248:249], v[248:249], s[100:101] op_sel_hi:[1,0]
	v_pk_add_f32 v[250:251], v[250:251], s[100:101] op_sel_hi:[1,0]
	v_pk_add_f32 v[252:253], v[252:253], s[100:101] op_sel_hi:[1,0]
	v_rcp_f32_e32 v246, v246
	v_rcp_f32_e32 v247, v247
	v_rcp_f32_e32 v248, v248
	v_rcp_f32_e32 v249, v249
	v_rcp_f32_e32 v250, v250
	v_rcp_f32_e32 v251, v251
	v_rcp_f32_e32 v252, v252
	v_rcp_f32_e32 v253, v253
	v_pk_mul_f32 v[76:77], v[76:77], v[246:247]
	v_pk_mul_f32 v[78:79], v[78:79], v[248:249]
	v_pk_mul_f32 v[74:75], v[74:75], v[250:251]
	v_pk_mul_f32 v[72:73], v[72:73], v[252:253]
; __device__ __forceinline__ unsigned cvt_pk_bf16(float lo, float hi) { unsigned r; asm volatile("v_cvt_pk_bf16_f32 %0, %1, %2" : "=v"(r) : "v"(lo), "v"(hi)); return r; }
; __device__ __forceinline__ float bf_lo(unsigned w) { return __uint_as_float(w << 16); }
; __device__ __forceinline__ float bf_hi(unsigned w) { return __uint_as_float(w & 0xffff0000u); }
; __device__ __forceinline__ float sigmoid_f(float x) { return __builtin_amdgcn_rcpf(1.0f + __expf(-x)); }
;     __device__ __forceinline__ void operator()(const f32x4 (&acc)[2][2][4][2], const Unit& u, int wr, int wc, int fr, int fq) const {
;         const int row0 = u.pm * BM + wr * 64 + fr; const int col0 = u.pn * BM + wc * 32 + 8 * fq;
; #pragma unroll
;         for (int bj = 0; bj < 2; ++bj) {
;             const int col = col0 + bj * HALF;
;             f32x4 b0 = (f32x4){0.f, 0.f, 0.f, 0.f}, b1 = b0;
;             if (MODE == 2) { b0 = *(const f32x4*)(bias + col); b1 = *(const f32x4*)(bias + col + 4); }
;             const bool act = (MODE == 1) && (col < act_cols);
; #pragma unroll
;             for (int ai = 0; ai < 2; ++ai)
; #pragma unroll
;                 for (int m = 0; m < 4; ++m) {
;                     const size_t row = (size_t)(row0 + ai * HALF + m * 16);
;                     f32x4 v0 = acc[ai][bj][m][0], v1 = acc[ai][bj][m][1];
;                     if (MODE == 1) { if (act) {
; #pragma unroll
;                         for (int j = 0; j < 4; ++j) { v0[j] = gelu_t(v0[j]); v1[j] = gelu_t(v1[j]); } } }
;                     if (MODE == 2) {
;                         const u32x4 y = *(const u32x4*)(Y + row * ldy + col);
;                         v0 = v0 + b0; v1 = v1 + b1;
;                         v0[0] = bf_lo(y.x) * sigmoid_f(v0[0]); v0[1] = bf_hi(y.x) * sigmoid_f(v0[1]); v0[2] = bf_lo(y.y) * sigmoid_f(v0[2]); v0[3] = bf_hi(y.y) * sigmoid_f(v0[3]);
;                         v1[0] = bf_lo(y.z) * sigmoid_f(v1[0]); v1[1] = bf_hi(y.z) * sigmoid_f(v1[1]); v1[2] = bf_lo(y.w) * sigmoid_f(v1[2]); v1[3] = bf_hi(y.w) * sigmoid_f(v1[3]);
;                     }
;                     u32x4 w; w.x = cvt_pk_bf16(v0[0], v0[1]); w.y = cvt_pk_bf16(v0[2], v0[3]); w.z = cvt_pk_bf16(v1[0], v1[1]); w.w = cvt_pk_bf16(v1[2], v1[3]);
;                     *(u32x4*)(O + row * ldc + col) = w;
;                 }
.LBB0_511:
	s_or_b64 exec, exec, s[26:27]
	v_add_u32_e32 v82, 0xa0, v152
	v_cvt_pk_bf16_f32 v76, v76, v77
	v_cvt_pk_bf16_f32 v77, v78, v79
	v_cvt_pk_bf16_f32 v78, v72, v73
	v_mov_b64_e32 v[72:73], s[12:13]
	v_mad_i64_i32 v[72:73], s[0:1], v82, s64, v[72:73]
	v_lshl_add_u64 v[72:73], v[144:145], 1, v[72:73]
	v_cvt_pk_bf16_f32 v79, v74, v75
	global_store_dwordx4 v[72:73], v[76:79], off
	s_and_saveexec_b64 s[26:27], vcc
	s_cbranch_execz .LBB0_513
	v_pk_mul_f32 v[246:247], v[68:69], v[242:243] op_sel_hi:[1,0]
	v_pk_mul_f32 v[248:249], v[70:71], v[242:243] op_sel_hi:[1,0]
	v_pk_mul_f32 v[250:251], v[66:67], v[242:243] op_sel_hi:[1,0]
	v_pk_mul_f32 v[252:253], v[64:65], v[242:243] op_sel_hi:[1,0]
	v_pk_mul_f32 v[246:247], v[68:69], v[246:247]
	v_pk_mul_f32 v[248:249], v[70:71], v[248:249]
	v_pk_mul_f32 v[250:251], v[66:67], v[250:251]
	v_pk_mul_f32 v[252:253], v[64:65], v[252:253]
	v_pk_fma_f32 v[246:247], v[68:69], v[246:247], v[68:69]
	v_pk_fma_f32 v[248:249], v[70:71], v[248:249], v[70:71]
	v_pk_fma_f32 v[250:251], v[66:67], v[250:251], v[66:67]
	v_pk_fma_f32 v[252:253], v[64:65], v[252:253], v[64:65]
	v_pk_mul_f32 v[246:247], v[246:247], v[244:245] op_sel_hi:[1,0]
	v_pk_mul_f32 v[248:249], v[248:249], v[244:245] op_sel_hi:[1,0]
	v_pk_mul_f32 v[250:251], v[250:251], v[244:245] op_sel_hi:[1,0]
	v_pk_mul_f32 v[252:253], v[252:253], v[244:245] op_sel_hi:[1,0]
	v_pk_mul_f32 v[246:247], v[246:247], s[98:99] op_sel_hi:[1,0]
	v_pk_mul_f32 v[248:249], v[248:249], s[98:99] op_sel_hi:[1,0]
	v_pk_mul_f32 v[250:251], v[250:251], s[98:99] op_sel_hi:[1,0]
	v_pk_mul_f32 v[252:253], v[252:253], s[98:99] op_sel_hi:[1,0]
	v_exp_f32_e32 v246, v246
	v_exp_f32_e32 v247, v247
	v_exp_f32_e32 v248, v248
	v_exp_f32_e32 v249, v249
	v_exp_f32_e32 v250, v250
	v_exp_f32_e32 v251, v251
	v_exp_f32_e32 v252, v252
	v_exp_f32_e32 v253, v253
	v_pk_add_f32 v[246:247], v[246:247], s[100:101] op_sel_hi:[1,0]
	v_pk_add_f32 v[248:249], v[248:249], s[100:101] op_sel_hi:[1,0]
	v_pk_add_f32 v[250:251], v[250:251], s[100:101] op_sel_hi:[1,0]
	v_pk_add_f32 v[252:253], v[252:253], s[100:101] op_sel_hi:[1,0]
	v_rcp_f32_e32 v246, v246
	v_rcp_f32_e32 v247, v247
	v_rcp_f32_e32 v248, v248
	v_rcp_f32_e32 v249, v249
	v_rcp_f32_e32 v250, v250
	v_rcp_f32_e32 v251, v251
	v_rcp_f32_e32 v252, v252
	v_rcp_f32_e32 v253, v253
	v_pk_mul_f32 v[68:69], v[68:69], v[246:247]
	v_pk_mul_f32 v[70:71], v[70:71], v[248:249]
	v_pk_mul_f32 v[66:67], v[66:67], v[250:251]
	v_pk_mul_f32 v[64:65], v[64:65], v[252:253]
.LBB0_513:
	s_or_b64 exec, exec, s[26:27]
	v_add_u32_e32 v74, 0xb0, v152
	v_cvt_pk_bf16_f32 v68, v68, v69
	v_cvt_pk_bf16_f32 v69, v70, v71
	v_cvt_pk_bf16_f32 v70, v64, v65
	v_mov_b64_e32 v[64:65], s[12:13]
	v_cvt_pk_bf16_f32 v71, v66, v67
	v_mad_i64_i32 v[64:65], s[0:1], v74, s64, v[64:65]
	v_or_b32_e32 v66, 0x80, v144
	v_lshl_add_u64 v[64:65], v[144:145], 1, v[64:65]
	v_cmp_gt_i32_e32 vcc, s54, v66
	global_store_dwordx4 v[64:65], v[68:71], off
	s_and_saveexec_b64 s[26:27], vcc
	s_cbranch_execz .LBB0_515
	v_pk_mul_f32 v[246:247], v[60:61], v[242:243] op_sel_hi:[1,0]
	v_pk_mul_f32 v[248:249], v[62:63], v[242:243] op_sel_hi:[1,0]
	v_pk_mul_f32 v[250:251], v[58:59], v[242:243] op_sel_hi:[1,0]
	v_pk_mul_f32 v[252:253], v[56:57], v[242:243] op_sel_hi:[1,0]
	v_pk_mul_f32 v[246:247], v[60:61], v[246:247]
	v_pk_mul_f32 v[248:249], v[62:63], v[248:249]
	v_pk_mul_f32 v[250:251], v[58:59], v[250:251]
	v_pk_mul_f32 v[252:253], v[56:57], v[252:253]
	v_pk_fma_f32 v[246:247], v[60:61], v[246:247], v[60:61]
	v_pk_fma_f32 v[248:249], v[62:63], v[248:249], v[62:63]
	v_pk_fma_f32 v[250:251], v[58:59], v[250:251], v[58:59]
	v_pk_fma_f32 v[252:253], v[56:57], v[252:253], v[56:57]
	v_pk_mul_f32 v[246:247], v[246:247], v[244:245] op_sel_hi:[1,0]
	v_pk_mul_f32 v[248:249], v[248:249], v[244:245] op_sel_hi:[1,0]
	v_pk_mul_f32 v[250:251], v[250:251], v[244:245] op_sel_hi:[1,0]
	v_pk_mul_f32 v[252:253], v[252:253], v[244:245] op_sel_hi:[1,0]
	v_pk_mul_f32 v[246:247], v[246:247], s[98:99] op_sel_hi:[1,0]
	v_pk_mul_f32 v[248:249], v[248:249], s[98:99] op_sel_hi:[1,0]
	v_pk_mul_f32 v[250:251], v[250:251], s[98:99] op_sel_hi:[1,0]
	v_pk_mul_f32 v[252:253], v[252:253], s[98:99] op_sel_hi:[1,0]
	v_exp_f32_e32 v246, v246
	v_exp_f32_e32 v247, v247
	v_exp_f32_e32 v248, v248
	v_exp_f32_e32 v249, v249
	v_exp_f32_e32 v250, v250
	v_exp_f32_e32 v251, v251
	v_exp_f32_e32 v252, v252
	v_exp_f32_e32 v253, v253
	v_pk_add_f32 v[246:247], v[246:247], s[100:101] op_sel_hi:[1,0]
	v_pk_add_f32 v[248:249], v[248:249], s[100:101] op_sel_hi:[1,0]
	v_pk_add_f32 v[250:251], v[250:251], s[100:101] op_sel_hi:[1,0]
	v_pk_add_f32 v[252:253], v[252:253], s[100:101] op_sel_hi:[1,0]
	v_rcp_f32_e32 v246, v246
	v_rcp_f32_e32 v247, v247
	v_rcp_f32_e32 v248, v248
	v_rcp_f32_e32 v249, v249
	v_rcp_f32_e32 v250, v250
	v_rcp_f32_e32 v251, v251
	v_rcp_f32_e32 v252, v252
	v_rcp_f32_e32 v253, v253
	v_pk_mul_f32 v[60:61], v[60:61], v[246:247]
	v_pk_mul_f32 v[62:63], v[62:63], v[248:249]
	v_pk_mul_f32 v[58:59], v[58:59], v[250:251]
	v_pk_mul_f32 v[56:57], v[56:57], v[252:253]
; __device__ __forceinline__ unsigned cvt_pk_bf16(float lo, float hi) { unsigned r; asm volatile("v_cvt_pk_bf16_f32 %0, %1, %2" : "=v"(r) : "v"(lo), "v"(hi)); return r; }
; __device__ __forceinline__ float bf_lo(unsigned w) { return __uint_as_float(w << 16); }
; __device__ __forceinline__ float bf_hi(unsigned w) { return __uint_as_float(w & 0xffff0000u); }
; __device__ __forceinline__ float sigmoid_f(float x) { return __builtin_amdgcn_rcpf(1.0f + __expf(-x)); }
;     __device__ __forceinline__ void operator()(const f32x4 (&acc)[2][2][4][2], const Unit& u, int wr, int wc, int fr, int fq) const {
;         const int row0 = u.pm * BM + wr * 64 + fr; const int col0 = u.pn * BM + wc * 32 + 8 * fq;
; #pragma unroll
;         for (int bj = 0; bj < 2; ++bj) {
;             const int col = col0 + bj * HALF;
;             f32x4 b0 = (f32x4){0.f, 0.f, 0.f, 0.f}, b1 = b0;
;             if (MODE == 2) { b0 = *(const f32x4*)(bias + col); b1 = *(const f32x4*)(bias + col + 4); }
;             const bool act = (MODE == 1) && (col < act_cols);
; #pragma unroll
;             for (int ai = 0; ai < 2; ++ai)
; #pragma unroll
;                 for (int m = 0; m < 4; ++m) {
;                     const size_t row = (size_t)(row0 + ai * HALF + m * 16);
;                     f32x4 v0 = acc[ai][bj][m][0], v1 = acc[ai][bj][m][1];
;                     if (MODE == 1) { if (act) {
; #pragma unroll
;                         for (int j = 0; j < 4; ++j) { v0[j] = gelu_t(v0[j]); v1[j] = gelu_t(v1[j]); } } }
;                     if (MODE == 2) {
;                         const u32x4 y = *(const u32x4*)(Y + row * ldy + col);
;                         v0 = v0 + b0; v1 = v1 + b1;
;                         v0[0] = bf_lo(y.x) * sigmoid_f(v0[0]); v0[1] = bf_hi(y.x) * sigmoid_f(v0[1]); v0[2] = bf_lo(y.y) * sigmoid_f(v0[2]); v0[3] = bf_hi(y.y) * sigmoid_f(v0[3]);
;                         v1[0] = bf_lo(y.z) * sigmoid_f(v1[0]); v1[1] = bf_hi(y.z) * sigmoid_f(v1[1]); v1[2] = bf_lo(y.w) * sigmoid_f(v1[2]); v1[3] = bf_hi(y.w) * sigmoid_f(v1[3]);
;                     }
;                     u32x4 w; w.x = cvt_pk_bf16(v0[0], v0[1]); w.y = cvt_pk_bf16(v0[2], v0[3]); w.z = cvt_pk_bf16(v1[0], v1[1]); w.w = cvt_pk_bf16(v1[2], v1[3]);
;                     *(u32x4*)(O + row * ldc + col) = w;
;                 }
.LBB0_515:
	s_or_b64 exec, exec, s[26:27]
	v_cvt_pk_bf16_f32 v60, v60, v61
	v_cvt_pk_bf16_f32 v61, v62, v63
	v_cvt_pk_bf16_f32 v62, v56, v57
	v_cvt_pk_bf16_f32 v63, v58, v59
	global_store_dwordx4 v[120:121], v[60:63], off offset:256
	s_and_saveexec_b64 s[26:27], vcc
	s_cbranch_execz .LBB0_517
	v_pk_mul_f32 v[246:247], v[52:53], v[242:243] op_sel_hi:[1,0]
	v_pk_mul_f32 v[248:249], v[54:55], v[242:243] op_sel_hi:[1,0]
	v_pk_mul_f32 v[250:251], v[50:51], v[242:243] op_sel_hi:[1,0]
	v_pk_mul_f32 v[252:253], v[48:49], v[242:243] op_sel_hi:[1,0]
	v_pk_mul_f32 v[246:247], v[52:53], v[246:247]
	v_pk_mul_f32 v[248:249], v[54:55], v[248:249]
	v_pk_mul_f32 v[250:251], v[50:51], v[250:251]
	v_pk_mul_f32 v[252:253], v[48:49], v[252:253]
	v_pk_fma_f32 v[246:247], v[52:53], v[246:247], v[52:53]
	v_pk_fma_f32 v[248:249], v[54:55], v[248:249], v[54:55]
	v_pk_fma_f32 v[250:251], v[50:51], v[250:251], v[50:51]
	v_pk_fma_f32 v[252:253], v[48:49], v[252:253], v[48:49]
	v_pk_mul_f32 v[246:247], v[246:247], v[244:245] op_sel_hi:[1,0]
	v_pk_mul_f32 v[248:249], v[248:249], v[244:245] op_sel_hi:[1,0]
	v_pk_mul_f32 v[250:251], v[250:251], v[244:245] op_sel_hi:[1,0]
	v_pk_mul_f32 v[252:253], v[252:253], v[244:245] op_sel_hi:[1,0]
	v_pk_mul_f32 v[246:247], v[246:247], s[98:99] op_sel_hi:[1,0]
	v_pk_mul_f32 v[248:249], v[248:249], s[98:99] op_sel_hi:[1,0]
	v_pk_mul_f32 v[250:251], v[250:251], s[98:99] op_sel_hi:[1,0]
	v_pk_mul_f32 v[252:253], v[252:253], s[98:99] op_sel_hi:[1,0]
	v_exp_f32_e32 v246, v246
	v_exp_f32_e32 v247, v247
	v_exp_f32_e32 v248, v248
	v_exp_f32_e32 v249, v249
	v_exp_f32_e32 v250, v250
	v_exp_f32_e32 v251, v251
	v_exp_f32_e32 v252, v252
	v_exp_f32_e32 v253, v253
	v_pk_add_f32 v[246:247], v[246:247], s[100:101] op_sel_hi:[1,0]
	v_pk_add_f32 v[248:249], v[248:249], s[100:101] op_sel_hi:[1,0]
	v_pk_add_f32 v[250:251], v[250:251], s[100:101] op_sel_hi:[1,0]
	v_pk_add_f32 v[252:253], v[252:253], s[100:101] op_sel_hi:[1,0]
	v_rcp_f32_e32 v246, v246
	v_rcp_f32_e32 v247, v247
	v_rcp_f32_e32 v248, v248
	v_rcp_f32_e32 v249, v249
	v_rcp_f32_e32 v250, v250
	v_rcp_f32_e32 v251, v251
	v_rcp_f32_e32 v252, v252
	v_rcp_f32_e32 v253, v253
	v_pk_mul_f32 v[52:53], v[52:53], v[246:247]
	v_pk_mul_f32 v[54:55], v[54:55], v[248:249]
	v_pk_mul_f32 v[50:51], v[50:51], v[250:251]
	v_pk_mul_f32 v[48:49], v[48:49], v[252:253]
.LBB0_517:
	s_or_b64 exec, exec, s[26:27]
	v_cvt_pk_bf16_f32 v52, v52, v53
	v_cvt_pk_bf16_f32 v53, v54, v55
	v_cvt_pk_bf16_f32 v54, v48, v49
	v_cvt_pk_bf16_f32 v55, v50, v51
	global_store_dwordx4 v[112:113], v[52:55], off offset:256
	s_and_saveexec_b64 s[26:27], vcc
	s_cbranch_execz .LBB0_519
	v_pk_mul_f32 v[246:247], v[44:45], v[242:243] op_sel_hi:[1,0]
	v_pk_mul_f32 v[248:249], v[46:47], v[242:243] op_sel_hi:[1,0]
	v_pk_mul_f32 v[250:251], v[42:43], v[242:243] op_sel_hi:[1,0]
	v_pk_mul_f32 v[252:253], v[40:41], v[242:243] op_sel_hi:[1,0]
	v_pk_mul_f32 v[246:247], v[44:45], v[246:247]
	v_pk_mul_f32 v[248:249], v[46:47], v[248:249]
	v_pk_mul_f32 v[250:251], v[42:43], v[250:251]
	v_pk_mul_f32 v[252:253], v[40:41], v[252:253]
	v_pk_fma_f32 v[246:247], v[44:45], v[246:247], v[44:45]
	v_pk_fma_f32 v[248:249], v[46:47], v[248:249], v[46:47]
	v_pk_fma_f32 v[250:251], v[42:43], v[250:251], v[42:43]
	v_pk_fma_f32 v[252:253], v[40:41], v[252:253], v[40:41]
	v_pk_mul_f32 v[246:247], v[246:247], v[244:245] op_sel_hi:[1,0]
	v_pk_mul_f32 v[248:249], v[248:249], v[244:245] op_sel_hi:[1,0]
	v_pk_mul_f32 v[250:251], v[250:251], v[244:245] op_sel_hi:[1,0]
	v_pk_mul_f32 v[252:253], v[252:253], v[244:245] op_sel_hi:[1,0]
	v_pk_mul_f32 v[246:247], v[246:247], s[98:99] op_sel_hi:[1,0]
	v_pk_mul_f32 v[248:249], v[248:249], s[98:99] op_sel_hi:[1,0]
	v_pk_mul_f32 v[250:251], v[250:251], s[98:99] op_sel_hi:[1,0]
	v_pk_mul_f32 v[252:253], v[252:253], s[98:99] op_sel_hi:[1,0]
	v_exp_f32_e32 v246, v246
	v_exp_f32_e32 v247, v247
	v_exp_f32_e32 v248, v248
	v_exp_f32_e32 v249, v249
	v_exp_f32_e32 v250, v250
	v_exp_f32_e32 v251, v251
	v_exp_f32_e32 v252, v252
	v_exp_f32_e32 v253, v253
	v_pk_add_f32 v[246:247], v[246:247], s[100:101] op_sel_hi:[1,0]
	v_pk_add_f32 v[248:249], v[248:249], s[100:101] op_sel_hi:[1,0]
	v_pk_add_f32 v[250:251], v[250:251], s[100:101] op_sel_hi:[1,0]
	v_pk_add_f32 v[252:253], v[252:253], s[100:101] op_sel_hi:[1,0]
	v_rcp_f32_e32 v246, v246
	v_rcp_f32_e32 v247, v247
	v_rcp_f32_e32 v248, v248
	v_rcp_f32_e32 v249, v249
	v_rcp_f32_e32 v250, v250
	v_rcp_f32_e32 v251, v251
	v_rcp_f32_e32 v252, v252
	v_rcp_f32_e32 v253, v253
	v_pk_mul_f32 v[44:45], v[44:45], v[246:247]
	v_pk_mul_f32 v[46:47], v[46:47], v[248:249]
	v_pk_mul_f32 v[42:43], v[42:43], v[250:251]
	v_pk_mul_f32 v[40:41], v[40:41], v[252:253]
; __device__ __forceinline__ unsigned cvt_pk_bf16(float lo, float hi) { unsigned r; asm volatile("v_cvt_pk_bf16_f32 %0, %1, %2" : "=v"(r) : "v"(lo), "v"(hi)); return r; }
; __device__ __forceinline__ float bf_lo(unsigned w) { return __uint_as_float(w << 16); }
; __device__ __forceinline__ float bf_hi(unsigned w) { return __uint_as_float(w & 0xffff0000u); }
; __device__ __forceinline__ float sigmoid_f(float x) { return __builtin_amdgcn_rcpf(1.0f + __expf(-x)); }
;     __device__ __forceinline__ void operator()(const f32x4 (&acc)[2][2][4][2], const Unit& u, int wr, int wc, int fr, int fq) const {
;         const int row0 = u.pm * BM + wr * 64 + fr; const int col0 = u.pn * BM + wc * 32 + 8 * fq;
; #pragma unroll
;         for (int bj = 0; bj < 2; ++bj) {
;             const int col = col0 + bj * HALF;
;             f32x4 b0 = (f32x4){0.f, 0.f, 0.f, 0.f}, b1 = b0;
;             if (MODE == 2) { b0 = *(const f32x4*)(bias + col); b1 = *(const f32x4*)(bias + col + 4); }
;             const bool act = (MODE == 1) && (col < act_cols);
; #pragma unroll
;             for (int ai = 0; ai < 2; ++ai)
; #pragma unroll
;                 for (int m = 0; m < 4; ++m) {
;                     const size_t row = (size_t)(row0 + ai * HALF + m * 16);
;                     f32x4 v0 = acc[ai][bj][m][0], v1 = acc[ai][bj][m][1];
;                     if (MODE == 1) { if (act) {
; #pragma unroll
;                         for (int j = 0; j < 4; ++j) { v0[j] = gelu_t(v0[j]); v1[j] = gelu_t(v1[j]); } } }
;                     if (MODE == 2) {
;                         const u32x4 y = *(const u32x4*)(Y + row * ldy + col);
;                         v0 = v0 + b0; v1 = v1 + b1;
;                         v0[0] = bf_lo(y.x) * sigmoid_f(v0[0]); v0[1] = bf_hi(y.x) * sigmoid_f(v0[1]); v0[2] = bf_lo(y.y) * sigmoid_f(v0[2]); v0[3] = bf_hi(y.y) * sigmoid_f(v0[3]);
;                         v1[0] = bf_lo(y.z) * sigmoid_f(v1[0]); v1[1] = bf_hi(y.z) * sigmoid_f(v1[1]); v1[2] = bf_lo(y.w) * sigmoid_f(v1[2]); v1[3] = bf_hi(y.w) * sigmoid_f(v1[3]);
;                     }
;                     u32x4 w; w.x = cvt_pk_bf16(v0[0], v0[1]); w.y = cvt_pk_bf16(v0[2], v0[3]); w.z = cvt_pk_bf16(v1[0], v1[1]); w.w = cvt_pk_bf16(v1[2], v1[3]);
;                     *(u32x4*)(O + row * ldc + col) = w;
;                 }
.LBB0_519:
	s_or_b64 exec, exec, s[26:27]
	v_cvt_pk_bf16_f32 v44, v44, v45
	v_cvt_pk_bf16_f32 v45, v46, v47
	v_cvt_pk_bf16_f32 v46, v40, v41
	v_cvt_pk_bf16_f32 v47, v42, v43
	global_store_dwordx4 v[104:105], v[44:47], off offset:256
	s_and_saveexec_b64 s[26:27], vcc
	s_cbranch_execz .LBB0_521
	v_pk_mul_f32 v[246:247], v[36:37], v[242:243] op_sel_hi:[1,0]
	v_pk_mul_f32 v[248:249], v[38:39], v[242:243] op_sel_hi:[1,0]
	v_pk_mul_f32 v[250:251], v[34:35], v[242:243] op_sel_hi:[1,0]
	v_pk_mul_f32 v[252:253], v[32:33], v[242:243] op_sel_hi:[1,0]
	v_pk_mul_f32 v[246:247], v[36:37], v[246:247]
	v_pk_mul_f32 v[248:249], v[38:39], v[248:249]
	v_pk_mul_f32 v[250:251], v[34:35], v[250:251]
	v_pk_mul_f32 v[252:253], v[32:33], v[252:253]
	v_pk_fma_f32 v[246:247], v[36:37], v[246:247], v[36:37]
	v_pk_fma_f32 v[248:249], v[38:39], v[248:249], v[38:39]
	v_pk_fma_f32 v[250:251], v[34:35], v[250:251], v[34:35]
	v_pk_fma_f32 v[252:253], v[32:33], v[252:253], v[32:33]
	v_pk_mul_f32 v[246:247], v[246:247], v[244:245] op_sel_hi:[1,0]
	v_pk_mul_f32 v[248:249], v[248:249], v[244:245] op_sel_hi:[1,0]
	v_pk_mul_f32 v[250:251], v[250:251], v[244:245] op_sel_hi:[1,0]
	v_pk_mul_f32 v[252:253], v[252:253], v[244:245] op_sel_hi:[1,0]
	v_pk_mul_f32 v[246:247], v[246:247], s[98:99] op_sel_hi:[1,0]
	v_pk_mul_f32 v[248:249], v[248:249], s[98:99] op_sel_hi:[1,0]
	v_pk_mul_f32 v[250:251], v[250:251], s[98:99] op_sel_hi:[1,0]
	v_pk_mul_f32 v[252:253], v[252:253], s[98:99] op_sel_hi:[1,0]
	v_exp_f32_e32 v246, v246
	v_exp_f32_e32 v247, v247
	v_exp_f32_e32 v248, v248
	v_exp_f32_e32 v249, v249
	v_exp_f32_e32 v250, v250
	v_exp_f32_e32 v251, v251
	v_exp_f32_e32 v252, v252
	v_exp_f32_e32 v253, v253
	v_pk_add_f32 v[246:247], v[246:247], s[100:101] op_sel_hi:[1,0]
	v_pk_add_f32 v[248:249], v[248:249], s[100:101] op_sel_hi:[1,0]
	v_pk_add_f32 v[250:251], v[250:251], s[100:101] op_sel_hi:[1,0]
	v_pk_add_f32 v[252:253], v[252:253], s[100:101] op_sel_hi:[1,0]
	v_rcp_f32_e32 v246, v246
	v_rcp_f32_e32 v247, v247
	v_rcp_f32_e32 v248, v248
	v_rcp_f32_e32 v249, v249
	v_rcp_f32_e32 v250, v250
	v_rcp_f32_e32 v251, v251
	v_rcp_f32_e32 v252, v252
	v_rcp_f32_e32 v253, v253
	v_pk_mul_f32 v[36:37], v[36:37], v[246:247]
	v_pk_mul_f32 v[38:39], v[38:39], v[248:249]
	v_pk_mul_f32 v[34:35], v[34:35], v[250:251]
	v_pk_mul_f32 v[32:33], v[32:33], v[252:253]
.LBB0_521:
	s_or_b64 exec, exec, s[26:27]
	v_cvt_pk_bf16_f32 v36, v36, v37
	v_cvt_pk_bf16_f32 v37, v38, v39
	v_cvt_pk_bf16_f32 v38, v32, v33
	v_cvt_pk_bf16_f32 v39, v34, v35
	global_store_dwordx4 v[96:97], v[36:39], off offset:256
	s_and_saveexec_b64 s[26:27], vcc
	s_cbranch_execz .LBB0_523
	v_pk_mul_f32 v[246:247], v[28:29], v[242:243] op_sel_hi:[1,0]
	v_pk_mul_f32 v[248:249], v[30:31], v[242:243] op_sel_hi:[1,0]
	v_pk_mul_f32 v[250:251], v[26:27], v[242:243] op_sel_hi:[1,0]
	v_pk_mul_f32 v[252:253], v[24:25], v[242:243] op_sel_hi:[1,0]
	v_pk_mul_f32 v[246:247], v[28:29], v[246:247]
	v_pk_mul_f32 v[248:249], v[30:31], v[248:249]
	v_pk_mul_f32 v[250:251], v[26:27], v[250:251]
	v_pk_mul_f32 v[252:253], v[24:25], v[252:253]
	v_pk_fma_f32 v[246:247], v[28:29], v[246:247], v[28:29]
	v_pk_fma_f32 v[248:249], v[30:31], v[248:249], v[30:31]
	v_pk_fma_f32 v[250:251], v[26:27], v[250:251], v[26:27]
	v_pk_fma_f32 v[252:253], v[24:25], v[252:253], v[24:25]
	v_pk_mul_f32 v[246:247], v[246:247], v[244:245] op_sel_hi:[1,0]
	v_pk_mul_f32 v[248:249], v[248:249], v[244:245] op_sel_hi:[1,0]
	v_pk_mul_f32 v[250:251], v[250:251], v[244:245] op_sel_hi:[1,0]
	v_pk_mul_f32 v[252:253], v[252:253], v[244:245] op_sel_hi:[1,0]
	v_pk_mul_f32 v[246:247], v[246:247], s[98:99] op_sel_hi:[1,0]
	v_pk_mul_f32 v[248:249], v[248:249], s[98:99] op_sel_hi:[1,0]
	v_pk_mul_f32 v[250:251], v[250:251], s[98:99] op_sel_hi:[1,0]
	v_pk_mul_f32 v[252:253], v[252:253], s[98:99] op_sel_hi:[1,0]
	v_exp_f32_e32 v246, v246
	v_exp_f32_e32 v247, v247
	v_exp_f32_e32 v248, v248
	v_exp_f32_e32 v249, v249
	v_exp_f32_e32 v250, v250
	v_exp_f32_e32 v251, v251
	v_exp_f32_e32 v252, v252
	v_exp_f32_e32 v253, v253
	v_pk_add_f32 v[246:247], v[246:247], s[100:101] op_sel_hi:[1,0]
	v_pk_add_f32 v[248:249], v[248:249], s[100:101] op_sel_hi:[1,0]
	v_pk_add_f32 v[250:251], v[250:251], s[100:101] op_sel_hi:[1,0]
	v_pk_add_f32 v[252:253], v[252:253], s[100:101] op_sel_hi:[1,0]
	v_rcp_f32_e32 v246, v246
	v_rcp_f32_e32 v247, v247
	v_rcp_f32_e32 v248, v248
	v_rcp_f32_e32 v249, v249
	v_rcp_f32_e32 v250, v250
	v_rcp_f32_e32 v251, v251
	v_rcp_f32_e32 v252, v252
	v_rcp_f32_e32 v253, v253
	v_pk_mul_f32 v[28:29], v[28:29], v[246:247]
	v_pk_mul_f32 v[30:31], v[30:31], v[248:249]
	v_pk_mul_f32 v[26:27], v[26:27], v[250:251]
	v_pk_mul_f32 v[24:25], v[24:25], v[252:253]
; __device__ __forceinline__ unsigned cvt_pk_bf16(float lo, float hi) { unsigned r; asm volatile("v_cvt_pk_bf16_f32 %0, %1, %2" : "=v"(r) : "v"(lo), "v"(hi)); return r; }
; __device__ __forceinline__ float bf_lo(unsigned w) { return __uint_as_float(w << 16); }
; __device__ __forceinline__ float bf_hi(unsigned w) { return __uint_as_float(w & 0xffff0000u); }
; __device__ __forceinline__ float sigmoid_f(float x) { return __builtin_amdgcn_rcpf(1.0f + __expf(-x)); }
;     __device__ __forceinline__ void operator()(const f32x4 (&acc)[2][2][4][2], const Unit& u, int wr, int wc, int fr, int fq) const {
;         const int row0 = u.pm * BM + wr * 64 + fr; const int col0 = u.pn * BM + wc * 32 + 8 * fq;
; #pragma unroll
;         for (int bj = 0; bj < 2; ++bj) {
;             const int col = col0 + bj * HALF;
;             f32x4 b0 = (f32x4){0.f, 0.f, 0.f, 0.f}, b1 = b0;
;             if (MODE == 2) { b0 = *(const f32x4*)(bias + col); b1 = *(const f32x4*)(bias + col + 4); }
;             const bool act = (MODE == 1) && (col < act_cols);
; #pragma unroll
;             for (int ai = 0; ai < 2; ++ai)
; #pragma unroll
;                 for (int m = 0; m < 4; ++m) {
;                     const size_t row = (size_t)(row0 + ai * HALF + m * 16);
;                     f32x4 v0 = acc[ai][bj][m][0], v1 = acc[ai][bj][m][1];
;                     if (MODE == 1) { if (act) {
; #pragma unroll
;                         for (int j = 0; j < 4; ++j) { v0[j] = gelu_t(v0[j]); v1[j] = gelu_t(v1[j]); } } }
;                     if (MODE == 2) {
;                         const u32x4 y = *(const u32x4*)(Y + row * ldy + col);
;                         v0 = v0 + b0; v1 = v1 + b1;
;                         v0[0] = bf_lo(y.x) * sigmoid_f(v0[0]); v0[1] = bf_hi(y.x) * sigmoid_f(v0[1]); v0[2] = bf_lo(y.y) * sigmoid_f(v0[2]); v0[3] = bf_hi(y.y) * sigmoid_f(v0[3]);
;                         v1[0] = bf_lo(y.z) * sigmoid_f(v1[0]); v1[1] = bf_hi(y.z) * sigmoid_f(v1[1]); v1[2] = bf_lo(y.w) * sigmoid_f(v1[2]); v1[3] = bf_hi(y.w) * sigmoid_f(v1[3]);
;                     }
;                     u32x4 w; w.x = cvt_pk_bf16(v0[0], v0[1]); w.y = cvt_pk_bf16(v0[2], v0[3]); w.z = cvt_pk_bf16(v1[0], v1[1]); w.w = cvt_pk_bf16(v1[2], v1[3]);
;                     *(u32x4*)(O + row * ldc + col) = w;
;                 }
.LBB0_523:
	s_or_b64 exec, exec, s[26:27]
	v_cvt_pk_bf16_f32 v28, v28, v29
	v_cvt_pk_bf16_f32 v29, v30, v31
	v_cvt_pk_bf16_f32 v30, v24, v25
	v_cvt_pk_bf16_f32 v31, v26, v27
	global_store_dwordx4 v[88:89], v[28:31], off offset:256
	s_and_saveexec_b64 s[26:27], vcc
	s_cbranch_execz .LBB0_525
	v_pk_mul_f32 v[246:247], v[20:21], v[242:243] op_sel_hi:[1,0]
	v_pk_mul_f32 v[248:249], v[22:23], v[242:243] op_sel_hi:[1,0]
	v_pk_mul_f32 v[250:251], v[18:19], v[242:243] op_sel_hi:[1,0]
	v_pk_mul_f32 v[252:253], v[16:17], v[242:243] op_sel_hi:[1,0]
	v_pk_mul_f32 v[246:247], v[20:21], v[246:247]
	v_pk_mul_f32 v[248:249], v[22:23], v[248:249]
	v_pk_mul_f32 v[250:251], v[18:19], v[250:251]
	v_pk_mul_f32 v[252:253], v[16:17], v[252:253]
	v_pk_fma_f32 v[246:247], v[20:21], v[246:247], v[20:21]
	v_pk_fma_f32 v[248:249], v[22:23], v[248:249], v[22:23]
	v_pk_fma_f32 v[250:251], v[18:19], v[250:251], v[18:19]
	v_pk_fma_f32 v[252:253], v[16:17], v[252:253], v[16:17]
	v_pk_mul_f32 v[246:247], v[246:247], v[244:245] op_sel_hi:[1,0]
	v_pk_mul_f32 v[248:249], v[248:249], v[244:245] op_sel_hi:[1,0]
	v_pk_mul_f32 v[250:251], v[250:251], v[244:245] op_sel_hi:[1,0]
	v_pk_mul_f32 v[252:253], v[252:253], v[244:245] op_sel_hi:[1,0]
	v_pk_mul_f32 v[246:247], v[246:247], s[98:99] op_sel_hi:[1,0]
	v_pk_mul_f32 v[248:249], v[248:249], s[98:99] op_sel_hi:[1,0]
	v_pk_mul_f32 v[250:251], v[250:251], s[98:99] op_sel_hi:[1,0]
	v_pk_mul_f32 v[252:253], v[252:253], s[98:99] op_sel_hi:[1,0]
	v_exp_f32_e32 v246, v246
	v_exp_f32_e32 v247, v247
	v_exp_f32_e32 v248, v248
	v_exp_f32_e32 v249, v249
	v_exp_f32_e32 v250, v250
	v_exp_f32_e32 v251, v251
	v_exp_f32_e32 v252, v252
	v_exp_f32_e32 v253, v253
	v_pk_add_f32 v[246:247], v[246:247], s[100:101] op_sel_hi:[1,0]
	v_pk_add_f32 v[248:249], v[248:249], s[100:101] op_sel_hi:[1,0]
	v_pk_add_f32 v[250:251], v[250:251], s[100:101] op_sel_hi:[1,0]
	v_pk_add_f32 v[252:253], v[252:253], s[100:101] op_sel_hi:[1,0]
	v_rcp_f32_e32 v246, v246
	v_rcp_f32_e32 v247, v247
	v_rcp_f32_e32 v248, v248
	v_rcp_f32_e32 v249, v249
	v_rcp_f32_e32 v250, v250
	v_rcp_f32_e32 v251, v251
	v_rcp_f32_e32 v252, v252
	v_rcp_f32_e32 v253, v253
	v_pk_mul_f32 v[20:21], v[20:21], v[246:247]
	v_pk_mul_f32 v[22:23], v[22:23], v[248:249]
	v_pk_mul_f32 v[18:19], v[18:19], v[250:251]
	v_pk_mul_f32 v[16:17], v[16:17], v[252:253]
.LBB0_525:
	s_or_b64 exec, exec, s[26:27]
	v_cvt_pk_bf16_f32 v20, v20, v21
	v_cvt_pk_bf16_f32 v21, v22, v23
	v_cvt_pk_bf16_f32 v22, v16, v17
	v_cvt_pk_bf16_f32 v23, v18, v19
	global_store_dwordx4 v[80:81], v[20:23], off offset:256
	s_and_saveexec_b64 s[26:27], vcc
	s_cbranch_execz .LBB0_527
	v_pk_mul_f32 v[246:247], v[12:13], v[242:243] op_sel_hi:[1,0]
	v_pk_mul_f32 v[248:249], v[14:15], v[242:243] op_sel_hi:[1,0]
	v_pk_mul_f32 v[250:251], v[10:11], v[242:243] op_sel_hi:[1,0]
	v_pk_mul_f32 v[252:253], v[8:9], v[242:243] op_sel_hi:[1,0]
	v_pk_mul_f32 v[246:247], v[12:13], v[246:247]
	v_pk_mul_f32 v[248:249], v[14:15], v[248:249]
	v_pk_mul_f32 v[250:251], v[10:11], v[250:251]
	v_pk_mul_f32 v[252:253], v[8:9], v[252:253]
	v_pk_fma_f32 v[246:247], v[12:13], v[246:247], v[12:13]
	v_pk_fma_f32 v[248:249], v[14:15], v[248:249], v[14:15]
	v_pk_fma_f32 v[250:251], v[10:11], v[250:251], v[10:11]
	v_pk_fma_f32 v[252:253], v[8:9], v[252:253], v[8:9]
	v_pk_mul_f32 v[246:247], v[246:247], v[244:245] op_sel_hi:[1,0]
	v_pk_mul_f32 v[248:249], v[248:249], v[244:245] op_sel_hi:[1,0]
	v_pk_mul_f32 v[250:251], v[250:251], v[244:245] op_sel_hi:[1,0]
	v_pk_mul_f32 v[252:253], v[252:253], v[244:245] op_sel_hi:[1,0]
	v_pk_mul_f32 v[246:247], v[246:247], s[98:99] op_sel_hi:[1,0]
	v_pk_mul_f32 v[248:249], v[248:249], s[98:99] op_sel_hi:[1,0]
	v_pk_mul_f32 v[250:251], v[250:251], s[98:99] op_sel_hi:[1,0]
	v_pk_mul_f32 v[252:253], v[252:253], s[98:99] op_sel_hi:[1,0]
	v_exp_f32_e32 v246, v246
	v_exp_f32_e32 v247, v247
	v_exp_f32_e32 v248, v248
	v_exp_f32_e32 v249, v249
	v_exp_f32_e32 v250, v250
	v_exp_f32_e32 v251, v251
	v_exp_f32_e32 v252, v252
	v_exp_f32_e32 v253, v253
	v_pk_add_f32 v[246:247], v[246:247], s[100:101] op_sel_hi:[1,0]
	v_pk_add_f32 v[248:249], v[248:249], s[100:101] op_sel_hi:[1,0]
	v_pk_add_f32 v[250:251], v[250:251], s[100:101] op_sel_hi:[1,0]
	v_pk_add_f32 v[252:253], v[252:253], s[100:101] op_sel_hi:[1,0]
	v_rcp_f32_e32 v246, v246
	v_rcp_f32_e32 v247, v247
	v_rcp_f32_e32 v248, v248
	v_rcp_f32_e32 v249, v249
	v_rcp_f32_e32 v250, v250
	v_rcp_f32_e32 v251, v251
	v_rcp_f32_e32 v252, v252
	v_rcp_f32_e32 v253, v253
	v_pk_mul_f32 v[12:13], v[12:13], v[246:247]
	v_pk_mul_f32 v[14:15], v[14:15], v[248:249]
	v_pk_mul_f32 v[10:11], v[10:11], v[250:251]
	v_pk_mul_f32 v[8:9], v[8:9], v[252:253]
.LBB0_527:
	s_or_b64 exec, exec, s[26:27]
	v_cvt_pk_bf16_f32 v12, v12, v13
	v_cvt_pk_bf16_f32 v13, v14, v15
	v_cvt_pk_bf16_f32 v14, v8, v9
	v_cvt_pk_bf16_f32 v15, v10, v11
	global_store_dwordx4 v[72:73], v[12:15], off offset:256
	s_and_saveexec_b64 s[26:27], vcc
	s_cbranch_execz .LBB0_529
	v_pk_mul_f32 v[246:247], v[4:5], v[242:243] op_sel_hi:[1,0]
	v_pk_mul_f32 v[248:249], v[6:7], v[242:243] op_sel_hi:[1,0]
	v_pk_mul_f32 v[250:251], v[2:3], v[242:243] op_sel_hi:[1,0]
	v_pk_mul_f32 v[252:253], v[0:1], v[242:243] op_sel_hi:[1,0]
	v_pk_mul_f32 v[246:247], v[4:5], v[246:247]
	v_pk_mul_f32 v[248:249], v[6:7], v[248:249]
	v_pk_mul_f32 v[250:251], v[2:3], v[250:251]
	v_pk_mul_f32 v[252:253], v[0:1], v[252:253]
	v_pk_fma_f32 v[246:247], v[4:5], v[246:247], v[4:5]
	v_pk_fma_f32 v[248:249], v[6:7], v[248:249], v[6:7]
	v_pk_fma_f32 v[250:251], v[2:3], v[250:251], v[2:3]
	v_pk_fma_f32 v[252:253], v[0:1], v[252:253], v[0:1]
	v_pk_mul_f32 v[246:247], v[246:247], v[244:245] op_sel_hi:[1,0]
	v_pk_mul_f32 v[248:249], v[248:249], v[244:245] op_sel_hi:[1,0]
	v_pk_mul_f32 v[250:251], v[250:251], v[244:245] op_sel_hi:[1,0]
	v_pk_mul_f32 v[252:253], v[252:253], v[244:245] op_sel_hi:[1,0]
	v_pk_mul_f32 v[246:247], v[246:247], s[98:99] op_sel_hi:[1,0]
	v_pk_mul_f32 v[248:249], v[248:249], s[98:99] op_sel_hi:[1,0]
	v_pk_mul_f32 v[250:251], v[250:251], s[98:99] op_sel_hi:[1,0]
	v_pk_mul_f32 v[252:253], v[252:253], s[98:99] op_sel_hi:[1,0]
	v_exp_f32_e32 v246, v246
	v_exp_f32_e32 v247, v247
	v_exp_f32_e32 v248, v248
	v_exp_f32_e32 v249, v249
	v_exp_f32_e32 v250, v250
	v_exp_f32_e32 v251, v251
	v_exp_f32_e32 v252, v252
	v_exp_f32_e32 v253, v253
	v_pk_add_f32 v[246:247], v[246:247], s[100:101] op_sel_hi:[1,0]
	v_pk_add_f32 v[248:249], v[248:249], s[100:101] op_sel_hi:[1,0]
	v_pk_add_f32 v[250:251], v[250:251], s[100:101] op_sel_hi:[1,0]
	v_pk_add_f32 v[252:253], v[252:253], s[100:101] op_sel_hi:[1,0]
	v_rcp_f32_e32 v246, v246
	v_rcp_f32_e32 v247, v247
	v_rcp_f32_e32 v248, v248
	v_rcp_f32_e32 v249, v249
	v_rcp_f32_e32 v250, v250
	v_rcp_f32_e32 v251, v251
	v_rcp_f32_e32 v252, v252
	v_rcp_f32_e32 v253, v253
	v_pk_mul_f32 v[4:5], v[4:5], v[246:247]
	v_pk_mul_f32 v[6:7], v[6:7], v[248:249]
	v_pk_mul_f32 v[2:3], v[2:3], v[250:251]
	v_pk_mul_f32 v[0:1], v[0:1], v[252:253]

; __device__ __forceinline__ int fresh_tid() { int t = (int)threadIdx.x; asm volatile("" : "+v"(t)); return t; }
; #define PG8_STAGE(bufoff, gbase, voff) do { _Pragma("unroll") for (int _i = 0; _i < 2; ++_i) \
;         __builtin_amdgcn_global_load_lds((const unsigned*)((const char*)(gbase) + (voff)[_i]), (PG8_LAS unsigned*)(lds + (bufoff) + ldsw + _i * 8192), 16, 0, 0); } while (0)
; #define PG8_WAIT_V(n) asm volatile("s_waitcnt vmcnt(" #n ")" ::: "memory")
; #define PG8_BAR __builtin_amdgcn_s_barrier()
; template <class Epi, class Sched, bool ALIGN_EPI = false, bool SP2 = false>
; __device__ __forceinline__ void gemm_phase(PG8_LAS unsigned char* lds, const Gemm g, const Sched& S, const Epi& E) {
;     const int tid = fresh_tid(), wid = __builtin_amdgcn_readfirstlane(tid >> 6), lane = tid & 63, wr = wid >> 2, wc = wid & 3, fr = lane & 15, fq = lane >> 4;
;     const int K = g.K, nt = K / BK;
;     unsigned voffA[2], voffB[2];
; #pragma unroll
;     for (int i = 0; i < 2; ++i) { int R, C; stage_rc(tid * 16 + i * 8192, R, C); const int Rb = Epi::PERM ? ((R & ~31) + perm32(R & 31)) : R;
;         voffA[i] = (unsigned)(R * K + C) * 2u; voffB[i] = (unsigned)(Rb * K + C) * 2u; }
;     const size_t kstep = (size_t)(BK * 2);
;     const size_t hstep = (size_t)HALF * K * 2;
;     const size_t tstep = 2 * hstep;
;     const unsigned ldsw = (unsigned)wid * 1024u;
;     const int aoff = lds_byte(wr * 64 + fr, fq * 8), boff = lds_byte(wc * 32 + fr, fq * 8);
;     ...
;     if constexpr (SP2) {
;         PG8_STAGE(PG8_SB(0, 0), cB, voffB); PG8_STAGE(PG8_SB(0, 1), cB + hstep, voffB); PG8_STAGE(PG8_SA(0, 0), cA, voffA); PG8_STAGE(PG8_SA(0, 1), cA + hstep, voffA);
;         if (wr == 1) PG8_BAR;
;         PG8_WAIT_V(2); PG8_BAR;
;         PG8_STAGE(PG8_SB(1, 0), cB + kstep, voffB); PG8_STAGE(PG8_SA(1, 0), cA + kstep, voffA); PG8_STAGE(PG8_SB(1, 1), cB + hstep + kstep, voffB);
;         PG8_WAIT_V(6); PG8_BAR;
.LBB0_917:
	v_ashrrev_i32_e32 v1, 31, v8
	v_lshrrev_b32_e32 v1, 26, v1
	v_add_u32_e32 v1, v8, v1
	v_ashrrev_i32_e32 v9, 6, v1
	v_bfe_i32 v1, v8, 27, 1
	v_lshlrev_b32_e32 v0, 4, v8
	v_lshrrev_b32_e32 v1, 22, v1
	v_add_u32_e32 v1, v0, v1
	v_and_b32_e32 v1, 0xfffffc00, v1
	v_sub_u32_e32 v1, v0, v1
	v_lshrrev_b32_e32 v2, 4, v1
	v_bitop3_b32 v2, v2, v1, 32 bitop3:0x6c
	v_ashrrev_i32_e32 v1, 31, v1
	v_lshrrev_b32_e32 v1, 26, v1
	v_add_u32_e32 v1, v2, v1
	v_ashrrev_i32_e32 v10, 6, v1
	v_lshlrev_b32_e32 v3, 3, v9
	v_mul_i32_i24_e32 v4, 64, v10
	v_and_b32_e32 v3, -16, v3
	v_sub_u32_e32 v2, v2, v4
	v_mov_b32_e32 v4, 1
	v_add_u32_e32 v1, v10, v3
	v_lshlrev_b32_e32 v3, 5, v9
	v_ashrrev_i16_sdwa v2, v4, sext(v2) dst_sel:DWORD dst_unused:UNUSED_PAD src0_sel:DWORD src1_sel:BYTE_0
	v_and_b32_e32 v3, 32, v3
	v_bfe_i32 v11, v2, 0, 16
	v_and_b32_e32 v6, 3, v10
	s_mov_b32 s1, 0x1fffe0
	v_add_lshl_u32 v3, v3, v11, 1
	v_add_u32_e32 v0, 0x2000, v0
	v_lshlrev_b32_e32 v2, 1, v1
	v_lshrrev_b32_e32 v5, 2, v1
	v_and_or_b32 v6, v1, s1, v6
	v_lshl_add_u32 v128, v1, 11, v3
	v_ashrrev_i32_e32 v1, 31, v0
	v_lshrrev_b32_e32 v1, 22, v1
	v_add_u32_e32 v1, v0, v1
	v_ashrrev_i32_e32 v12, 10, v1
	v_mul_i32_i24_e32 v1, 0x400, v12
	v_sub_u32_e32 v0, v0, v1
	v_and_b32_e32 v2, 24, v2
	v_and_b32_e32 v5, 4, v5
	v_lshrrev_b32_e32 v1, 4, v0
	v_or3_b32 v2, v6, v5, v2
	v_bitop3_b32 v0, v1, v0, 32 bitop3:0x6c
	v_lshl_add_u32 v130, v2, 11, v3
	v_ashrrev_i32_e32 v2, 31, v0
	s_ashr_i32 s0, s18, 3
	v_lshrrev_b32_e32 v2, 26, v2
	s_waitcnt lgkmcnt(0)
	s_add_u32 s43, s14, 0x16400000
	v_add_u32_e32 v2, v0, v2
	s_addc_u32 s47, s15, 0
	v_lshlrev_b32_e32 v1, 3, v12
	v_ashrrev_i32_e32 v13, 6, v2
	v_and_b32_e32 v2, 0xc0, v2
	s_add_u32 s54, s12, 0x1600000
	v_and_b32_e32 v1, -16, v1
	v_sub_u32_e32 v0, v0, v2
	s_addc_u32 s55, s13, 0
	v_add_u32_e32 v1, v13, v1
	v_ashrrev_i16_sdwa v0, v4, sext(v0) dst_sel:DWORD dst_unused:UNUSED_PAD src0_sel:DWORD src1_sel:BYTE_0
	v_and_b32_e32 v4, 3, v13
	s_add_i32 s0, s19, s0
	v_and_or_b32 v4, v1, s1, v4
	s_ashr_i32 s1, s0, 31
	s_lshr_b32 s1, s1, 27
	s_add_i32 s1, s0, s1
	s_ashr_i32 s3, s1, 5
	s_andn2_b32 s1, s1, 31
	s_sub_i32 s0, s0, s1
	s_bfe_i32 s1, s0, 0x80000
	s_bfe_u32 s1, s1, 0x3000c
	s_add_i32 s1, s0, s1
	s_bfe_i32 s12, s1, 0x80000
	s_and_b32 s1, s1, 0xf8
	s_sub_i32 s0, s0, s1
	s_lshl_b32 s3, s3, 3
	s_sext_i32_i16 s12, s12
	s_sext_i32_i8 s0, s0
	s_lshr_b32 s20, s12, 3
	s_add_i32 s38, s3, s0
	s_ashr_i32 s18, s21, 6
	s_ashr_i32 s39, s38, 31
	s_bfe_i64 s[12:13], s[20:21], 0x100000
	s_ashr_i32 s22, s21, 8
	s_lshl_b32 s56, s18, 10
	s_lshl_b64 s[0:1], s[38:39], 19
	s_lshl_b64 s[12:13], s[12:13], 19
	s_add_u32 s50, s54, s12
	v_lshlrev_b32_e32 v3, 5, v12
	v_bfe_i32 v14, v0, 0, 16
	v_lshlrev_b32_e32 v0, 1, v1
	v_lshrrev_b32_e32 v2, 2, v1
	s_addc_u32 s51, s55, s13
	s_add_i32 s39, s56, 0
	v_and_b32_e32 v3, 32, v3
	v_and_b32_e32 v0, 24, v0
	v_and_b32_e32 v2, 4, v2
	s_add_i32 m0, s39, 0x10000
	v_or3_b32 v0, v4, v2, v0
	v_add_lshl_u32 v2, v3, v14, 1
	v_bfe_u32 v239, v8, 3, 3
	v_and_b32_e32 v240, 7, v8
	v_xor_b32_e32 v240, v240, v239
	v_lshlrev_b32_e32 v240, 4, v240
	v_lshrrev_b32_e32 v241, 6, v8
	v_lshl_add_u32 v242, v241, 3, v239
	v_mov_b32_e32 v243, 0x800
	v_mad_u32_u24 v128, v242, v243, v240
	v_add_u32_e32 v132, 0x20000, v128
	v_lshrrev_b32_e32 v244, 2, v241
	v_lshlrev_b32_e32 v244, 5, v244
	v_and_b32_e32 v245, 1, v241
	v_lshrrev_b32_e32 v246, 2, v239
	v_lshl_add_u32 v245, v245, 1, v246
	v_lshl_add_u32 v244, v245, 3, v244
	v_bfe_u32 v245, v241, 1, 1
	v_lshl_add_u32 v244, v245, 2, v244
	v_and_b32_e32 v245, 3, v239
	v_add_u32_e32 v244, v244, v245
	v_mad_u32_u24 v130, v244, v243, v240
	v_add_u32_e32 v134, 0x20000, v130
	global_load_lds_dwordx4 v130, s[50:51]
	s_add_i32 m0, s39, 0x12000
	s_add_u32 s12, s50, 0x40000
	global_load_lds_dwordx4 v134, s[50:51]
	s_addc_u32 s13, s51, 0
	s_add_i32 m0, s39, 0x14000
	global_load_lds_dwordx4 v130, s[12:13]
	s_add_i32 m0, s39, 0x16000
	s_add_u32 s40, s43, s0
	s_addc_u32 s41, s47, s1
	s_add_i32 s57, s39, 0x2000
	global_load_lds_dwordx4 v134, s[12:13]
	s_mov_b32 m0, s39
	s_add_u32 s0, s40, 0x40000
	global_load_lds_dwordx4 v128, s[40:41]
	s_mov_b32 m0, s57
	s_addc_u32 s1, s41, 0
	s_add_i32 s58, s39, 0x4000
	global_load_lds_dwordx4 v132, s[40:41]
	s_mov_b32 m0, s58
	s_add_i32 s59, s39, 0x6000
	global_load_lds_dwordx4 v128, s[0:1]
	s_mov_b32 m0, s59
	v_mov_b32_e32 v131, 0
	global_load_lds_dwordx4 v132, s[0:1]
	v_mov_b32_e32 v135, v131
	v_mov_b32_e32 v129, v131
	v_mov_b32_e32 v133, v131
	s_cmp_eq_u32 s22, 1
	s_mov_b32 s60, 0
	v_lshl_add_u64 v[6:7], s[50:51], 0, v[130:131]
	v_lshl_add_u64 v[2:3], s[50:51], 0, v[134:135]
	s_mov_b64 s[12:13], 0x40000
	v_lshl_add_u64 v[0:1], s[40:41], 0, v[128:129]
	s_cselect_b64 s[14:15], -1, 0
	s_cmp_lg_u32 s22, 1
	v_lshl_add_u64 v[4:5], s[40:41], 0, v[132:133]
	s_cbranch_scc1 .LBB0_919
	s_barrier
; #define PG8_STAGE(bufoff, gbase, voff) do { _Pragma("unroll") for (int _i = 0; _i < 2; ++_i) \
;         __builtin_amdgcn_global_load_lds((const unsigned*)((const char*)(gbase) + (voff)[_i]), (PG8_LAS unsigned*)(lds + (bufoff) + ldsw + _i * 8192), 16, 0, 0); } while (0)
; #define PG8_WAIT_V(n) asm volatile("s_waitcnt vmcnt(" #n ")" ::: "memory")
; #define PG8_BAR __builtin_amdgcn_s_barrier()
; template <class Epi, class Sched, bool ALIGN_EPI = false, bool SP2 = false>
; __device__ __forceinline__ void gemm_phase(PG8_LAS unsigned char* lds, const Gemm g, const Sched& S, const Epi& E) {
;     ...
;     const int aoff = lds_byte(wr * 64 + fr, fq * 8), boff = lds_byte(wc * 32 + fr, fq * 8);
;     ...
;         PG8_STAGE(PG8_SB(1, 0), cB + kstep, voffB); PG8_STAGE(PG8_SA(1, 0), cA + kstep, voffA); PG8_STAGE(PG8_SB(1, 1), cB + hstep + kstep, voffB);
;         PG8_WAIT_V(6); PG8_BAR;
;     ...
;     for (;;) {
;         const bool has_next = S.next(ui + 1, nxt);
;         const char* nA = has_next ? (const char*)g.A + (size_t)nxt.pm * tstep : cA; const char* nB = has_next ? (const char*)g.Bt + (size_t)nxt.pn * tstep : cB;
;         for (int t = 0; t < nt; t += 2) {
;             const bool last = (t == nt - 2);
;             const char* a1 = cA + (size_t)(t + 1) * kstep;
;             const char* a2 = last ? nA : cA + (size_t)(t + 2) * kstep; const char* b2 = last ? nB : cB + (size_t)(t + 2) * kstep;
.LBB0_919:
	s_add_u32 s16, s10, 0x7100000
	s_addc_u32 s17, s11, 0
	s_lshl_b32 s0, s18, 5
	s_mov_b64 s[18:19], 0x80
	s_and_b32 s10, s0, 0x60
	s_add_i32 m0, s39, 0x18000
	v_lshl_add_u64 v[6:7], v[6:7], 0, s[18:19]
	s_lshl_b32 s3, s22, 13
	s_lshl_b32 s11, s10, 7
	s_waitcnt vmcnt(2)
	s_barrier
	global_load_lds_dwordx4 v[6:7], off
	v_lshl_add_u64 v[2:3], v[2:3], 0, s[18:19]
	s_add_i32 m0, s39, 0x1a000
	s_add_i32 s61, s39, 0x8000
	s_add_i32 s62, s39, 0xa000
	global_load_lds_dwordx4 v[2:3], off
	v_lshl_add_u64 v[0:1], v[0:1], 0, s[18:19]
	s_mov_b32 m0, s61
	s_add_u32 s0, s50, 0x40080
	global_load_lds_dwordx4 v[0:1], off
	v_lshl_add_u64 v[0:1], v[4:5], 0, s[18:19]
	s_mov_b32 m0, s62
	s_addc_u32 s1, s51, 0
	global_load_lds_dwordx4 v[0:1], off
	s_add_i32 m0, s39, 0x1c000
	v_lshl_add_u64 v[0:1], s[0:1], 0, v[130:131]
	global_load_lds_dwordx4 v[0:1], off
	v_lshl_add_u64 v[0:1], s[0:1], 0, v[134:135]
	s_add_i32 m0, s39, 0x1e000
	s_cmpk_lt_u32 s21, 0x100
	global_load_lds_dwordx4 v[0:1], off
	v_lshrrev_b32_e32 v1, 1, v8
	v_and_b32_e32 v1, 24, v1
	v_and_b32_e32 v0, 15, v8
	v_lshlrev_b32_e32 v2, 1, v1
	v_lshl_or_b32 v144, s22, 6, v0
	v_lshl_or_b32 v0, v0, 6, v2
	v_lshlrev_b32_e32 v2, 2, v8
	v_and_b32_e32 v2, 32, v2
	v_bitop3_b32 v3, v0, s3, v2 bitop3:0xde
	v_bitop3_b32 v145, v0, s11, v2 bitop3:0xde
	v_and_b32_e32 v239, 15, v8
	v_and_b32_e32 v240, 7, v239
	v_lshrrev_b32_e32 v239, 3, v239
	v_lshlrev_b32_e32 v239, 10, v239
	v_lshl_add_u32 v239, v240, 7, v239
	v_bfe_u32 v241, v8, 4, 2
	v_xor_b32_e32 v242, v241, v240
	v_or_b32_e32 v241, 4, v241
	v_xor_b32_e32 v243, v241, v240
	v_lshl_add_u32 v242, v242, 4, v239
	v_lshl_add_u32 v243, v243, 4, v239
	v_lshrrev_b32_e32 v244, 8, v8
	v_lshlrev_b32_e32 v244, 13, v244
	v_add_u32_e32 v3, v244, v242
	v_add_u32_e32 v233, v244, v243
	v_bfe_u32 v244, v8, 6, 2
	v_lshlrev_b32_e32 v244, 12, v244
	v_add_u32_e32 v145, v244, v242
	v_add_u32_e32 v234, v244, v243
	v_lshlrev_b32_e32 v0, 14, v9
	v_and_b32_e32 v0, 0xffff8000, v0
	v_or_b32_e32 v146, s10, v1
	v_lshl_add_u32 v0, v10, 11, v0
	v_and_b32_e32 v1, 1, v9
	v_lshl_or_b32 v0, v1, 6, v0
	v_lshl_add_u32 v136, v11, 1, v0
	v_mov_b32_e32 v136, v128
	v_lshlrev_b32_e32 v0, 14, v12
	v_and_b32_e32 v0, 0xffff8000, v0
	s_waitcnt vmcnt(6)
	v_lshl_add_u32 v0, v13, 11, v0
	v_and_b32_e32 v1, 1, v12
	s_sext_i32_i8 s1, s20
	s_cselect_b64 s[20:21], -1, 0
	v_lshl_or_b32 v0, v1, 6, v0
	s_add_i32 s65, 0, 0x10000
	s_add_i32 s66, 0, 0x14000
	s_ashr_i32 s63, s94, 31
	s_mov_b32 s64, s94
	v_mov_b32_e32 v137, v131
	v_lshl_add_u32 v138, v14, 1, v0
	v_mov_b32_e32 v138, v132
	v_mov_b32_e32 v139, v131
	v_mov_b64_e32 v[140:141], 0x200
	v_mov_b64_e32 v[142:143], 0x1ff
	v_add_u32_e32 v147, s65, v145
	v_add_u32_e32 v235, s65, v234
	v_add_u32_e32 v148, s66, v145
	v_add_u32_e32 v236, s66, v234
	v_add_u32_e32 v149, 0, v3
	s_mov_b32 s67, 0x40000
	s_mov_b64 s[22:23], 0x48000
	s_mov_b32 s68, 0x48000
	s_mov_b64 s[24:25], 0x50000
	s_mov_b32 s69, 0x50000
	s_mov_b64 s[26:27], 0x58000
	s_mov_b32 s0, 0x58000
	s_barrier
	s_branch .LBB0_922

; #define PG8_STAGE(bufoff, gbase, voff) do { _Pragma("unroll") for (int _i = 0; _i < 2; ++_i) \
;         __builtin_amdgcn_global_load_lds((const unsigned*)((const char*)(gbase) + (voff)[_i]), (PG8_LAS unsigned*)(lds + (bufoff) + ldsw + _i * 8192), 16, 0, 0); } while (0)
; #define PG8_LDA(dst, b, h) do { _Pragma("unroll") for (int m = 0; m < 4; ++m) _Pragma("unroll") for (int k = 0; k < 2; ++k) dst[m][k] = *(const PG8_LAS bf16x8*)(lds + PG8_SA(b, h) + aoff + m * 2048 + k * 1024); } while (0)
; #define PG8_LDB(dst, b, h) do { _Pragma("unroll") for (int n = 0; n < 2; ++n) _Pragma("unroll") for (int k = 0; k < 2; ++k) dst[n][k] = *(const PG8_LAS bf16x8*)(lds + PG8_SB(b, h) + boff + n * 2048 + k * 1024); } while (0)
; #define PG8_MMA(ai, bj, At, Bt) do { __builtin_amdgcn_s_setprio(1); _Pragma("unroll") for (int m = 0; m < 4; ++m) _Pragma("unroll") for (int n = 0; n < 2; ++n) _Pragma("unroll") for (int k = 0; k < 2; ++k) \
;         acc[ai][bj][m][n] = __builtin_amdgcn_mfma_f32_16x16x32_bf16(Bt[n][k], At[m][k], acc[ai][bj][m][n], 0, 0, 0); __builtin_amdgcn_s_setprio(0); } while (0)
; #define PG8_WAIT_V(n) asm volatile("s_waitcnt vmcnt(" #n ")" ::: "memory")
; #define PG8_WAIT_L(n) asm volatile("s_waitcnt lgkmcnt(" #n ")" ::: "memory")
; #define PG8_BAR __builtin_amdgcn_s_barrier()
; #define PG8_SCHED __builtin_amdgcn_sched_barrier(0)
; template <class Epi, class Sched, bool ALIGN_EPI = false, bool SP2 = false>
; __device__ __forceinline__ void gemm_phase(PG8_LAS unsigned char* lds, const Gemm g, const Sched& S, const Epi& E) {
;     ...
;             PG8_LDB(B0, 0, 0); PG8_LDB(B1, 0, 1); PG8_SCHED; PG8_LDA(At, 0, 0); PG8_STAGE(PG8_SA(1, 1), a1 + hstep, voffA);
;             PG8_WAIT_V(8); PG8_WAIT_L(0); PG8_BAR; PG8_MMA(0, 0, At, B0); PG8_MMA(0, 1, At, B1); PG8_BAR; PG8_SCHED;
;             PG8_LDA(At, 0, 1); PG8_STAGE(PG8_SB(0, 0), b2, voffB); PG8_STAGE(PG8_SB(0, 1), b2 + hstep, voffB); PG8_STAGE(PG8_SA(0, 0), a2, voffA);
;             PG8_WAIT_V(8); PG8_WAIT_L(0); PG8_BAR; PG8_MMA(1, 0, At, B0); PG8_MMA(1, 1, At, B1); PG8_BAR; PG8_SCHED;
.LBB0_929:
	ds_read_b128 v[150:153], v147
	ds_read_b128 v[154:157], v235
	ds_read_b128 v[158:161], v147 offset:2048
	ds_read_b128 v[162:165], v235 offset:2048
	ds_read_b128 v[166:169], v148
	ds_read_b128 v[170:173], v236
	ds_read_b128 v[174:177], v148 offset:2048
	ds_read_b128 v[178:181], v236 offset:2048
	s_add_u32 s3, s40, 0xfffc0080
	s_addc_u32 s45, s41, -1
	s_cmp_eq_u32 s76, 12
	s_cselect_b32 s53, s31, s45
	s_cselect_b32 s52, s72, s3
	s_cselect_b32 s51, s29, s75
	s_cselect_b32 s50, s73, s74
	v_lshl_add_u64 v[222:223], s[40:41], 0, v[136:137]
	s_add_i32 m0, s39, 0xc000
	ds_read_b128 v[190:193], v149
	ds_read_b128 v[194:197], v233
	ds_read_b128 v[198:201], v149 offset:2048
	ds_read_b128 v[202:205], v233 offset:2048
	ds_read_b128 v[206:209], v149 offset:4096
	ds_read_b128 v[210:213], v233 offset:4096
	ds_read_b128 v[214:217], v149 offset:6144
	ds_read_b128 v[218:221], v233 offset:6144
	global_load_lds_dwordx4 v[222:223], off
	v_lshl_add_u64 v[222:223], s[40:41], 0, v[138:139]
	s_add_i32 m0, s39, 0xe000
	s_nop 0
	global_load_lds_dwordx4 v[222:223], off
	s_waitcnt vmcnt(8)
	s_waitcnt lgkmcnt(0)
	s_barrier
	s_setprio 1
	s_waitcnt lgkmcnt(0)
	v_mfma_f32_16x16x32_bf16 v[124:127], v[150:153], v[190:193], v[124:127]
	v_mfma_f32_16x16x32_bf16 v[120:123], v[158:161], v[190:193], v[120:123]
	v_mfma_f32_16x16x32_bf16 v[116:119], v[150:153], v[198:201], v[116:119]
	v_mfma_f32_16x16x32_bf16 v[112:115], v[158:161], v[198:201], v[112:115]
	v_mfma_f32_16x16x32_bf16 v[108:111], v[150:153], v[206:209], v[108:111]
	v_mfma_f32_16x16x32_bf16 v[104:107], v[158:161], v[206:209], v[104:107]
	v_mfma_f32_16x16x32_bf16 v[100:103], v[150:153], v[214:217], v[100:103]
	v_mfma_f32_16x16x32_bf16 v[96:99], v[158:161], v[214:217], v[96:99]
	v_mfma_f32_16x16x32_bf16 v[124:127], v[154:157], v[194:197], v[124:127]
	v_mfma_f32_16x16x32_bf16 v[120:123], v[162:165], v[194:197], v[120:123]
	v_mfma_f32_16x16x32_bf16 v[116:119], v[154:157], v[202:205], v[116:119]
	v_mfma_f32_16x16x32_bf16 v[112:115], v[162:165], v[202:205], v[112:115]
	v_mfma_f32_16x16x32_bf16 v[108:111], v[154:157], v[210:213], v[108:111]
	v_mfma_f32_16x16x32_bf16 v[104:107], v[162:165], v[210:213], v[104:107]
	v_mfma_f32_16x16x32_bf16 v[100:103], v[154:157], v[218:221], v[100:103]
	v_mfma_f32_16x16x32_bf16 v[96:99], v[162:165], v[218:221], v[96:99]
	s_setprio 0
	s_setprio 1
	v_mfma_f32_16x16x32_bf16 v[76:79], v[166:169], v[190:193], v[76:79]
	v_mfma_f32_16x16x32_bf16 v[68:71], v[174:177], v[190:193], v[68:71]
	v_mfma_f32_16x16x32_bf16 v[60:63], v[166:169], v[198:201], v[60:63]
	v_mfma_f32_16x16x32_bf16 v[52:55], v[174:177], v[198:201], v[52:55]
	v_mfma_f32_16x16x32_bf16 v[44:47], v[166:169], v[206:209], v[44:47]
	v_mfma_f32_16x16x32_bf16 v[40:43], v[174:177], v[206:209], v[40:43]
	v_mfma_f32_16x16x32_bf16 v[36:39], v[166:169], v[214:217], v[36:39]
	v_mfma_f32_16x16x32_bf16 v[32:35], v[174:177], v[214:217], v[32:35]
	v_mfma_f32_16x16x32_bf16 v[76:79], v[170:173], v[194:197], v[76:79]
	v_mfma_f32_16x16x32_bf16 v[68:71], v[178:181], v[194:197], v[68:71]
	v_mfma_f32_16x16x32_bf16 v[60:63], v[170:173], v[202:205], v[60:63]
	v_mfma_f32_16x16x32_bf16 v[52:55], v[178:181], v[202:205], v[52:55]
	v_mfma_f32_16x16x32_bf16 v[44:47], v[170:173], v[210:213], v[44:47]
	v_mfma_f32_16x16x32_bf16 v[40:43], v[178:181], v[210:213], v[40:43]
	v_mfma_f32_16x16x32_bf16 v[36:39], v[170:173], v[218:221], v[36:39]
	v_mfma_f32_16x16x32_bf16 v[32:35], v[178:181], v[218:221], v[32:35]
	s_setprio 0
	s_barrier
	s_add_i32 s3, s65, s56
	v_lshl_add_u64 v[222:223], s[50:51], 0, v[130:131]
	s_mov_b32 m0, s3
	ds_read_b128 v[190:193], v149 offset:16384
	ds_read_b128 v[194:197], v233 offset:16384
	ds_read_b128 v[198:201], v149 offset:18432
	ds_read_b128 v[202:205], v233 offset:18432
	ds_read_b128 v[206:209], v149 offset:20480
	ds_read_b128 v[210:213], v233 offset:20480
	ds_read_b128 v[214:217], v149 offset:22528
	ds_read_b128 v[218:221], v233 offset:22528
	global_load_lds_dwordx4 v[222:223], off
	s_add_i32 m0, s3, 0x2000
	s_add_u32 s70, s50, 0x40000
	v_lshl_add_u64 v[224:225], s[50:51], 0, v[134:135]
	s_addc_u32 s71, s51, 0
	s_add_i32 s3, s66, s56
	global_load_lds_dwordx4 v[224:225], off
	v_lshl_add_u64 v[226:227], s[70:71], 0, v[130:131]
	s_mov_b32 m0, s3
	v_lshl_add_u64 v[228:229], s[52:53], 0, v[132:133]
	global_load_lds_dwordx4 v[226:227], off
	v_lshl_add_u64 v[226:227], s[70:71], 0, v[134:135]
	s_add_i32 m0, s3, 0x2000
	s_nop 0
	global_load_lds_dwordx4 v[226:227], off
	v_lshl_add_u64 v[226:227], s[52:53], 0, v[128:129]
	s_mov_b32 m0, s39
	s_nop 0
	global_load_lds_dwordx4 v[226:227], off
	s_mov_b32 m0, s57
	s_nop 0
	global_load_lds_dwordx4 v[228:229], off
	s_waitcnt vmcnt(8)
	s_waitcnt lgkmcnt(0)
	s_barrier
; #define PG8_STAGE(bufoff, gbase, voff) do { _Pragma("unroll") for (int _i = 0; _i < 2; ++_i) \
;         __builtin_amdgcn_global_load_lds((const unsigned*)((const char*)(gbase) + (voff)[_i]), (PG8_LAS unsigned*)(lds + (bufoff) + ldsw + _i * 8192), 16, 0, 0); } while (0)
; #define PG8_LDA(dst, b, h) do { _Pragma("unroll") for (int m = 0; m < 4; ++m) _Pragma("unroll") for (int k = 0; k < 2; ++k) dst[m][k] = *(const PG8_LAS bf16x8*)(lds + PG8_SA(b, h) + aoff + m * 2048 + k * 1024); } while (0)
; #define PG8_LDB(dst, b, h) do { _Pragma("unroll") for (int n = 0; n < 2; ++n) _Pragma("unroll") for (int k = 0; k < 2; ++k) dst[n][k] = *(const PG8_LAS bf16x8*)(lds + PG8_SB(b, h) + boff + n * 2048 + k * 1024); } while (0)
; #define PG8_MMA(ai, bj, At, Bt) do { __builtin_amdgcn_s_setprio(1); _Pragma("unroll") for (int m = 0; m < 4; ++m) _Pragma("unroll") for (int n = 0; n < 2; ++n) _Pragma("unroll") for (int k = 0; k < 2; ++k) \
;         acc[ai][bj][m][n] = __builtin_amdgcn_mfma_f32_16x16x32_bf16(Bt[n][k], At[m][k], acc[ai][bj][m][n], 0, 0, 0); __builtin_amdgcn_s_setprio(0); } while (0)
; #define PG8_WAIT_V(n) asm volatile("s_waitcnt vmcnt(" #n ")" ::: "memory")
; #define PG8_WAIT_L(n) asm volatile("s_waitcnt lgkmcnt(" #n ")" ::: "memory")
; #define PG8_BAR __builtin_amdgcn_s_barrier()
; #define PG8_SCHED __builtin_amdgcn_sched_barrier(0)
; template <class Epi, class Sched, bool ALIGN_EPI = false, bool SP2 = false>
; __device__ __forceinline__ void gemm_phase(PG8_LAS unsigned char* lds, const Gemm g, const Sched& S, const Epi& E) {
;     ...
;             PG8_WAIT_V(8); PG8_WAIT_L(0); PG8_BAR; PG8_MMA(1, 0, At, B0); PG8_MMA(1, 1, At, B1); PG8_BAR; PG8_SCHED;
;             PG8_LDB(B0, 1, 0); PG8_LDB(B1, 1, 1); PG8_SCHED; PG8_LDA(At, 1, 0); PG8_STAGE(PG8_SA(0, 1), a2 + hstep, voffA);
;             PG8_WAIT_V(8); PG8_WAIT_L(0); PG8_BAR; PG8_MMA(0, 0, At, B0); PG8_MMA(0, 1, At, B1); PG8_BAR; PG8_SCHED;
;             PG8_LDA(At, 1, 1); PG8_STAGE(PG8_SB(1, 0), b3, voffB); PG8_STAGE(PG8_SB(1, 1), b3 + hstep, voffB); PG8_STAGE(PG8_SA(1, 0), a3, voffA);
	s_setprio 1
	s_waitcnt lgkmcnt(0)
	v_mfma_f32_16x16x32_bf16 v[92:95], v[150:153], v[190:193], v[92:95]
	v_mfma_f32_16x16x32_bf16 v[88:91], v[158:161], v[190:193], v[88:91]
	v_mfma_f32_16x16x32_bf16 v[84:87], v[150:153], v[198:201], v[84:87]
	v_mfma_f32_16x16x32_bf16 v[80:83], v[158:161], v[198:201], v[80:83]
	v_mfma_f32_16x16x32_bf16 v[72:75], v[150:153], v[206:209], v[72:75]
	v_mfma_f32_16x16x32_bf16 v[64:67], v[158:161], v[206:209], v[64:67]
	v_mfma_f32_16x16x32_bf16 v[56:59], v[150:153], v[214:217], v[56:59]
	v_mfma_f32_16x16x32_bf16 v[48:51], v[158:161], v[214:217], v[48:51]
	v_mfma_f32_16x16x32_bf16 v[92:95], v[154:157], v[194:197], v[92:95]
	v_mfma_f32_16x16x32_bf16 v[88:91], v[162:165], v[194:197], v[88:91]
	v_mfma_f32_16x16x32_bf16 v[84:87], v[154:157], v[202:205], v[84:87]
	v_mfma_f32_16x16x32_bf16 v[80:83], v[162:165], v[202:205], v[80:83]
	v_mfma_f32_16x16x32_bf16 v[72:75], v[154:157], v[210:213], v[72:75]
	v_mfma_f32_16x16x32_bf16 v[64:67], v[162:165], v[210:213], v[64:67]
	v_mfma_f32_16x16x32_bf16 v[56:59], v[154:157], v[218:221], v[56:59]
	v_mfma_f32_16x16x32_bf16 v[48:51], v[162:165], v[218:221], v[48:51]
	s_setprio 0
	s_setprio 1
	v_mfma_f32_16x16x32_bf16 v[28:31], v[166:169], v[190:193], v[28:31]
	v_mfma_f32_16x16x32_bf16 v[24:27], v[174:177], v[190:193], v[24:27]
	v_mfma_f32_16x16x32_bf16 v[20:23], v[166:169], v[198:201], v[20:23]
	v_mfma_f32_16x16x32_bf16 v[16:19], v[174:177], v[198:201], v[16:19]
	v_mfma_f32_16x16x32_bf16 v[12:15], v[166:169], v[206:209], v[12:15]
	v_mfma_f32_16x16x32_bf16 v[8:11], v[174:177], v[206:209], v[8:11]
	v_mfma_f32_16x16x32_bf16 v[4:7], v[166:169], v[214:217], v[4:7]
	v_mfma_f32_16x16x32_bf16 v[0:3], v[174:177], v[214:217], v[0:3]
	v_mfma_f32_16x16x32_bf16 v[28:31], v[170:173], v[194:197], v[28:31]
	v_mfma_f32_16x16x32_bf16 v[24:27], v[178:181], v[194:197], v[24:27]
	v_mfma_f32_16x16x32_bf16 v[20:23], v[170:173], v[202:205], v[20:23]
	v_mfma_f32_16x16x32_bf16 v[16:19], v[178:181], v[202:205], v[16:19]
	v_mfma_f32_16x16x32_bf16 v[12:15], v[170:173], v[210:213], v[12:15]
	v_mfma_f32_16x16x32_bf16 v[8:11], v[178:181], v[210:213], v[8:11]
	v_mfma_f32_16x16x32_bf16 v[4:7], v[170:173], v[218:221], v[4:7]
	v_mfma_f32_16x16x32_bf16 v[0:3], v[178:181], v[218:221], v[0:3]
	s_setprio 0
	s_barrier
	s_add_i32 s3, 0, 0x18000
	s_add_i32 s45, 0, 0x1c000
	v_add_u32_e32 v162, s3, v145
	v_add_u32_e32 v237, s3, v234
	v_add_u32_e32 v178, s45, v145
	v_add_u32_e32 v238, s45, v234
	ds_read_b128 v[150:153], v162
	ds_read_b128 v[154:157], v237
	ds_read_b128 v[158:161], v162 offset:2048
	ds_read_b128 v[162:165], v237 offset:2048
	ds_read_b128 v[166:169], v178
	ds_read_b128 v[170:173], v238
	ds_read_b128 v[174:177], v178 offset:2048
	ds_read_b128 v[178:181], v238 offset:2048
	s_add_u32 s52, s52, 0x40000
	s_addc_u32 s53, s53, 0
	s_mov_b32 m0, s58
	v_lshl_add_u64 v[230:231], s[52:53], 0, v[128:129]
	ds_read_b128 v[190:193], v149 offset:32768
	ds_read_b128 v[194:197], v233 offset:32768
	ds_read_b128 v[198:201], v149 offset:34816
	ds_read_b128 v[202:205], v233 offset:34816
	ds_read_b128 v[206:209], v149 offset:36864
	ds_read_b128 v[210:213], v233 offset:36864
	ds_read_b128 v[214:217], v149 offset:38912
	ds_read_b128 v[218:221], v233 offset:38912
	global_load_lds_dwordx4 v[230:231], off
	v_lshl_add_u64 v[230:231], s[52:53], 0, v[132:133]
	s_mov_b32 m0, s59
	s_nop 0
	global_load_lds_dwordx4 v[230:231], off
	s_waitcnt vmcnt(8)
	s_waitcnt lgkmcnt(0)
	s_barrier
	s_setprio 1
	s_waitcnt lgkmcnt(0)
	v_mfma_f32_16x16x32_bf16 v[124:127], v[150:153], v[190:193], v[124:127]
	v_mfma_f32_16x16x32_bf16 v[120:123], v[158:161], v[190:193], v[120:123]
	v_mfma_f32_16x16x32_bf16 v[116:119], v[150:153], v[198:201], v[116:119]
	v_mfma_f32_16x16x32_bf16 v[112:115], v[158:161], v[198:201], v[112:115]
	v_mfma_f32_16x16x32_bf16 v[108:111], v[150:153], v[206:209], v[108:111]
	v_mfma_f32_16x16x32_bf16 v[104:107], v[158:161], v[206:209], v[104:107]
	v_mfma_f32_16x16x32_bf16 v[100:103], v[150:153], v[214:217], v[100:103]
	v_mfma_f32_16x16x32_bf16 v[96:99], v[158:161], v[214:217], v[96:99]
	v_mfma_f32_16x16x32_bf16 v[124:127], v[154:157], v[194:197], v[124:127]
	v_mfma_f32_16x16x32_bf16 v[120:123], v[162:165], v[194:197], v[120:123]
	v_mfma_f32_16x16x32_bf16 v[116:119], v[154:157], v[202:205], v[116:119]
	v_mfma_f32_16x16x32_bf16 v[112:115], v[162:165], v[202:205], v[112:115]
	v_mfma_f32_16x16x32_bf16 v[108:111], v[154:157], v[210:213], v[108:111]
	v_mfma_f32_16x16x32_bf16 v[104:107], v[162:165], v[210:213], v[104:107]
	v_mfma_f32_16x16x32_bf16 v[100:103], v[154:157], v[218:221], v[100:103]
	v_mfma_f32_16x16x32_bf16 v[96:99], v[162:165], v[218:221], v[96:99]
	s_setprio 0
	s_setprio 1
	v_mfma_f32_16x16x32_bf16 v[76:79], v[166:169], v[190:193], v[76:79]
	v_mfma_f32_16x16x32_bf16 v[68:71], v[174:177], v[190:193], v[68:71]
	v_mfma_f32_16x16x32_bf16 v[60:63], v[166:169], v[198:201], v[60:63]
	v_mfma_f32_16x16x32_bf16 v[52:55], v[174:177], v[198:201], v[52:55]
	v_mfma_f32_16x16x32_bf16 v[44:47], v[166:169], v[206:209], v[44:47]
	v_mfma_f32_16x16x32_bf16 v[40:43], v[174:177], v[206:209], v[40:43]
	v_mfma_f32_16x16x32_bf16 v[36:39], v[166:169], v[214:217], v[36:39]
	v_mfma_f32_16x16x32_bf16 v[32:35], v[174:177], v[214:217], v[32:35]
	v_mfma_f32_16x16x32_bf16 v[76:79], v[170:173], v[194:197], v[76:79]
	v_mfma_f32_16x16x32_bf16 v[68:71], v[178:181], v[194:197], v[68:71]
	v_mfma_f32_16x16x32_bf16 v[60:63], v[170:173], v[202:205], v[60:63]
	v_mfma_f32_16x16x32_bf16 v[52:55], v[178:181], v[202:205], v[52:55]
	v_mfma_f32_16x16x32_bf16 v[44:47], v[170:173], v[210:213], v[44:47]
	v_mfma_f32_16x16x32_bf16 v[40:43], v[178:181], v[210:213], v[40:43]
	v_mfma_f32_16x16x32_bf16 v[36:39], v[170:173], v[218:221], v[36:39]
	v_mfma_f32_16x16x32_bf16 v[32:35], v[178:181], v[218:221], v[32:35]
	s_setprio 0
	s_barrier
; #define PG8_STAGE(bufoff, gbase, voff) do { _Pragma("unroll") for (int _i = 0; _i < 2; ++_i) \
;         __builtin_amdgcn_global_load_lds((const unsigned*)((const char*)(gbase) + (voff)[_i]), (PG8_LAS unsigned*)(lds + (bufoff) + ldsw + _i * 8192), 16, 0, 0); } while (0)
; #define PG8_LDA(dst, b, h) do { _Pragma("unroll") for (int m = 0; m < 4; ++m) _Pragma("unroll") for (int k = 0; k < 2; ++k) dst[m][k] = *(const PG8_LAS bf16x8*)(lds + PG8_SA(b, h) + aoff + m * 2048 + k * 1024); } while (0)
; #define PG8_MMA(ai, bj, At, Bt) do { __builtin_amdgcn_s_setprio(1); _Pragma("unroll") for (int m = 0; m < 4; ++m) _Pragma("unroll") for (int n = 0; n < 2; ++n) _Pragma("unroll") for (int k = 0; k < 2; ++k) \
;         acc[ai][bj][m][n] = __builtin_amdgcn_mfma_f32_16x16x32_bf16(Bt[n][k], At[m][k], acc[ai][bj][m][n], 0, 0, 0); __builtin_amdgcn_s_setprio(0); } while (0)
; #define PG8_WAIT_V(n) asm volatile("s_waitcnt vmcnt(" #n ")" ::: "memory")
; #define PG8_WAIT_L(n) asm volatile("s_waitcnt lgkmcnt(" #n ")" ::: "memory")
; #define PG8_BAR __builtin_amdgcn_s_barrier()
; #define PG8_SCHED __builtin_amdgcn_sched_barrier(0)
; template <class Epi, class Sched, bool ALIGN_EPI = false, bool SP2 = false>
; __device__ __forceinline__ void gemm_phase(PG8_LAS unsigned char* lds, const Gemm g, const Sched& S, const Epi& E) {
;     ...
;         for (int t = 0; t < nt; t += 2) {
;     ...
;             PG8_LDA(At, 1, 1); PG8_STAGE(PG8_SB(1, 0), b3, voffB); PG8_STAGE(PG8_SB(1, 1), b3 + hstep, voffB); PG8_STAGE(PG8_SA(1, 0), a3, voffA);
;             PG8_WAIT_V(8); PG8_WAIT_L(0); PG8_BAR; PG8_MMA(1, 0, At, B0); PG8_MMA(1, 1, At, B1); PG8_BAR; PG8_SCHED;
	s_add_i32 s3, s3, s56
	v_lshl_add_u64 v[222:223], v[222:223], 0, s[18:19]
	s_mov_b32 m0, s3
	ds_read_b128 v[190:193], v149 offset:49152
	ds_read_b128 v[194:197], v233 offset:49152
	ds_read_b128 v[198:201], v149 offset:51200
	ds_read_b128 v[202:205], v233 offset:51200
	ds_read_b128 v[206:209], v149 offset:53248
	ds_read_b128 v[210:213], v233 offset:53248
	ds_read_b128 v[214:217], v149 offset:55296
	ds_read_b128 v[218:221], v233 offset:55296
	global_load_lds_dwordx4 v[222:223], off
	s_add_i32 m0, s3, 0x2000
	s_add_u32 s50, s50, 0x40080
	v_lshl_add_u64 v[222:223], v[224:225], 0, s[18:19]
	s_addc_u32 s51, s51, 0
	s_add_i32 s3, s45, s56
	global_load_lds_dwordx4 v[222:223], off
	v_lshl_add_u64 v[222:223], s[50:51], 0, v[130:131]
	s_mov_b32 m0, s3
	s_nop 0
	global_load_lds_dwordx4 v[222:223], off
	v_lshl_add_u64 v[222:223], s[50:51], 0, v[134:135]
	s_add_i32 m0, s3, 0x2000
	s_nop 0
	global_load_lds_dwordx4 v[222:223], off
	v_lshl_add_u64 v[222:223], v[226:227], 0, s[18:19]
	s_mov_b32 m0, s61
	s_nop 0
	global_load_lds_dwordx4 v[222:223], off
	v_lshl_add_u64 v[222:223], v[228:229], 0, s[18:19]
	s_mov_b32 m0, s62
	s_nop 0
	global_load_lds_dwordx4 v[222:223], off
	s_waitcnt vmcnt(8)
	s_waitcnt lgkmcnt(0)
	s_barrier
	s_setprio 1
	s_waitcnt lgkmcnt(0)
	v_mfma_f32_16x16x32_bf16 v[92:95], v[150:153], v[190:193], v[92:95]
	v_mfma_f32_16x16x32_bf16 v[88:91], v[158:161], v[190:193], v[88:91]
	v_mfma_f32_16x16x32_bf16 v[84:87], v[150:153], v[198:201], v[84:87]
	v_mfma_f32_16x16x32_bf16 v[80:83], v[158:161], v[198:201], v[80:83]
	v_mfma_f32_16x16x32_bf16 v[72:75], v[150:153], v[206:209], v[72:75]
	v_mfma_f32_16x16x32_bf16 v[64:67], v[158:161], v[206:209], v[64:67]
	v_mfma_f32_16x16x32_bf16 v[56:59], v[150:153], v[214:217], v[56:59]
	v_mfma_f32_16x16x32_bf16 v[48:51], v[158:161], v[214:217], v[48:51]
	v_mfma_f32_16x16x32_bf16 v[92:95], v[154:157], v[194:197], v[92:95]
	v_mfma_f32_16x16x32_bf16 v[88:91], v[162:165], v[194:197], v[88:91]
	v_mfma_f32_16x16x32_bf16 v[84:87], v[154:157], v[202:205], v[84:87]
	v_mfma_f32_16x16x32_bf16 v[80:83], v[162:165], v[202:205], v[80:83]
	v_mfma_f32_16x16x32_bf16 v[72:75], v[154:157], v[210:213], v[72:75]
	v_mfma_f32_16x16x32_bf16 v[64:67], v[162:165], v[210:213], v[64:67]
	v_mfma_f32_16x16x32_bf16 v[56:59], v[154:157], v[218:221], v[56:59]
	v_mfma_f32_16x16x32_bf16 v[48:51], v[162:165], v[218:221], v[48:51]
	s_setprio 0
	s_setprio 1
	v_mfma_f32_16x16x32_bf16 v[28:31], v[166:169], v[190:193], v[28:31]
	v_mfma_f32_16x16x32_bf16 v[24:27], v[174:177], v[190:193], v[24:27]
	v_mfma_f32_16x16x32_bf16 v[20:23], v[166:169], v[198:201], v[20:23]
	v_mfma_f32_16x16x32_bf16 v[16:19], v[174:177], v[198:201], v[16:19]
	v_mfma_f32_16x16x32_bf16 v[12:15], v[166:169], v[206:209], v[12:15]
	v_mfma_f32_16x16x32_bf16 v[8:11], v[174:177], v[206:209], v[8:11]
	v_mfma_f32_16x16x32_bf16 v[4:7], v[166:169], v[214:217], v[4:7]
	v_mfma_f32_16x16x32_bf16 v[0:3], v[174:177], v[214:217], v[0:3]
	v_mfma_f32_16x16x32_bf16 v[28:31], v[170:173], v[194:197], v[28:31]
	v_mfma_f32_16x16x32_bf16 v[24:27], v[178:181], v[194:197], v[24:27]
	v_mfma_f32_16x16x32_bf16 v[20:23], v[170:173], v[202:205], v[20:23]
	v_mfma_f32_16x16x32_bf16 v[16:19], v[178:181], v[202:205], v[16:19]
	v_mfma_f32_16x16x32_bf16 v[12:15], v[170:173], v[210:213], v[12:15]
	v_mfma_f32_16x16x32_bf16 v[8:11], v[178:181], v[210:213], v[8:11]
	v_mfma_f32_16x16x32_bf16 v[4:7], v[170:173], v[218:221], v[4:7]
	v_mfma_f32_16x16x32_bf16 v[0:3], v[178:181], v[218:221], v[0:3]
	s_setprio 0
	s_barrier
	s_add_i32 s76, s76, 2
	s_add_u32 s40, s40, 0x100
	s_addc_u32 s41, s41, 0
	s_add_u32 s74, s74, 0x100
	s_addc_u32 s75, s75, 0
	s_cmp_gt_u32 s76, 13
	s_cbranch_scc0 .LBB0_929
	s_and_b64 vcc, exec, s[20:21]
	s_cbranch_vccz .LBB0_932
	s_barrier

; __device__ __forceinline__ int fresh_tid() { int t = (int)threadIdx.x; asm volatile("" : "+v"(t)); return t; }
; #define PG8_STAGE(bufoff, gbase, voff) do { _Pragma("unroll") for (int _i = 0; _i < 2; ++_i) \
;         __builtin_amdgcn_global_load_lds((const unsigned*)((const char*)(gbase) + (voff)[_i]), (PG8_LAS unsigned*)(lds + (bufoff) + ldsw + _i * 8192), 16, 0, 0); } while (0)
; #define PG8_WAIT_V(n) asm volatile("s_waitcnt vmcnt(" #n ")" ::: "memory")
; #define PG8_BAR __builtin_amdgcn_s_barrier()
; template <class Epi, class Sched, bool ALIGN_EPI = false, bool SP2 = false>
; __device__ __forceinline__ void gemm_phase(PG8_LAS unsigned char* lds, const Gemm g, const Sched& S, const Epi& E) {
;     const int tid = fresh_tid(), wid = __builtin_amdgcn_readfirstlane(tid >> 6), lane = tid & 63, wr = wid >> 2, wc = wid & 3, fr = lane & 15, fq = lane >> 4;
;     const int K = g.K, nt = K / BK;
;     unsigned voffA[2], voffB[2];
; #pragma unroll
;     for (int i = 0; i < 2; ++i) { int R, C; stage_rc(tid * 16 + i * 8192, R, C); const int Rb = Epi::PERM ? ((R & ~31) + perm32(R & 31)) : R;
;         voffA[i] = (unsigned)(R * K + C) * 2u; voffB[i] = (unsigned)(Rb * K + C) * 2u; }
;     const size_t kstep = (size_t)(BK * 2);
;     const size_t hstep = (size_t)HALF * K * 2;
;     const size_t tstep = 2 * hstep;
;     const unsigned ldsw = (unsigned)wid * 1024u;
;     const int aoff = lds_byte(wr * 64 + fr, fq * 8), boff = lds_byte(wc * 32 + fr, fq * 8);
;     ...
;     if constexpr (SP2) {
;         PG8_STAGE(PG8_SB(0, 0), cB, voffB); PG8_STAGE(PG8_SB(0, 1), cB + hstep, voffB); PG8_STAGE(PG8_SA(0, 0), cA, voffA); PG8_STAGE(PG8_SA(0, 1), cA + hstep, voffA);
;         if (wr == 1) PG8_BAR;
;         PG8_WAIT_V(2); PG8_BAR;
;         PG8_STAGE(PG8_SB(1, 0), cB + kstep, voffB); PG8_STAGE(PG8_SA(1, 0), cA + kstep, voffA); PG8_STAGE(PG8_SB(1, 1), cB + hstep + kstep, voffB);
;         PG8_WAIT_V(6); PG8_BAR;
.LBB0_1109:
	s_mov_b64 s[12:13], s[80:81]
	s_mov_b64 s[14:15], s[80:81]
	s_mov_b64 s[10:11], s[80:81]
	v_mov_b32_e32 v8, v182
	s_barrier
	s_andn2_b64 vcc, exec, s[48:49]
	v_readfirstlane_b32 s19, v8
	s_cbranch_vccnz .LBB0_1125
	v_lshlrev_b32_e32 v0, 4, v8
	v_add_u32_e32 v1, 0x2000, v0
	v_ashrrev_i32_e32 v2, 31, v1
	v_lshrrev_b32_e32 v2, 22, v2
	v_add_u32_e32 v2, v1, v2
	v_ashrrev_i32_e32 v9, 10, v2
	v_mul_i32_i24_e32 v2, 0x400, v9
	v_sub_u32_e32 v1, v1, v2
	v_lshrrev_b32_e32 v2, 4, v1
	v_bitop3_b32 v1, v2, v1, 32 bitop3:0x6c
	v_ashrrev_i32_e32 v2, 31, v1
	s_load_dwordx2 s[0:1], s[12:13], 0x110
	s_load_dwordx2 s[16:17], s[14:15], 0x110
	v_lshrrev_b32_e32 v2, 26, v2
	v_add_u32_e32 v2, v1, v2
	v_lshlrev_b32_e32 v3, 3, v9
	v_ashrrev_i32_e32 v10, 6, v2
	v_and_b32_e32 v3, -16, v3
	v_add_u32_e32 v3, v10, v3
	s_waitcnt lgkmcnt(0)
	s_add_u32 s38, s0, 0x3000000
	v_and_b32_e32 v4, 3, v10
	s_mov_b32 s0, 0x1fffe0
	v_lshrrev_b32_e32 v5, 2, v3
	v_lshlrev_b32_e32 v6, 1, v3
	v_and_b32_e32 v2, 0xc0, v2
	v_and_or_b32 v4, v3, s0, v4
	v_and_b32_e32 v5, 4, v5
	v_and_b32_e32 v6, 24, v6
	v_sub_u32_e32 v1, v1, v2
	v_mov_b32_e32 v2, 1
	v_or3_b32 v4, v4, v5, v6
	v_lshlrev_b32_e32 v5, 5, v9
	v_ashrrev_i16_sdwa v1, v2, sext(v1) dst_sel:DWORD dst_unused:UNUSED_PAD src0_sel:DWORD src1_sel:BYTE_0
	v_and_b32_e32 v5, 32, v5
	v_bfe_i32 v11, v1, 0, 16
	v_add_lshl_u32 v1, v5, v11, 1
	v_lshl_add_u32 v128, v4, 11, v1
	v_lshl_add_u32 v130, v3, 11, v1
	v_bfe_i32 v1, v8, 27, 1
	v_lshrrev_b32_e32 v1, 22, v1
	v_add_u32_e32 v1, v0, v1
	v_and_b32_e32 v1, 0xfffffc00, v1
	v_sub_u32_e32 v0, v0, v1
	v_lshrrev_b32_e32 v1, 4, v0
	v_bitop3_b32 v1, v1, v0, 32 bitop3:0x6c
	v_ashrrev_i32_e32 v0, 31, v0
	v_lshrrev_b32_e32 v0, 26, v0
	v_add_u32_e32 v0, v1, v0
	v_ashrrev_i32_e32 v12, 6, v0
	v_ashrrev_i32_e32 v0, 31, v8
	v_lshrrev_b32_e32 v0, 26, v0
	v_add_u32_e32 v0, v8, v0
	v_ashrrev_i32_e32 v13, 6, v0
	s_addc_u32 s39, s1, 0
	v_lshlrev_b32_e32 v0, 3, v13
	s_add_u32 s40, s16, 0x1800000
	v_and_b32_e32 v0, -16, v0
	s_addc_u32 s41, s17, 0
	v_add_u32_e32 v0, v12, v0
	v_and_b32_e32 v3, 3, v12
	s_ashr_i32 s43, s33, 31
	v_and_or_b32 v3, v0, s0, v3
	s_lshr_b32 s0, s43, 29
	s_add_i32 s0, s33, s0
	s_ashr_i32 s16, s19, 6
	s_ashr_i32 s1, s0, 3
	s_and_b32 s0, s0, -8
	s_ashr_i32 s20, s19, 8
	s_lshl_b32 s42, s16, 10
	s_sub_i32 s0, s33, s0
	s_cmp_lt_i32 s0, 0
	s_movk_i32 s47, 0x161
	s_cselect_b32 s3, s47, 0x160
	s_mul_i32 s0, s0, s3
	s_add_i32 s0, s0, s1
	s_mul_hi_i32 s1, s0, 0x2e8ba2e9
	s_lshr_b32 s3, s1, 31
	s_ashr_i32 s1, s1, 5
	s_add_i32 s1, s1, s3
	s_lshl_b32 s3, s1, 3
	s_mulk_i32 s1, 0xb0
	s_sub_i32 s0, s0, s1
	s_sext_i32_i16 s1, s0
	s_bfe_u32 s1, s1, 0x3001c
	s_add_i32 s1, s0, s1
	s_sext_i32_i16 s12, s1
	s_and_b32 s1, s1, 0xfff8
	v_lshrrev_b32_e32 v4, 2, v0
	v_lshlrev_b32_e32 v5, 1, v0
	s_sub_i32 s0, s0, s1
	v_and_b32_e32 v4, 4, v4
	v_and_b32_e32 v5, 24, v5
	s_sext_i32_i16 s0, s0
	v_or3_b32 v3, v3, v4, v5
	v_mul_i32_i24_e32 v5, 64, v12
	s_lshr_b32 s18, s12, 3
	s_add_i32 s28, s3, s0
	v_sub_u32_e32 v1, v1, v5
	s_ashr_i32 s29, s28, 31
	s_bfe_i64 s[12:13], s[18:19], 0x100000
	v_lshlrev_b32_e32 v4, 5, v13
	v_ashrrev_i16_sdwa v1, v2, sext(v1) dst_sel:DWORD dst_unused:UNUSED_PAD src0_sel:DWORD src1_sel:BYTE_0
	s_lshl_b64 s[0:1], s[28:29], 19
	s_lshl_b64 s[12:13], s[12:13], 19
	v_and_b32_e32 v4, 32, v4
	v_bfe_i32 v14, v1, 0, 16
	s_add_u32 s34, s40, s12
	v_add_lshl_u32 v1, v4, v14, 1
	s_addc_u32 s35, s41, s13
	s_add_i32 s29, s42, 0
	v_lshl_add_u32 v132, v3, 11, v1
	s_add_i32 m0, s29, 0x10000
	v_lshl_add_u32 v134, v0, 11, v1
	v_bfe_u32 v239, v8, 3, 3
	v_and_b32_e32 v240, 7, v8
	v_xor_b32_e32 v240, v240, v239
	v_lshlrev_b32_e32 v240, 4, v240
	v_lshrrev_b32_e32 v241, 6, v8
	v_lshl_add_u32 v242, v241, 3, v239
	v_mov_b32_e32 v243, 0x800
	v_mad_u32_u24 v134, v242, v243, v240
	v_add_u32_e32 v130, 0x20000, v134
	v_lshrrev_b32_e32 v244, 2, v241
	v_lshlrev_b32_e32 v244, 5, v244
	v_and_b32_e32 v245, 1, v241
	v_lshrrev_b32_e32 v246, 2, v239
	v_lshl_add_u32 v245, v245, 1, v246
	v_lshl_add_u32 v244, v245, 3, v244
	v_bfe_u32 v245, v241, 1, 1
	v_lshl_add_u32 v244, v245, 2, v244
	v_and_b32_e32 v245, 3, v239
	v_add_u32_e32 v244, v244, v245
	v_mad_u32_u24 v132, v244, v243, v240
	v_add_u32_e32 v128, 0x20000, v132
	global_load_lds_dwordx4 v132, s[34:35]
	s_add_i32 m0, s29, 0x12000
	s_add_u32 s12, s34, 0x40000
	global_load_lds_dwordx4 v128, s[34:35]
	s_addc_u32 s13, s35, 0
	s_add_i32 m0, s29, 0x14000
	s_load_dwordx2 s[10:11], s[10:11], 0x110
	global_load_lds_dwordx4 v132, s[12:13]
	s_add_i32 m0, s29, 0x16000
	s_add_u32 s30, s38, s0
	s_addc_u32 s31, s39, s1
	s_add_i32 s48, s29, 0x2000
	global_load_lds_dwordx4 v128, s[12:13]
	s_mov_b32 m0, s29
	s_add_u32 s0, s30, 0x40000
	global_load_lds_dwordx4 v134, s[30:31]
	s_mov_b32 m0, s48
	s_addc_u32 s1, s31, 0
	s_add_i32 s49, s29, 0x4000
	global_load_lds_dwordx4 v130, s[30:31]
	s_mov_b32 m0, s49
	s_add_i32 s50, s29, 0x6000
	global_load_lds_dwordx4 v134, s[0:1]
	s_mov_b32 m0, s50
	v_mov_b32_e32 v133, 0
	global_load_lds_dwordx4 v130, s[0:1]
	v_mov_b32_e32 v129, v133
	v_mov_b32_e32 v135, v133
	v_mov_b32_e32 v131, v133
	s_cmp_eq_u32 s20, 1
	s_mov_b32 s51, 0
	v_lshl_add_u64 v[6:7], s[34:35], 0, v[132:133]
	v_lshl_add_u64 v[4:5], s[34:35], 0, v[128:129]
	v_lshl_add_u64 v[0:1], s[30:31], 0, v[134:135]
	s_cselect_b64 s[12:13], -1, 0
	s_cmp_lg_u32 s20, 1
	v_lshl_add_u64 v[2:3], s[30:31], 0, v[130:131]
	s_cbranch_scc1 .LBB0_1112
	s_barrier
; #define PG8_STAGE(bufoff, gbase, voff) do { _Pragma("unroll") for (int _i = 0; _i < 2; ++_i) \
;         __builtin_amdgcn_global_load_lds((const unsigned*)((const char*)(gbase) + (voff)[_i]), (PG8_LAS unsigned*)(lds + (bufoff) + ldsw + _i * 8192), 16, 0, 0); } while (0)
; #define PG8_WAIT_V(n) asm volatile("s_waitcnt vmcnt(" #n ")" ::: "memory")
; #define PG8_BAR __builtin_amdgcn_s_barrier()
; template <class Epi, class Sched, bool ALIGN_EPI = false, bool SP2 = false>
; __device__ __forceinline__ void gemm_phase(PG8_LAS unsigned char* lds, const Gemm g, const Sched& S, const Epi& E) {
;     ...
;     const int aoff = lds_byte(wr * 64 + fr, fq * 8), boff = lds_byte(wc * 32 + fr, fq * 8);
;     ...
;         PG8_STAGE(PG8_SB(1, 0), cB + kstep, voffB); PG8_STAGE(PG8_SA(1, 0), cA + kstep, voffA); PG8_STAGE(PG8_SB(1, 1), cB + hstep + kstep, voffB);
;         PG8_WAIT_V(6); PG8_BAR;
;     ...
;     for (;;) {
;         const bool has_next = S.next(ui + 1, nxt);
;         const char* nA = has_next ? (const char*)g.A + (size_t)nxt.pm * tstep : cA; const char* nB = has_next ? (const char*)g.Bt + (size_t)nxt.pn * tstep : cB;
;         for (int t = 0; t < nt; t += 2) {
;             const bool last = (t == nt - 2);
;             const char* a1 = cA + (size_t)(t + 1) * kstep;
;             const char* a2 = last ? nA : cA + (size_t)(t + 2) * kstep; const char* b2 = last ? nB : cB + (size_t)(t + 2) * kstep;
.LBB0_1112:
	s_waitcnt lgkmcnt(0)
	s_add_u32 s14, s10, 0xb200000
	s_addc_u32 s15, s11, 0
	s_lshl_b32 s0, s16, 5
	s_mov_b64 s[16:17], 0x80
	s_and_b32 s10, s0, 0x60
	s_add_i32 m0, s29, 0x18000
	v_lshl_add_u64 v[6:7], v[6:7], 0, s[16:17]
	s_lshl_b32 s3, s20, 13
	s_lshl_b32 s11, s10, 7
	s_waitcnt vmcnt(2)
	s_barrier
	global_load_lds_dwordx4 v[6:7], off
	v_lshl_add_u64 v[4:5], v[4:5], 0, s[16:17]
	s_add_i32 m0, s29, 0x1a000
	s_add_i32 s52, s29, 0x8000
	s_add_i32 s53, s29, 0xa000
	global_load_lds_dwordx4 v[4:5], off
	v_lshl_add_u64 v[0:1], v[0:1], 0, s[16:17]
	s_mov_b32 m0, s52
	s_add_u32 s0, s34, 0x40080
	global_load_lds_dwordx4 v[0:1], off
	v_lshl_add_u64 v[0:1], v[2:3], 0, s[16:17]
	s_mov_b32 m0, s53
	s_addc_u32 s1, s35, 0
	global_load_lds_dwordx4 v[0:1], off
	s_add_i32 m0, s29, 0x1c000
	v_lshl_add_u64 v[0:1], s[0:1], 0, v[132:133]
	global_load_lds_dwordx4 v[0:1], off
	v_lshl_add_u64 v[0:1], s[0:1], 0, v[128:129]
	s_add_i32 m0, s29, 0x1e000
	s_cmpk_lt_u32 s19, 0x100
	global_load_lds_dwordx4 v[0:1], off
	v_lshrrev_b32_e32 v1, 1, v8
	v_and_b32_e32 v1, 24, v1
	v_and_b32_e32 v0, 15, v8
	v_lshlrev_b32_e32 v2, 1, v1
	v_lshl_or_b32 v148, s20, 6, v0
	v_lshl_or_b32 v0, v0, 6, v2
	v_lshlrev_b32_e32 v2, 2, v8
	v_and_b32_e32 v2, 32, v2
	v_bitop3_b32 v3, v0, s3, v2 bitop3:0xde
	v_bitop3_b32 v149, v0, s11, v2 bitop3:0xde
	v_and_b32_e32 v239, 15, v8
	v_and_b32_e32 v240, 7, v239
	v_lshrrev_b32_e32 v239, 3, v239
	v_lshlrev_b32_e32 v239, 10, v239
	v_lshl_add_u32 v239, v240, 7, v239
	v_bfe_u32 v241, v8, 4, 2
	v_xor_b32_e32 v242, v241, v240
	v_or_b32_e32 v241, 4, v241
	v_xor_b32_e32 v243, v241, v240
	v_lshl_add_u32 v242, v242, 4, v239
	v_lshl_add_u32 v243, v243, 4, v239
	v_lshrrev_b32_e32 v244, 8, v8
	v_lshlrev_b32_e32 v244, 13, v244
	v_add_u32_e32 v3, v244, v242
	v_add_u32_e32 v233, v244, v243
	v_bfe_u32 v244, v8, 6, 2
	v_lshlrev_b32_e32 v244, 12, v244
	v_add_u32_e32 v149, v244, v242
	v_add_u32_e32 v234, v244, v243
	v_lshlrev_b32_e32 v0, 14, v13
	v_and_b32_e32 v0, 0xffff8000, v0
	v_or_b32_e32 v150, s10, v1
	v_lshl_add_u32 v0, v12, 11, v0
	v_and_b32_e32 v1, 1, v13
	v_lshl_or_b32 v0, v1, 6, v0
	v_lshl_add_u32 v136, v14, 1, v0
	v_mov_b32_e32 v136, v134
	v_lshlrev_b32_e32 v0, 14, v9
	v_and_b32_e32 v0, 0xffff8000, v0
	s_waitcnt vmcnt(6)
	v_lshl_add_u32 v0, v10, 11, v0
	v_and_b32_e32 v1, 1, v9
	s_sext_i32_i16 s59, s18
	s_cselect_b64 s[18:19], -1, 0
	v_lshl_or_b32 v0, v1, 6, v0
	s_add_i32 s56, 0, 0x10000
	s_add_i32 s57, 0, 0x14000
	s_ashr_i32 s54, s94, 31
	s_mov_b32 s55, s94
	v_mov_b32_e32 v137, v133
	v_lshl_add_u32 v138, v11, 1, v0
	v_mov_b32_e32 v138, v130
	v_mov_b32_e32 v139, v133
	v_mov_b64_e32 v[140:141], 0xb00
	v_mov_b64_e32 v[142:143], 0xaff
	v_add_u32_e32 v151, s56, v149
	v_add_u32_e32 v235, s56, v234
	v_add_u32_e32 v152, s57, v149
	v_add_u32_e32 v236, s57, v234
	v_add_u32_e32 v153, 0, v3
	s_movk_i32 s58, 0x1600
	s_barrier
	s_branch .LBB0_1115

; #define PG8_STAGE(bufoff, gbase, voff) do { _Pragma("unroll") for (int _i = 0; _i < 2; ++_i) \
;         __builtin_amdgcn_global_load_lds((const unsigned*)((const char*)(gbase) + (voff)[_i]), (PG8_LAS unsigned*)(lds + (bufoff) + ldsw + _i * 8192), 16, 0, 0); } while (0)
; #define PG8_LDA(dst, b, h) do { _Pragma("unroll") for (int m = 0; m < 4; ++m) _Pragma("unroll") for (int k = 0; k < 2; ++k) dst[m][k] = *(const PG8_LAS bf16x8*)(lds + PG8_SA(b, h) + aoff + m * 2048 + k * 1024); } while (0)
; #define PG8_LDB(dst, b, h) do { _Pragma("unroll") for (int n = 0; n < 2; ++n) _Pragma("unroll") for (int k = 0; k < 2; ++k) dst[n][k] = *(const PG8_LAS bf16x8*)(lds + PG8_SB(b, h) + boff + n * 2048 + k * 1024); } while (0)
; #define PG8_MMA(ai, bj, At, Bt) do { __builtin_amdgcn_s_setprio(1); _Pragma("unroll") for (int m = 0; m < 4; ++m) _Pragma("unroll") for (int n = 0; n < 2; ++n) _Pragma("unroll") for (int k = 0; k < 2; ++k) \
;         acc[ai][bj][m][n] = __builtin_amdgcn_mfma_f32_16x16x32_bf16(Bt[n][k], At[m][k], acc[ai][bj][m][n], 0, 0, 0); __builtin_amdgcn_s_setprio(0); } while (0)
; #define PG8_WAIT_V(n) asm volatile("s_waitcnt vmcnt(" #n ")" ::: "memory")
; #define PG8_WAIT_L(n) asm volatile("s_waitcnt lgkmcnt(" #n ")" ::: "memory")
; #define PG8_BAR __builtin_amdgcn_s_barrier()
; #define PG8_SCHED __builtin_amdgcn_sched_barrier(0)
; template <class Epi, class Sched, bool ALIGN_EPI = false, bool SP2 = false>
; __device__ __forceinline__ void gemm_phase(PG8_LAS unsigned char* lds, const Gemm g, const Sched& S, const Epi& E) {
;     ...
;             PG8_LDB(B0, 0, 0); PG8_LDB(B1, 0, 1); PG8_SCHED; PG8_LDA(At, 0, 0); PG8_STAGE(PG8_SA(1, 1), a1 + hstep, voffA);
;             PG8_WAIT_V(8); PG8_WAIT_L(0); PG8_BAR; PG8_MMA(0, 0, At, B0); PG8_MMA(0, 1, At, B1); PG8_BAR; PG8_SCHED;
;             PG8_LDA(At, 0, 1); PG8_STAGE(PG8_SB(0, 0), b2, voffB); PG8_STAGE(PG8_SB(0, 1), b2 + hstep, voffB); PG8_STAGE(PG8_SA(0, 0), a2, voffA);
;             PG8_WAIT_V(8); PG8_WAIT_L(0); PG8_BAR; PG8_MMA(1, 0, At, B0); PG8_MMA(1, 1, At, B1); PG8_BAR; PG8_SCHED;
.LBB0_1118:
	ds_read_b128 v[144:147], v151
	ds_read_b128 v[154:157], v235
	ds_read_b128 v[158:161], v151 offset:2048
	ds_read_b128 v[162:165], v235 offset:2048
	ds_read_b128 v[166:169], v152
	ds_read_b128 v[170:173], v236
	ds_read_b128 v[174:177], v152 offset:2048
	ds_read_b128 v[178:181], v236 offset:2048
	s_add_u32 s0, s30, 0xfffc0080
	s_addc_u32 s1, s31, -1
	s_cmp_eq_u32 s64, 12
	s_cselect_b32 s37, s23, s1
	s_cselect_b32 s36, s60, s0
	s_cselect_b32 s35, s21, s63
	s_cselect_b32 s34, s61, s62
	v_lshl_add_u64 v[222:223], s[30:31], 0, v[136:137]
	s_add_i32 m0, s29, 0xc000
	ds_read_b128 v[190:193], v153
	ds_read_b128 v[194:197], v233
	ds_read_b128 v[198:201], v153 offset:2048
	ds_read_b128 v[202:205], v233 offset:2048
	ds_read_b128 v[206:209], v153 offset:4096
	ds_read_b128 v[210:213], v233 offset:4096
	ds_read_b128 v[214:217], v153 offset:6144
	ds_read_b128 v[218:221], v233 offset:6144
	global_load_lds_dwordx4 v[222:223], off
	v_lshl_add_u64 v[222:223], s[30:31], 0, v[138:139]
	s_add_i32 m0, s29, 0xe000
	s_nop 0
	global_load_lds_dwordx4 v[222:223], off
	s_waitcnt vmcnt(8)
	s_waitcnt lgkmcnt(0)
	s_barrier
	s_setprio 1
	s_waitcnt lgkmcnt(0)
	v_mfma_f32_16x16x32_bf16 v[124:127], v[144:147], v[190:193], v[124:127]
	v_mfma_f32_16x16x32_bf16 v[120:123], v[158:161], v[190:193], v[120:123]
	v_mfma_f32_16x16x32_bf16 v[108:111], v[144:147], v[198:201], v[108:111]
	v_mfma_f32_16x16x32_bf16 v[104:107], v[158:161], v[198:201], v[104:107]
	v_mfma_f32_16x16x32_bf16 v[92:95], v[144:147], v[206:209], v[92:95]
	v_mfma_f32_16x16x32_bf16 v[88:91], v[158:161], v[206:209], v[88:91]
	v_mfma_f32_16x16x32_bf16 v[76:79], v[144:147], v[214:217], v[76:79]
	v_mfma_f32_16x16x32_bf16 v[72:75], v[158:161], v[214:217], v[72:75]
	v_mfma_f32_16x16x32_bf16 v[124:127], v[154:157], v[194:197], v[124:127]
	v_mfma_f32_16x16x32_bf16 v[120:123], v[162:165], v[194:197], v[120:123]
	v_mfma_f32_16x16x32_bf16 v[108:111], v[154:157], v[202:205], v[108:111]
	v_mfma_f32_16x16x32_bf16 v[104:107], v[162:165], v[202:205], v[104:107]
	v_mfma_f32_16x16x32_bf16 v[92:95], v[154:157], v[210:213], v[92:95]
	v_mfma_f32_16x16x32_bf16 v[88:91], v[162:165], v[210:213], v[88:91]
	v_mfma_f32_16x16x32_bf16 v[76:79], v[154:157], v[218:221], v[76:79]
	v_mfma_f32_16x16x32_bf16 v[72:75], v[162:165], v[218:221], v[72:75]
	s_setprio 0
	s_setprio 1
	v_mfma_f32_16x16x32_bf16 v[116:119], v[166:169], v[190:193], v[116:119]
	v_mfma_f32_16x16x32_bf16 v[112:115], v[174:177], v[190:193], v[112:115]
	v_mfma_f32_16x16x32_bf16 v[100:103], v[166:169], v[198:201], v[100:103]
	v_mfma_f32_16x16x32_bf16 v[96:99], v[174:177], v[198:201], v[96:99]
	v_mfma_f32_16x16x32_bf16 v[84:87], v[166:169], v[206:209], v[84:87]
	v_mfma_f32_16x16x32_bf16 v[80:83], v[174:177], v[206:209], v[80:83]
	v_mfma_f32_16x16x32_bf16 v[68:71], v[166:169], v[214:217], v[68:71]
	v_mfma_f32_16x16x32_bf16 v[64:67], v[174:177], v[214:217], v[64:67]
	v_mfma_f32_16x16x32_bf16 v[116:119], v[170:173], v[194:197], v[116:119]
	v_mfma_f32_16x16x32_bf16 v[112:115], v[178:181], v[194:197], v[112:115]
	v_mfma_f32_16x16x32_bf16 v[100:103], v[170:173], v[202:205], v[100:103]
	v_mfma_f32_16x16x32_bf16 v[96:99], v[178:181], v[202:205], v[96:99]
	v_mfma_f32_16x16x32_bf16 v[84:87], v[170:173], v[210:213], v[84:87]
	v_mfma_f32_16x16x32_bf16 v[80:83], v[178:181], v[210:213], v[80:83]
	v_mfma_f32_16x16x32_bf16 v[68:71], v[170:173], v[218:221], v[68:71]
	v_mfma_f32_16x16x32_bf16 v[64:67], v[178:181], v[218:221], v[64:67]
	s_setprio 0
	s_barrier
	s_add_i32 s0, s56, s42
	v_lshl_add_u64 v[222:223], s[34:35], 0, v[132:133]
	s_mov_b32 m0, s0
	ds_read_b128 v[190:193], v153 offset:16384
	ds_read_b128 v[194:197], v233 offset:16384
	ds_read_b128 v[198:201], v153 offset:18432
	ds_read_b128 v[202:205], v233 offset:18432
	ds_read_b128 v[206:209], v153 offset:20480
	ds_read_b128 v[210:213], v233 offset:20480
	ds_read_b128 v[214:217], v153 offset:22528
	ds_read_b128 v[218:221], v233 offset:22528
	global_load_lds_dwordx4 v[222:223], off
	s_add_i32 m0, s0, 0x2000
	s_add_u32 s0, s34, 0x40000
	v_lshl_add_u64 v[224:225], s[34:35], 0, v[128:129]
	s_addc_u32 s1, s35, 0
	s_add_i32 s3, s57, s42
	global_load_lds_dwordx4 v[224:225], off
	v_lshl_add_u64 v[226:227], s[0:1], 0, v[132:133]
	s_mov_b32 m0, s3
	v_lshl_add_u64 v[228:229], s[36:37], 0, v[130:131]
	global_load_lds_dwordx4 v[226:227], off
	v_lshl_add_u64 v[226:227], s[0:1], 0, v[128:129]
	s_add_i32 m0, s3, 0x2000
	s_nop 0
	global_load_lds_dwordx4 v[226:227], off
	v_lshl_add_u64 v[226:227], s[36:37], 0, v[134:135]
	s_mov_b32 m0, s29
	s_nop 0
	global_load_lds_dwordx4 v[226:227], off
	s_mov_b32 m0, s48
	s_nop 0
	global_load_lds_dwordx4 v[228:229], off
	s_waitcnt vmcnt(8)
	s_waitcnt lgkmcnt(0)
	s_barrier
; #define PG8_STAGE(bufoff, gbase, voff) do { _Pragma("unroll") for (int _i = 0; _i < 2; ++_i) \
;         __builtin_amdgcn_global_load_lds((const unsigned*)((const char*)(gbase) + (voff)[_i]), (PG8_LAS unsigned*)(lds + (bufoff) + ldsw + _i * 8192), 16, 0, 0); } while (0)
; #define PG8_LDA(dst, b, h) do { _Pragma("unroll") for (int m = 0; m < 4; ++m) _Pragma("unroll") for (int k = 0; k < 2; ++k) dst[m][k] = *(const PG8_LAS bf16x8*)(lds + PG8_SA(b, h) + aoff + m * 2048 + k * 1024); } while (0)
; #define PG8_LDB(dst, b, h) do { _Pragma("unroll") for (int n = 0; n < 2; ++n) _Pragma("unroll") for (int k = 0; k < 2; ++k) dst[n][k] = *(const PG8_LAS bf16x8*)(lds + PG8_SB(b, h) + boff + n * 2048 + k * 1024); } while (0)
; #define PG8_MMA(ai, bj, At, Bt) do { __builtin_amdgcn_s_setprio(1); _Pragma("unroll") for (int m = 0; m < 4; ++m) _Pragma("unroll") for (int n = 0; n < 2; ++n) _Pragma("unroll") for (int k = 0; k < 2; ++k) \
;         acc[ai][bj][m][n] = __builtin_amdgcn_mfma_f32_16x16x32_bf16(Bt[n][k], At[m][k], acc[ai][bj][m][n], 0, 0, 0); __builtin_amdgcn_s_setprio(0); } while (0)
; #define PG8_WAIT_V(n) asm volatile("s_waitcnt vmcnt(" #n ")" ::: "memory")
; #define PG8_WAIT_L(n) asm volatile("s_waitcnt lgkmcnt(" #n ")" ::: "memory")
; #define PG8_BAR __builtin_amdgcn_s_barrier()
; #define PG8_SCHED __builtin_amdgcn_sched_barrier(0)
; template <class Epi, class Sched, bool ALIGN_EPI = false, bool SP2 = false>
; __device__ __forceinline__ void gemm_phase(PG8_LAS unsigned char* lds, const Gemm g, const Sched& S, const Epi& E) {
;     ...
;             PG8_WAIT_V(8); PG8_WAIT_L(0); PG8_BAR; PG8_MMA(1, 0, At, B0); PG8_MMA(1, 1, At, B1); PG8_BAR; PG8_SCHED;
;             PG8_LDB(B0, 1, 0); PG8_LDB(B1, 1, 1); PG8_SCHED; PG8_LDA(At, 1, 0); PG8_STAGE(PG8_SA(0, 1), a2 + hstep, voffA);
;             PG8_WAIT_V(8); PG8_WAIT_L(0); PG8_BAR; PG8_MMA(0, 0, At, B0); PG8_MMA(0, 1, At, B1); PG8_BAR; PG8_SCHED;
;             PG8_LDA(At, 1, 1); PG8_STAGE(PG8_SB(1, 0), b3, voffB); PG8_STAGE(PG8_SB(1, 1), b3 + hstep, voffB); PG8_STAGE(PG8_SA(1, 0), a3, voffA);
	s_setprio 1
	s_waitcnt lgkmcnt(0)
	v_mfma_f32_16x16x32_bf16 v[60:63], v[144:147], v[190:193], v[60:63]
	v_mfma_f32_16x16x32_bf16 v[56:59], v[158:161], v[190:193], v[56:59]
	v_mfma_f32_16x16x32_bf16 v[44:47], v[144:147], v[198:201], v[44:47]
	v_mfma_f32_16x16x32_bf16 v[40:43], v[158:161], v[198:201], v[40:43]
	v_mfma_f32_16x16x32_bf16 v[28:31], v[144:147], v[206:209], v[28:31]
	v_mfma_f32_16x16x32_bf16 v[24:27], v[158:161], v[206:209], v[24:27]
	v_mfma_f32_16x16x32_bf16 v[12:15], v[144:147], v[214:217], v[12:15]
	v_mfma_f32_16x16x32_bf16 v[8:11], v[158:161], v[214:217], v[8:11]
	v_mfma_f32_16x16x32_bf16 v[60:63], v[154:157], v[194:197], v[60:63]
	v_mfma_f32_16x16x32_bf16 v[56:59], v[162:165], v[194:197], v[56:59]
	v_mfma_f32_16x16x32_bf16 v[44:47], v[154:157], v[202:205], v[44:47]
	v_mfma_f32_16x16x32_bf16 v[40:43], v[162:165], v[202:205], v[40:43]
	v_mfma_f32_16x16x32_bf16 v[28:31], v[154:157], v[210:213], v[28:31]
	v_mfma_f32_16x16x32_bf16 v[24:27], v[162:165], v[210:213], v[24:27]
	v_mfma_f32_16x16x32_bf16 v[12:15], v[154:157], v[218:221], v[12:15]
	v_mfma_f32_16x16x32_bf16 v[8:11], v[162:165], v[218:221], v[8:11]
	s_setprio 0
	s_setprio 1
	v_mfma_f32_16x16x32_bf16 v[52:55], v[166:169], v[190:193], v[52:55]
	v_mfma_f32_16x16x32_bf16 v[48:51], v[174:177], v[190:193], v[48:51]
	v_mfma_f32_16x16x32_bf16 v[36:39], v[166:169], v[198:201], v[36:39]
	v_mfma_f32_16x16x32_bf16 v[32:35], v[174:177], v[198:201], v[32:35]
	v_mfma_f32_16x16x32_bf16 v[20:23], v[166:169], v[206:209], v[20:23]
	v_mfma_f32_16x16x32_bf16 v[16:19], v[174:177], v[206:209], v[16:19]
	v_mfma_f32_16x16x32_bf16 v[4:7], v[166:169], v[214:217], v[4:7]
	v_mfma_f32_16x16x32_bf16 v[0:3], v[174:177], v[214:217], v[0:3]
	v_mfma_f32_16x16x32_bf16 v[52:55], v[170:173], v[194:197], v[52:55]
	v_mfma_f32_16x16x32_bf16 v[48:51], v[178:181], v[194:197], v[48:51]
	v_mfma_f32_16x16x32_bf16 v[36:39], v[170:173], v[202:205], v[36:39]
	v_mfma_f32_16x16x32_bf16 v[32:35], v[178:181], v[202:205], v[32:35]
	v_mfma_f32_16x16x32_bf16 v[20:23], v[170:173], v[210:213], v[20:23]
	v_mfma_f32_16x16x32_bf16 v[16:19], v[178:181], v[210:213], v[16:19]
	v_mfma_f32_16x16x32_bf16 v[4:7], v[170:173], v[218:221], v[4:7]
	v_mfma_f32_16x16x32_bf16 v[0:3], v[178:181], v[218:221], v[0:3]
	s_setprio 0
	s_barrier
	s_add_i32 s3, 0, 0x18000
	s_add_i32 s45, 0, 0x1c000
	v_add_u32_e32 v162, s3, v149
	v_add_u32_e32 v237, s3, v234
	v_add_u32_e32 v178, s45, v149
	v_add_u32_e32 v238, s45, v234
	ds_read_b128 v[144:147], v162
	ds_read_b128 v[154:157], v237
	ds_read_b128 v[158:161], v162 offset:2048
	ds_read_b128 v[162:165], v237 offset:2048
	ds_read_b128 v[166:169], v178
	ds_read_b128 v[170:173], v238
	ds_read_b128 v[174:177], v178 offset:2048
	ds_read_b128 v[178:181], v238 offset:2048
	s_add_u32 s0, s36, 0x40000
	s_addc_u32 s1, s37, 0
	s_mov_b32 m0, s49
	v_lshl_add_u64 v[230:231], s[0:1], 0, v[134:135]
	ds_read_b128 v[190:193], v153 offset:32768
	ds_read_b128 v[194:197], v233 offset:32768
	ds_read_b128 v[198:201], v153 offset:34816
	ds_read_b128 v[202:205], v233 offset:34816
	ds_read_b128 v[206:209], v153 offset:36864
	ds_read_b128 v[210:213], v233 offset:36864
	ds_read_b128 v[214:217], v153 offset:38912
	ds_read_b128 v[218:221], v233 offset:38912
	global_load_lds_dwordx4 v[230:231], off
	v_lshl_add_u64 v[230:231], s[0:1], 0, v[130:131]
	s_mov_b32 m0, s50
	s_nop 0
	global_load_lds_dwordx4 v[230:231], off
	s_waitcnt vmcnt(8)
	s_waitcnt lgkmcnt(0)
	s_barrier
	s_setprio 1
	s_waitcnt lgkmcnt(0)
	v_mfma_f32_16x16x32_bf16 v[124:127], v[144:147], v[190:193], v[124:127]
	v_mfma_f32_16x16x32_bf16 v[120:123], v[158:161], v[190:193], v[120:123]
	v_mfma_f32_16x16x32_bf16 v[108:111], v[144:147], v[198:201], v[108:111]
	v_mfma_f32_16x16x32_bf16 v[104:107], v[158:161], v[198:201], v[104:107]
	v_mfma_f32_16x16x32_bf16 v[92:95], v[144:147], v[206:209], v[92:95]
	v_mfma_f32_16x16x32_bf16 v[88:91], v[158:161], v[206:209], v[88:91]
	v_mfma_f32_16x16x32_bf16 v[76:79], v[144:147], v[214:217], v[76:79]
	v_mfma_f32_16x16x32_bf16 v[72:75], v[158:161], v[214:217], v[72:75]
	v_mfma_f32_16x16x32_bf16 v[124:127], v[154:157], v[194:197], v[124:127]
	v_mfma_f32_16x16x32_bf16 v[120:123], v[162:165], v[194:197], v[120:123]
	v_mfma_f32_16x16x32_bf16 v[108:111], v[154:157], v[202:205], v[108:111]
	v_mfma_f32_16x16x32_bf16 v[104:107], v[162:165], v[202:205], v[104:107]
	v_mfma_f32_16x16x32_bf16 v[92:95], v[154:157], v[210:213], v[92:95]
	v_mfma_f32_16x16x32_bf16 v[88:91], v[162:165], v[210:213], v[88:91]
	v_mfma_f32_16x16x32_bf16 v[76:79], v[154:157], v[218:221], v[76:79]
	v_mfma_f32_16x16x32_bf16 v[72:75], v[162:165], v[218:221], v[72:75]
	s_setprio 0
	s_setprio 1
	v_mfma_f32_16x16x32_bf16 v[116:119], v[166:169], v[190:193], v[116:119]
	v_mfma_f32_16x16x32_bf16 v[112:115], v[174:177], v[190:193], v[112:115]
	v_mfma_f32_16x16x32_bf16 v[100:103], v[166:169], v[198:201], v[100:103]
	v_mfma_f32_16x16x32_bf16 v[96:99], v[174:177], v[198:201], v[96:99]
	v_mfma_f32_16x16x32_bf16 v[84:87], v[166:169], v[206:209], v[84:87]
	v_mfma_f32_16x16x32_bf16 v[80:83], v[174:177], v[206:209], v[80:83]
	v_mfma_f32_16x16x32_bf16 v[68:71], v[166:169], v[214:217], v[68:71]
	v_mfma_f32_16x16x32_bf16 v[64:67], v[174:177], v[214:217], v[64:67]
	v_mfma_f32_16x16x32_bf16 v[116:119], v[170:173], v[194:197], v[116:119]
	v_mfma_f32_16x16x32_bf16 v[112:115], v[178:181], v[194:197], v[112:115]
	v_mfma_f32_16x16x32_bf16 v[100:103], v[170:173], v[202:205], v[100:103]
	v_mfma_f32_16x16x32_bf16 v[96:99], v[178:181], v[202:205], v[96:99]
	v_mfma_f32_16x16x32_bf16 v[84:87], v[170:173], v[210:213], v[84:87]
	v_mfma_f32_16x16x32_bf16 v[80:83], v[178:181], v[210:213], v[80:83]
	v_mfma_f32_16x16x32_bf16 v[68:71], v[170:173], v[218:221], v[68:71]
	v_mfma_f32_16x16x32_bf16 v[64:67], v[178:181], v[218:221], v[64:67]
	s_setprio 0
	s_barrier
; __device__ __forceinline__ unsigned cvt_pk_bf16(float lo, float hi) { unsigned r; asm volatile("v_cvt_pk_bf16_f32 %0, %1, %2" : "=v"(r) : "v"(lo), "v"(hi)); return r; }
; __device__ __forceinline__ float silu_f(float x) { return x * sigmoid_f(x); }
; #define PG8_STAGE(bufoff, gbase, voff) do { _Pragma("unroll") for (int _i = 0; _i < 2; ++_i) \
;         __builtin_amdgcn_global_load_lds((const unsigned*)((const char*)(gbase) + (voff)[_i]), (PG8_LAS unsigned*)(lds + (bufoff) + ldsw + _i * 8192), 16, 0, 0); } while (0)
; #define PG8_LDA(dst, b, h) do { _Pragma("unroll") for (int m = 0; m < 4; ++m) _Pragma("unroll") for (int k = 0; k < 2; ++k) dst[m][k] = *(const PG8_LAS bf16x8*)(lds + PG8_SA(b, h) + aoff + m * 2048 + k * 1024); } while (0)
; #define PG8_WAIT_V(n) asm volatile("s_waitcnt vmcnt(" #n ")" ::: "memory")
; #define PG8_WAIT_L(n) asm volatile("s_waitcnt lgkmcnt(" #n ")" ::: "memory")
; #define PG8_BAR __builtin_amdgcn_s_barrier()
; #define PG8_SCHED __builtin_amdgcn_sched_barrier(0)
;     __device__ __forceinline__ void operator()(const f32x4 (&acc)[2][2][4][2], const Unit& u, int wr, int wc, int fr, int fq) const {
;         const int row0 = u.pm * BM + wr * 64 + fr; const int col0 = u.pn * HALF + wc * 32 + 8 * fq;
; #pragma unroll
;         for (int ai = 0; ai < 2; ++ai)
; #pragma unroll
;             for (int m = 0; m < 4; ++m) {
;                 bf16_t* rowp = O + (size_t)(row0 + ai * HALF + m * 16) * ldc + col0;
;                 const f32x4 g0 = acc[ai][0][m][0], g1 = acc[ai][0][m][1], u0 = acc[ai][1][m][0], u1 = acc[ai][1][m][1];
;                 u32x4 w;
;                 w.x = cvt_pk_bf16(silu_f(g0[0]) * u0[0], silu_f(g0[1]) * u0[1]); w.y = cvt_pk_bf16(silu_f(g0[2]) * u0[2], silu_f(g0[3]) * u0[3]);
;                 w.z = cvt_pk_bf16(silu_f(g1[0]) * u1[0], silu_f(g1[1]) * u1[1]); w.w = cvt_pk_bf16(silu_f(g1[2]) * u1[2], silu_f(g1[3]) * u1[3]);
;                 *(u32x4*)rowp = w;
; template <class Epi, class Sched, bool ALIGN_EPI = false, bool SP2 = false>
; __device__ __forceinline__ void gemm_phase(PG8_LAS unsigned char* lds, const Gemm g, const Sched& S, const Epi& E) {
;     ...
;             PG8_LDA(At, 1, 1); PG8_STAGE(PG8_SB(1, 0), b3, voffB); PG8_STAGE(PG8_SB(1, 1), b3 + hstep, voffB); PG8_STAGE(PG8_SA(1, 0), a3, voffA);
;             PG8_WAIT_V(8); PG8_WAIT_L(0); PG8_BAR; PG8_MMA(1, 0, At, B0); PG8_MMA(1, 1, At, B1); PG8_BAR; PG8_SCHED;
	s_add_i32 s0, s3, s42
	v_lshl_add_u64 v[222:223], v[222:223], 0, s[16:17]
	s_mov_b32 m0, s0
	ds_read_b128 v[190:193], v153 offset:49152
	ds_read_b128 v[194:197], v233 offset:49152
	ds_read_b128 v[198:201], v153 offset:51200
	ds_read_b128 v[202:205], v233 offset:51200
	ds_read_b128 v[206:209], v153 offset:53248
	ds_read_b128 v[210:213], v233 offset:53248
	ds_read_b128 v[214:217], v153 offset:55296
	ds_read_b128 v[218:221], v233 offset:55296
	global_load_lds_dwordx4 v[222:223], off
	s_add_i32 m0, s0, 0x2000
	s_add_u32 s0, s34, 0x40080
	v_lshl_add_u64 v[222:223], v[224:225], 0, s[16:17]
	s_addc_u32 s1, s35, 0
	s_add_i32 s3, s45, s42
	global_load_lds_dwordx4 v[222:223], off
	v_lshl_add_u64 v[222:223], s[0:1], 0, v[132:133]
	s_mov_b32 m0, s3
	s_nop 0
	global_load_lds_dwordx4 v[222:223], off
	v_lshl_add_u64 v[222:223], s[0:1], 0, v[128:129]
	s_add_i32 m0, s3, 0x2000
	s_nop 0
	global_load_lds_dwordx4 v[222:223], off
	v_lshl_add_u64 v[222:223], v[226:227], 0, s[16:17]
	s_mov_b32 m0, s52
	s_nop 0
	global_load_lds_dwordx4 v[222:223], off
	v_lshl_add_u64 v[222:223], v[228:229], 0, s[16:17]
	s_mov_b32 m0, s53
	s_nop 0
	global_load_lds_dwordx4 v[222:223], off
	s_waitcnt vmcnt(8)
	s_waitcnt lgkmcnt(0)
	s_barrier
	s_setprio 1
	s_waitcnt lgkmcnt(0)
	v_mfma_f32_16x16x32_bf16 v[60:63], v[144:147], v[190:193], v[60:63]
	v_mfma_f32_16x16x32_bf16 v[56:59], v[158:161], v[190:193], v[56:59]
	v_mfma_f32_16x16x32_bf16 v[44:47], v[144:147], v[198:201], v[44:47]
	v_mfma_f32_16x16x32_bf16 v[40:43], v[158:161], v[198:201], v[40:43]
	v_mfma_f32_16x16x32_bf16 v[28:31], v[144:147], v[206:209], v[28:31]
	v_mfma_f32_16x16x32_bf16 v[24:27], v[158:161], v[206:209], v[24:27]
	v_mfma_f32_16x16x32_bf16 v[12:15], v[144:147], v[214:217], v[12:15]
	v_mfma_f32_16x16x32_bf16 v[8:11], v[158:161], v[214:217], v[8:11]
	v_mfma_f32_16x16x32_bf16 v[60:63], v[154:157], v[194:197], v[60:63]
	v_mfma_f32_16x16x32_bf16 v[56:59], v[162:165], v[194:197], v[56:59]
	v_mfma_f32_16x16x32_bf16 v[44:47], v[154:157], v[202:205], v[44:47]
	v_mfma_f32_16x16x32_bf16 v[40:43], v[162:165], v[202:205], v[40:43]
	v_mfma_f32_16x16x32_bf16 v[28:31], v[154:157], v[210:213], v[28:31]
	v_mfma_f32_16x16x32_bf16 v[24:27], v[162:165], v[210:213], v[24:27]
	v_mfma_f32_16x16x32_bf16 v[12:15], v[154:157], v[218:221], v[12:15]
	v_mfma_f32_16x16x32_bf16 v[8:11], v[162:165], v[218:221], v[8:11]
	s_setprio 0
	s_setprio 1
	v_mfma_f32_16x16x32_bf16 v[52:55], v[166:169], v[190:193], v[52:55]
	v_mfma_f32_16x16x32_bf16 v[48:51], v[174:177], v[190:193], v[48:51]
	v_mfma_f32_16x16x32_bf16 v[36:39], v[166:169], v[198:201], v[36:39]
	v_mfma_f32_16x16x32_bf16 v[32:35], v[174:177], v[198:201], v[32:35]
	v_mfma_f32_16x16x32_bf16 v[20:23], v[166:169], v[206:209], v[20:23]
	v_mfma_f32_16x16x32_bf16 v[16:19], v[174:177], v[206:209], v[16:19]
	v_mfma_f32_16x16x32_bf16 v[4:7], v[166:169], v[214:217], v[4:7]
	v_mfma_f32_16x16x32_bf16 v[0:3], v[174:177], v[214:217], v[0:3]
	v_mfma_f32_16x16x32_bf16 v[52:55], v[170:173], v[194:197], v[52:55]
	v_mfma_f32_16x16x32_bf16 v[48:51], v[178:181], v[194:197], v[48:51]
	v_mfma_f32_16x16x32_bf16 v[36:39], v[170:173], v[202:205], v[36:39]
	v_mfma_f32_16x16x32_bf16 v[32:35], v[178:181], v[202:205], v[32:35]
	v_mfma_f32_16x16x32_bf16 v[20:23], v[170:173], v[210:213], v[20:23]
	v_mfma_f32_16x16x32_bf16 v[16:19], v[178:181], v[210:213], v[16:19]
	v_mfma_f32_16x16x32_bf16 v[4:7], v[170:173], v[218:221], v[4:7]
	v_mfma_f32_16x16x32_bf16 v[0:3], v[178:181], v[218:221], v[0:3]
	s_setprio 0
	s_barrier
	s_add_i32 s64, s64, 2
	s_add_u32 s30, s30, 0x100
	s_addc_u32 s31, s31, 0
	s_add_u32 s62, s62, 0x100
	s_addc_u32 s63, s63, 0
	s_cmp_gt_u32 s64, 13
	s_cbranch_scc0 .LBB0_1118
	s_and_b64 vcc, exec, s[18:19]
	s_cbranch_vccz .LBB0_1121
	s_barrier
.LBB0_1121:
	v_lshl_or_b32 v146, s59, 7, v150
	v_lshl_add_u32 v154, s28, 8, v148
	v_ashrrev_i32_e32 v147, 31, v146
	v_mov_b64_e32 v[144:145], s[14:15]
	v_mad_i64_i32 v[156:157], s[0:1], v154, s58, v[144:145]
	v_lshlrev_b64 v[146:147], 1, v[146:147]
	v_lshl_add_u64 v[156:157], v[156:157], 0, v[146:147]
	s_mov_b32 s98, 0xbfb8aa3b
	s_mov_b32 s100, 1.0
	v_pk_mul_f32 v[242:243], v[124:125], s[98:99] op_sel_hi:[1,0]
	v_pk_mul_f32 v[244:245], v[126:127], s[98:99] op_sel_hi:[1,0]
	v_pk_mul_f32 v[246:247], v[120:121], s[98:99] op_sel_hi:[1,0]
	v_pk_mul_f32 v[248:249], v[122:123], s[98:99] op_sel_hi:[1,0]
	v_exp_f32_e32 v242, v242
	v_exp_f32_e32 v243, v243
	v_exp_f32_e32 v244, v244
	v_exp_f32_e32 v245, v245
	v_exp_f32_e32 v246, v246
	v_exp_f32_e32 v247, v247
	v_exp_f32_e32 v248, v248
	v_exp_f32_e32 v249, v249
	v_pk_add_f32 v[242:243], v[242:243], s[100:101] op_sel_hi:[1,0]
	v_pk_add_f32 v[244:245], v[244:245], s[100:101] op_sel_hi:[1,0]
	v_pk_add_f32 v[246:247], v[246:247], s[100:101] op_sel_hi:[1,0]
	v_pk_add_f32 v[248:249], v[248:249], s[100:101] op_sel_hi:[1,0]
	v_rcp_f32_e32 v242, v242
	v_rcp_f32_e32 v243, v243
	v_rcp_f32_e32 v244, v244
	v_rcp_f32_e32 v245, v245
	v_rcp_f32_e32 v246, v246
	v_rcp_f32_e32 v247, v247
	v_rcp_f32_e32 v248, v248
	v_rcp_f32_e32 v249, v249
	v_pk_mul_f32 v[242:243], v[124:125], v[242:243]
	v_pk_mul_f32 v[244:245], v[126:127], v[244:245]
	v_pk_mul_f32 v[246:247], v[120:121], v[246:247]
	v_pk_mul_f32 v[248:249], v[122:123], v[248:249]
	v_pk_mul_f32 v[242:243], v[242:243], v[116:117]
	v_pk_mul_f32 v[244:245], v[244:245], v[118:119]
	v_pk_mul_f32 v[246:247], v[246:247], v[112:113]
	v_pk_mul_f32 v[248:249], v[248:249], v[114:115]
	v_cvt_pk_bf16_f32 v116, v242, v243
	v_cvt_pk_bf16_f32 v117, v244, v245
	v_cvt_pk_bf16_f32 v118, v246, v247
	v_cvt_pk_bf16_f32 v119, v248, v249
	global_store_dwordx4 v[156:157], v[116:119], off
	v_or_b32_e32 v112, 16, v154
; __device__ __forceinline__ unsigned cvt_pk_bf16(float lo, float hi) { unsigned r; asm volatile("v_cvt_pk_bf16_f32 %0, %1, %2" : "=v"(r) : "v"(lo), "v"(hi)); return r; }
; __device__ __forceinline__ float silu_f(float x) { return x * sigmoid_f(x); }
;     __device__ __forceinline__ void operator()(const f32x4 (&acc)[2][2][4][2], const Unit& u, int wr, int wc, int fr, int fq) const {
;         const int row0 = u.pm * BM + wr * 64 + fr; const int col0 = u.pn * HALF + wc * 32 + 8 * fq;
; #pragma unroll
;         for (int ai = 0; ai < 2; ++ai)
; #pragma unroll
;             for (int m = 0; m < 4; ++m) {
;                 bf16_t* rowp = O + (size_t)(row0 + ai * HALF + m * 16) * ldc + col0;
;                 const f32x4 g0 = acc[ai][0][m][0], g1 = acc[ai][0][m][1], u0 = acc[ai][1][m][0], u1 = acc[ai][1][m][1];
;                 u32x4 w;
;                 w.x = cvt_pk_bf16(silu_f(g0[0]) * u0[0], silu_f(g0[1]) * u0[1]); w.y = cvt_pk_bf16(silu_f(g0[2]) * u0[2], silu_f(g0[3]) * u0[3]);
;                 w.z = cvt_pk_bf16(silu_f(g1[0]) * u1[0], silu_f(g1[1]) * u1[1]); w.w = cvt_pk_bf16(silu_f(g1[2]) * u1[2], silu_f(g1[3]) * u1[3]);
;                 *(u32x4*)rowp = w;
	v_mad_i64_i32 v[112:113], s[0:1], v112, s58, v[144:145]
	v_lshl_add_u64 v[112:113], v[112:113], 0, v[146:147]
	v_pk_mul_f32 v[242:243], v[108:109], s[98:99] op_sel_hi:[1,0]
	v_pk_mul_f32 v[244:245], v[110:111], s[98:99] op_sel_hi:[1,0]
	v_pk_mul_f32 v[246:247], v[104:105], s[98:99] op_sel_hi:[1,0]
	v_pk_mul_f32 v[248:249], v[106:107], s[98:99] op_sel_hi:[1,0]
	v_exp_f32_e32 v242, v242
	v_exp_f32_e32 v243, v243
	v_exp_f32_e32 v244, v244
	v_exp_f32_e32 v245, v245
	v_exp_f32_e32 v246, v246
	v_exp_f32_e32 v247, v247
	v_exp_f32_e32 v248, v248
	v_exp_f32_e32 v249, v249
	v_pk_add_f32 v[242:243], v[242:243], s[100:101] op_sel_hi:[1,0]
	v_pk_add_f32 v[244:245], v[244:245], s[100:101] op_sel_hi:[1,0]
	v_pk_add_f32 v[246:247], v[246:247], s[100:101] op_sel_hi:[1,0]
	v_pk_add_f32 v[248:249], v[248:249], s[100:101] op_sel_hi:[1,0]
	v_rcp_f32_e32 v242, v242
	v_rcp_f32_e32 v243, v243
	v_rcp_f32_e32 v244, v244
	v_rcp_f32_e32 v245, v245
	v_rcp_f32_e32 v246, v246
	v_rcp_f32_e32 v247, v247
	v_rcp_f32_e32 v248, v248
	v_rcp_f32_e32 v249, v249
	v_pk_mul_f32 v[242:243], v[108:109], v[242:243]
	v_pk_mul_f32 v[244:245], v[110:111], v[244:245]
	v_pk_mul_f32 v[246:247], v[104:105], v[246:247]
	v_pk_mul_f32 v[248:249], v[106:107], v[248:249]
	v_pk_mul_f32 v[242:243], v[242:243], v[100:101]
	v_pk_mul_f32 v[244:245], v[244:245], v[102:103]
	v_pk_mul_f32 v[246:247], v[246:247], v[96:97]
	v_pk_mul_f32 v[248:249], v[248:249], v[98:99]
	v_cvt_pk_bf16_f32 v100, v242, v243
	v_cvt_pk_bf16_f32 v101, v244, v245
	v_cvt_pk_bf16_f32 v102, v246, v247
	v_cvt_pk_bf16_f32 v103, v248, v249
	global_store_dwordx4 v[112:113], v[100:103], off
	v_or_b32_e32 v96, 32, v154
	v_mad_i64_i32 v[96:97], s[0:1], v96, s58, v[144:145]
	v_lshl_add_u64 v[96:97], v[96:97], 0, v[146:147]
	v_pk_mul_f32 v[242:243], v[92:93], s[98:99] op_sel_hi:[1,0]
	v_pk_mul_f32 v[244:245], v[94:95], s[98:99] op_sel_hi:[1,0]
	v_pk_mul_f32 v[246:247], v[88:89], s[98:99] op_sel_hi:[1,0]
	v_pk_mul_f32 v[248:249], v[90:91], s[98:99] op_sel_hi:[1,0]
	v_exp_f32_e32 v242, v242
	v_exp_f32_e32 v243, v243
	v_exp_f32_e32 v244, v244
	v_exp_f32_e32 v245, v245
	v_exp_f32_e32 v246, v246
	v_exp_f32_e32 v247, v247
	v_exp_f32_e32 v248, v248
	v_exp_f32_e32 v249, v249
	v_pk_add_f32 v[242:243], v[242:243], s[100:101] op_sel_hi:[1,0]
	v_pk_add_f32 v[244:245], v[244:245], s[100:101] op_sel_hi:[1,0]
	v_pk_add_f32 v[246:247], v[246:247], s[100:101] op_sel_hi:[1,0]
	v_pk_add_f32 v[248:249], v[248:249], s[100:101] op_sel_hi:[1,0]
	v_rcp_f32_e32 v242, v242
	v_rcp_f32_e32 v243, v243
	v_rcp_f32_e32 v244, v244
	v_rcp_f32_e32 v245, v245
	v_rcp_f32_e32 v246, v246
	v_rcp_f32_e32 v247, v247
	v_rcp_f32_e32 v248, v248
	v_rcp_f32_e32 v249, v249
	v_pk_mul_f32 v[242:243], v[92:93], v[242:243]
	v_pk_mul_f32 v[244:245], v[94:95], v[244:245]
	v_pk_mul_f32 v[246:247], v[88:89], v[246:247]
	v_pk_mul_f32 v[248:249], v[90:91], v[248:249]
	v_pk_mul_f32 v[242:243], v[242:243], v[84:85]
	v_pk_mul_f32 v[244:245], v[244:245], v[86:87]
	v_pk_mul_f32 v[246:247], v[246:247], v[80:81]
	v_pk_mul_f32 v[248:249], v[248:249], v[82:83]
	v_cvt_pk_bf16_f32 v84, v242, v243
	v_cvt_pk_bf16_f32 v85, v244, v245
	v_cvt_pk_bf16_f32 v86, v246, v247
	v_cvt_pk_bf16_f32 v87, v248, v249
	global_store_dwordx4 v[96:97], v[84:87], off
	v_or_b32_e32 v80, 48, v154
	v_mad_i64_i32 v[80:81], s[0:1], v80, s58, v[144:145]
	v_lshl_add_u64 v[80:81], v[80:81], 0, v[146:147]
	v_pk_mul_f32 v[242:243], v[76:77], s[98:99] op_sel_hi:[1,0]
	v_pk_mul_f32 v[244:245], v[78:79], s[98:99] op_sel_hi:[1,0]
	v_pk_mul_f32 v[246:247], v[72:73], s[98:99] op_sel_hi:[1,0]
	v_pk_mul_f32 v[248:249], v[74:75], s[98:99] op_sel_hi:[1,0]
	v_exp_f32_e32 v242, v242
	v_exp_f32_e32 v243, v243
	v_exp_f32_e32 v244, v244
	v_exp_f32_e32 v245, v245
	v_exp_f32_e32 v246, v246
	v_exp_f32_e32 v247, v247
	v_exp_f32_e32 v248, v248
	v_exp_f32_e32 v249, v249
	v_pk_add_f32 v[242:243], v[242:243], s[100:101] op_sel_hi:[1,0]
	v_pk_add_f32 v[244:245], v[244:245], s[100:101] op_sel_hi:[1,0]
	v_pk_add_f32 v[246:247], v[246:247], s[100:101] op_sel_hi:[1,0]
	v_pk_add_f32 v[248:249], v[248:249], s[100:101] op_sel_hi:[1,0]
	v_rcp_f32_e32 v242, v242
	v_rcp_f32_e32 v243, v243
	v_rcp_f32_e32 v244, v244
	v_rcp_f32_e32 v245, v245
	v_rcp_f32_e32 v246, v246
	v_rcp_f32_e32 v247, v247
	v_rcp_f32_e32 v248, v248
	v_rcp_f32_e32 v249, v249
	v_pk_mul_f32 v[242:243], v[76:77], v[242:243]
	v_pk_mul_f32 v[244:245], v[78:79], v[244:245]
	v_pk_mul_f32 v[246:247], v[72:73], v[246:247]
	v_pk_mul_f32 v[248:249], v[74:75], v[248:249]
	v_pk_mul_f32 v[242:243], v[242:243], v[68:69]
	v_pk_mul_f32 v[244:245], v[244:245], v[70:71]
	v_pk_mul_f32 v[246:247], v[246:247], v[64:65]
	v_pk_mul_f32 v[248:249], v[248:249], v[66:67]
	v_cvt_pk_bf16_f32 v68, v242, v243
	v_cvt_pk_bf16_f32 v69, v244, v245
	v_cvt_pk_bf16_f32 v70, v246, v247
	v_cvt_pk_bf16_f32 v71, v248, v249
	global_store_dwordx4 v[80:81], v[68:71], off
	v_add_u32_e32 v64, 0x80, v154
	v_mad_i64_i32 v[64:65], s[0:1], v64, s58, v[144:145]
	v_lshl_add_u64 v[64:65], v[64:65], 0, v[146:147]
	v_pk_mul_f32 v[242:243], v[60:61], s[98:99] op_sel_hi:[1,0]
	v_pk_mul_f32 v[244:245], v[62:63], s[98:99] op_sel_hi:[1,0]
	v_pk_mul_f32 v[246:247], v[56:57], s[98:99] op_sel_hi:[1,0]
	v_pk_mul_f32 v[248:249], v[58:59], s[98:99] op_sel_hi:[1,0]
	v_exp_f32_e32 v242, v242
	v_exp_f32_e32 v243, v243
	v_exp_f32_e32 v244, v244
	v_exp_f32_e32 v245, v245
	v_exp_f32_e32 v246, v246
	v_exp_f32_e32 v247, v247
	v_exp_f32_e32 v248, v248
	v_exp_f32_e32 v249, v249
	v_pk_add_f32 v[242:243], v[242:243], s[100:101] op_sel_hi:[1,0]
	v_pk_add_f32 v[244:245], v[244:245], s[100:101] op_sel_hi:[1,0]
	v_pk_add_f32 v[246:247], v[246:247], s[100:101] op_sel_hi:[1,0]
; __device__ __forceinline__ unsigned cvt_pk_bf16(float lo, float hi) { unsigned r; asm volatile("v_cvt_pk_bf16_f32 %0, %1, %2" : "=v"(r) : "v"(lo), "v"(hi)); return r; }
; __device__ __forceinline__ float silu_f(float x) { return x * sigmoid_f(x); }
; #define PG8_BAR __builtin_amdgcn_s_barrier()
;     __device__ __forceinline__ void operator()(const f32x4 (&acc)[2][2][4][2], const Unit& u, int wr, int wc, int fr, int fq) const {
;         const int row0 = u.pm * BM + wr * 64 + fr; const int col0 = u.pn * HALF + wc * 32 + 8 * fq;
; #pragma unroll
;         for (int ai = 0; ai < 2; ++ai)
; #pragma unroll
;             for (int m = 0; m < 4; ++m) {
;                 bf16_t* rowp = O + (size_t)(row0 + ai * HALF + m * 16) * ldc + col0;
;                 const f32x4 g0 = acc[ai][0][m][0], g1 = acc[ai][0][m][1], u0 = acc[ai][1][m][0], u1 = acc[ai][1][m][1];
;                 u32x4 w;
;                 w.x = cvt_pk_bf16(silu_f(g0[0]) * u0[0], silu_f(g0[1]) * u0[1]); w.y = cvt_pk_bf16(silu_f(g0[2]) * u0[2], silu_f(g0[3]) * u0[3]);
;                 w.z = cvt_pk_bf16(silu_f(g1[0]) * u1[0], silu_f(g1[1]) * u1[1]); w.w = cvt_pk_bf16(silu_f(g1[2]) * u1[2], silu_f(g1[3]) * u1[3]);
;                 *(u32x4*)rowp = w;
; template <class Epi, class Sched, bool ALIGN_EPI = false, bool SP2 = false>
; __device__ __forceinline__ void gemm_phase(PG8_LAS unsigned char* lds, const Gemm g, const Sched& S, const Epi& E) {
;     ...
;         if (!has_next) break;
; #pragma unroll
;         for (int a = 0; a < 2; ++a)
; #pragma unroll
;             for (int b = 0; b < 2; ++b)
; #pragma unroll
;                 for (int m = 0; m < 4; ++m)
; #pragma unroll
;                     for (int n = 0; n < 2; ++n) acc[a][b][m][n] = (f32x4){0.f, 0.f, 0.f, 0.f};
;         cur = nxt; cA = nA; cB = nB; ++ui;
;         if constexpr (ALIGN_EPI) { if (wr == 1) PG8_BAR; }
;     }
	v_pk_add_f32 v[248:249], v[248:249], s[100:101] op_sel_hi:[1,0]
	v_rcp_f32_e32 v242, v242
	v_rcp_f32_e32 v243, v243
	v_rcp_f32_e32 v244, v244
	v_rcp_f32_e32 v245, v245
	v_rcp_f32_e32 v246, v246
	v_rcp_f32_e32 v247, v247
	v_rcp_f32_e32 v248, v248
	v_rcp_f32_e32 v249, v249
	v_pk_mul_f32 v[242:243], v[60:61], v[242:243]
	v_pk_mul_f32 v[244:245], v[62:63], v[244:245]
	v_pk_mul_f32 v[246:247], v[56:57], v[246:247]
	v_pk_mul_f32 v[248:249], v[58:59], v[248:249]
	v_pk_mul_f32 v[242:243], v[242:243], v[52:53]
	v_pk_mul_f32 v[244:245], v[244:245], v[54:55]
	v_pk_mul_f32 v[246:247], v[246:247], v[48:49]
	v_pk_mul_f32 v[248:249], v[248:249], v[50:51]
	v_cvt_pk_bf16_f32 v52, v242, v243
	v_cvt_pk_bf16_f32 v53, v244, v245
	v_cvt_pk_bf16_f32 v54, v246, v247
	v_cvt_pk_bf16_f32 v55, v248, v249
	global_store_dwordx4 v[64:65], v[52:55], off
	v_add_u32_e32 v48, 0x90, v154
	v_mad_i64_i32 v[48:49], s[0:1], v48, s58, v[144:145]
	v_lshl_add_u64 v[48:49], v[48:49], 0, v[146:147]
	v_pk_mul_f32 v[242:243], v[44:45], s[98:99] op_sel_hi:[1,0]
	v_pk_mul_f32 v[244:245], v[46:47], s[98:99] op_sel_hi:[1,0]
	v_pk_mul_f32 v[246:247], v[40:41], s[98:99] op_sel_hi:[1,0]
	v_pk_mul_f32 v[248:249], v[42:43], s[98:99] op_sel_hi:[1,0]
	v_exp_f32_e32 v242, v242
	v_exp_f32_e32 v243, v243
	v_exp_f32_e32 v244, v244
	v_exp_f32_e32 v245, v245
	v_exp_f32_e32 v246, v246
	v_exp_f32_e32 v247, v247
	v_exp_f32_e32 v248, v248
	v_exp_f32_e32 v249, v249
	v_pk_add_f32 v[242:243], v[242:243], s[100:101] op_sel_hi:[1,0]
	v_pk_add_f32 v[244:245], v[244:245], s[100:101] op_sel_hi:[1,0]
	v_pk_add_f32 v[246:247], v[246:247], s[100:101] op_sel_hi:[1,0]
	v_pk_add_f32 v[248:249], v[248:249], s[100:101] op_sel_hi:[1,0]
	v_rcp_f32_e32 v242, v242
	v_rcp_f32_e32 v243, v243
	v_rcp_f32_e32 v244, v244
	v_rcp_f32_e32 v245, v245
	v_rcp_f32_e32 v246, v246
	v_rcp_f32_e32 v247, v247
	v_rcp_f32_e32 v248, v248
	v_rcp_f32_e32 v249, v249
	v_pk_mul_f32 v[242:243], v[44:45], v[242:243]
	v_pk_mul_f32 v[244:245], v[46:47], v[244:245]
	v_pk_mul_f32 v[246:247], v[40:41], v[246:247]
	v_pk_mul_f32 v[248:249], v[42:43], v[248:249]
	v_pk_mul_f32 v[242:243], v[242:243], v[36:37]
	v_pk_mul_f32 v[244:245], v[244:245], v[38:39]
	v_pk_mul_f32 v[246:247], v[246:247], v[32:33]
	v_pk_mul_f32 v[248:249], v[248:249], v[34:35]
	v_cvt_pk_bf16_f32 v36, v242, v243
	v_cvt_pk_bf16_f32 v37, v244, v245
	v_cvt_pk_bf16_f32 v38, v246, v247
	v_cvt_pk_bf16_f32 v39, v248, v249
	global_store_dwordx4 v[48:49], v[36:39], off
	v_add_u32_e32 v32, 0xa0, v154
	v_mad_i64_i32 v[32:33], s[0:1], v32, s58, v[144:145]
	v_lshl_add_u64 v[32:33], v[32:33], 0, v[146:147]
	v_pk_mul_f32 v[242:243], v[28:29], s[98:99] op_sel_hi:[1,0]
	v_pk_mul_f32 v[244:245], v[30:31], s[98:99] op_sel_hi:[1,0]
	v_pk_mul_f32 v[246:247], v[24:25], s[98:99] op_sel_hi:[1,0]
	v_pk_mul_f32 v[248:249], v[26:27], s[98:99] op_sel_hi:[1,0]
	v_exp_f32_e32 v242, v242
	v_exp_f32_e32 v243, v243
	v_exp_f32_e32 v244, v244
	v_exp_f32_e32 v245, v245
	v_exp_f32_e32 v246, v246
	v_exp_f32_e32 v247, v247
	v_exp_f32_e32 v248, v248
	v_exp_f32_e32 v249, v249
	v_pk_add_f32 v[242:243], v[242:243], s[100:101] op_sel_hi:[1,0]
	v_pk_add_f32 v[244:245], v[244:245], s[100:101] op_sel_hi:[1,0]
	v_pk_add_f32 v[246:247], v[246:247], s[100:101] op_sel_hi:[1,0]
	v_pk_add_f32 v[248:249], v[248:249], s[100:101] op_sel_hi:[1,0]
	v_rcp_f32_e32 v242, v242
	v_rcp_f32_e32 v243, v243
	v_rcp_f32_e32 v244, v244
	v_rcp_f32_e32 v245, v245
	v_rcp_f32_e32 v246, v246
	v_rcp_f32_e32 v247, v247
	v_rcp_f32_e32 v248, v248
	v_rcp_f32_e32 v249, v249
	v_pk_mul_f32 v[242:243], v[28:29], v[242:243]
	v_pk_mul_f32 v[244:245], v[30:31], v[244:245]
	v_pk_mul_f32 v[246:247], v[24:25], v[246:247]
	v_pk_mul_f32 v[248:249], v[26:27], v[248:249]
	v_pk_mul_f32 v[242:243], v[242:243], v[20:21]
	v_pk_mul_f32 v[244:245], v[244:245], v[22:23]
	v_pk_mul_f32 v[246:247], v[246:247], v[16:17]
	v_pk_mul_f32 v[248:249], v[248:249], v[18:19]
	v_cvt_pk_bf16_f32 v20, v242, v243
	v_cvt_pk_bf16_f32 v21, v244, v245
	v_cvt_pk_bf16_f32 v22, v246, v247
	v_cvt_pk_bf16_f32 v23, v248, v249
	global_store_dwordx4 v[32:33], v[20:23], off
	v_add_u32_e32 v16, 0xb0, v154
	v_mad_i64_i32 v[16:17], s[0:1], v16, s58, v[144:145]
	v_lshl_add_u64 v[16:17], v[16:17], 0, v[146:147]
	s_andn2_b64 vcc, exec, s[10:11]
	s_mov_b64 s[10:11], -1
	v_pk_mul_f32 v[242:243], v[12:13], s[98:99] op_sel_hi:[1,0]
	v_pk_mul_f32 v[244:245], v[14:15], s[98:99] op_sel_hi:[1,0]
	v_pk_mul_f32 v[246:247], v[8:9], s[98:99] op_sel_hi:[1,0]
	v_pk_mul_f32 v[248:249], v[10:11], s[98:99] op_sel_hi:[1,0]
	v_exp_f32_e32 v242, v242
	v_exp_f32_e32 v243, v243
	v_exp_f32_e32 v244, v244
	v_exp_f32_e32 v245, v245
	v_exp_f32_e32 v246, v246
	v_exp_f32_e32 v247, v247
	v_exp_f32_e32 v248, v248
	v_exp_f32_e32 v249, v249
	v_pk_add_f32 v[242:243], v[242:243], s[100:101] op_sel_hi:[1,0]
	v_pk_add_f32 v[244:245], v[244:245], s[100:101] op_sel_hi:[1,0]
	v_pk_add_f32 v[246:247], v[246:247], s[100:101] op_sel_hi:[1,0]
	v_pk_add_f32 v[248:249], v[248:249], s[100:101] op_sel_hi:[1,0]
	v_rcp_f32_e32 v242, v242
	v_rcp_f32_e32 v243, v243
	v_rcp_f32_e32 v244, v244
	v_rcp_f32_e32 v245, v245
	v_rcp_f32_e32 v246, v246
	v_rcp_f32_e32 v247, v247
	v_rcp_f32_e32 v248, v248
	v_rcp_f32_e32 v249, v249
	v_pk_mul_f32 v[242:243], v[12:13], v[242:243]
	v_pk_mul_f32 v[244:245], v[14:15], v[244:245]
	v_pk_mul_f32 v[246:247], v[8:9], v[246:247]
	v_pk_mul_f32 v[248:249], v[10:11], v[248:249]
	v_pk_mul_f32 v[242:243], v[242:243], v[4:5]
	v_pk_mul_f32 v[244:245], v[244:245], v[6:7]
	v_pk_mul_f32 v[246:247], v[246:247], v[0:1]
	v_pk_mul_f32 v[248:249], v[248:249], v[2:3]
	v_cvt_pk_bf16_f32 v4, v242, v243
	v_cvt_pk_bf16_f32 v5, v244, v245
	v_cvt_pk_bf16_f32 v6, v246, v247
	v_cvt_pk_bf16_f32 v7, v248, v249
	global_store_dwordx4 v[16:17], v[4:7], off
	s_cbranch_vccnz .LBB0_1114
	s_andn2_b64 vcc, exec, s[12:13]
	s_cbranch_vccnz .LBB0_1113
	s_barrier
	s_branch .LBB0_1113

; __device__ __forceinline__ int fresh_tid() { int t = (int)threadIdx.x; asm volatile("" : "+v"(t)); return t; }
; #define PG8_STAGE(bufoff, gbase, voff) do { _Pragma("unroll") for (int _i = 0; _i < 2; ++_i) \
;         __builtin_amdgcn_global_load_lds((const unsigned*)((const char*)(gbase) + (voff)[_i]), (PG8_LAS unsigned*)(lds + (bufoff) + ldsw + _i * 8192), 16, 0, 0); } while (0)
; #define PG8_WAIT_V(n) asm volatile("s_waitcnt vmcnt(" #n ")" ::: "memory")
; #define PG8_BAR __builtin_amdgcn_s_barrier()
; template <class Epi, class Sched, bool ALIGN_EPI = false, bool SP2 = false>
; __device__ __forceinline__ void gemm_phase(PG8_LAS unsigned char* lds, const Gemm g, const Sched& S, const Epi& E) {
;     const int tid = fresh_tid(), wid = __builtin_amdgcn_readfirstlane(tid >> 6), lane = tid & 63, wr = wid >> 2, wc = wid & 3, fr = lane & 15, fq = lane >> 4;
;     const int K = g.K, nt = K / BK;
;     unsigned voffA[2], voffB[2];
; #pragma unroll
;     for (int i = 0; i < 2; ++i) { int R, C; stage_rc(tid * 16 + i * 8192, R, C); const int Rb = Epi::PERM ? ((R & ~31) + perm32(R & 31)) : R;
;         voffA[i] = (unsigned)(R * K + C) * 2u; voffB[i] = (unsigned)(Rb * K + C) * 2u; }
;     const size_t kstep = (size_t)(BK * 2);
;     const size_t hstep = (size_t)HALF * K * 2;
;     const size_t tstep = 2 * hstep;
;     const unsigned ldsw = (unsigned)wid * 1024u;
;     const int aoff = lds_byte(wr * 64 + fr, fq * 8), boff = lds_byte(wc * 32 + fr, fq * 8);
;     ...
;     if constexpr (SP2) {
;         PG8_STAGE(PG8_SB(0, 0), cB, voffB); PG8_STAGE(PG8_SB(0, 1), cB + hstep, voffB); PG8_STAGE(PG8_SA(0, 0), cA, voffA); PG8_STAGE(PG8_SA(0, 1), cA + hstep, voffA);
;         if (wr == 1) PG8_BAR;
;         PG8_WAIT_V(2); PG8_BAR;
;         PG8_STAGE(PG8_SB(1, 0), cB + kstep, voffB); PG8_STAGE(PG8_SA(1, 0), cA + kstep, voffA); PG8_STAGE(PG8_SB(1, 1), cB + hstep + kstep, voffB);
;         PG8_WAIT_V(6); PG8_BAR;
.LBB0_1193:
	v_ashrrev_i32_e32 v1, 31, v8
	v_lshrrev_b32_e32 v1, 26, v1
	v_add_u32_e32 v1, v8, v1
	v_ashrrev_i32_e32 v9, 6, v1
	v_bfe_i32 v1, v8, 27, 1
	v_lshlrev_b32_e32 v0, 4, v8
	v_lshrrev_b32_e32 v1, 22, v1
	v_add_u32_e32 v1, v0, v1
	v_and_b32_e32 v1, 0xfffffc00, v1
	v_sub_u32_e32 v1, v0, v1
	v_lshrrev_b32_e32 v2, 4, v1
	v_bitop3_b32 v2, v2, v1, 32 bitop3:0x6c
	v_ashrrev_i32_e32 v1, 31, v1
	v_lshrrev_b32_e32 v1, 26, v1
	v_lshlrev_b32_e32 v3, 3, v9
	v_add_u32_e32 v1, v2, v1
	v_and_b32_e32 v3, -16, v3
	v_ashrrev_i32_e32 v11, 6, v1
	v_add_u32_e32 v1, v11, v3
	v_lshlrev_b32_e32 v3, 5, v9
	v_and_b32_e32 v10, 32, v3
	v_mul_i32_i24_e32 v3, 64, v11
	s_waitcnt lgkmcnt(0)
	s_add_u32 s39, s10, 0xb200000
	v_sub_u32_e32 v2, v2, v3
	v_mov_b32_e32 v3, 1
	s_addc_u32 s40, s11, 0
	v_ashrrev_i16_sdwa v2, v3, sext(v2) dst_sel:DWORD dst_unused:UNUSED_PAD src0_sel:DWORD src1_sel:BYTE_0
	v_lshlrev_b32_e32 v4, 1, v1
	v_lshrrev_b32_e32 v5, 2, v1
	v_and_b32_e32 v6, 3, v11
	s_mov_b32 s0, 0xffffe0
	s_add_u32 s41, s8, 0x2300000
	v_bfe_i32 v12, v2, 0, 16
	v_and_b32_e32 v4, 24, v4
	v_and_b32_e32 v5, 4, v5
	v_and_or_b32 v6, v1, s0, v6
	s_movk_i32 s8, 0xb00
	v_add_u32_e32 v2, v10, v12
	v_or3_b32 v4, v6, v5, v4
	v_mul_lo_u32 v1, v1, s8
	v_add_lshl_u32 v128, v2, v1, 1
	v_mul_u32_u24_e32 v1, 0xb00, v4
	v_add_u32_e32 v0, 0x2000, v0
	v_add_lshl_u32 v130, v1, v2, 1
	v_ashrrev_i32_e32 v1, 31, v0
	v_lshrrev_b32_e32 v1, 22, v1
	v_add_u32_e32 v1, v0, v1
	v_ashrrev_i32_e32 v13, 10, v1
	v_mul_i32_i24_e32 v1, 0x400, v13
	v_sub_u32_e32 v0, v0, v1
	v_lshrrev_b32_e32 v1, 4, v0
	v_bitop3_b32 v0, v1, v0, 32 bitop3:0x6c
	v_ashrrev_i32_e32 v2, 31, v0
	v_lshrrev_b32_e32 v2, 26, v2
	v_lshlrev_b32_e32 v1, 3, v13
	v_add_u32_e32 v2, v0, v2
	v_and_b32_e32 v1, -16, v1
	v_ashrrev_i32_e32 v14, 6, v2
	v_lshlrev_b32_e32 v4, 5, v13
	v_add_u32_e32 v1, v14, v1
	v_and_b32_e32 v15, 32, v4
	v_and_b32_e32 v4, 3, v14
	s_addc_u32 s42, s9, 0
	v_and_or_b32 v4, v1, s0, v4
	s_add_i32 s0, s14, s12
	s_ashr_i32 s1, s0, 31
	s_lshr_b32 s1, s1, 27
	s_add_i32 s1, s0, s1
	s_ashr_i32 s3, s1, 5
	s_andn2_b32 s1, s1, 31
	s_sub_i32 s0, s0, s1
	s_bfe_i32 s1, s0, 0x80000
	s_bfe_u32 s1, s1, 0x3000c
	s_add_i32 s1, s0, s1
	s_bfe_i32 s10, s1, 0x80000
	s_and_b32 s1, s1, 0xf8
	s_sub_i32 s0, s1, s0
	s_sext_i32_i8 s0, s0
	s_lshl_b32 s1, s3, 3
	s_sext_i32_i16 s10, s10
	s_sub_i32 s0, s0, s1
	s_ashr_i32 s9, s16, 6
	v_and_b32_e32 v2, 0xc0, v2
	s_add_i32 s64, s0, 0x7f
	s_ashr_i32 s0, s10, 3
	v_sub_u32_e32 v0, v0, v2
	s_ashr_i32 s17, s16, 8
	s_lshl_b32 s43, s9, 10
	s_lshr_b32 s18, s10, 3
	s_mul_hi_i32 s1, s0, 0x160000
	s_mul_i32 s0, s0, 0x160000
	v_ashrrev_i16_sdwa v0, v3, sext(v0) dst_sel:DWORD dst_unused:UNUSED_PAD src0_sel:DWORD src1_sel:BYTE_0
	v_lshlrev_b32_e32 v2, 1, v1
	v_lshrrev_b32_e32 v3, 2, v1
	s_add_u32 s30, s41, s0
	v_bfe_i32 v16, v0, 0, 16
	v_and_b32_e32 v2, 24, v2
	v_and_b32_e32 v3, 4, v3
	s_addc_u32 s31, s42, s1
	s_add_i32 s47, s43, 0
	v_add_u32_e32 v0, v15, v16
	v_or3_b32 v2, v4, v3, v2
	v_mul_lo_u32 v1, v1, s8
	s_add_i32 m0, s47, 0x10000
	v_add_lshl_u32 v132, v0, v1, 1
	v_mul_u32_u24_e32 v1, 0xb00, v2
	v_bfe_u32 v239, v8, 3, 3
	v_and_b32_e32 v240, 7, v8
	v_xor_b32_e32 v240, v240, v239
	v_lshlrev_b32_e32 v240, 4, v240
	v_lshrrev_b32_e32 v241, 6, v8
	v_lshl_add_u32 v242, v241, 3, v239
	v_mov_b32_e32 v243, 0x1600
	v_mad_u32_u24 v128, v242, v243, v240
	v_add_u32_e32 v132, 0x58000, v128
	v_lshrrev_b32_e32 v244, 2, v241
	v_lshlrev_b32_e32 v244, 5, v244
	v_and_b32_e32 v245, 1, v241
	v_lshrrev_b32_e32 v246, 2, v239
	v_lshl_add_u32 v245, v245, 1, v246
	v_lshl_add_u32 v244, v245, 3, v244
	v_bfe_u32 v245, v241, 1, 1
	v_lshl_add_u32 v244, v245, 2, v244
	v_and_b32_e32 v245, 3, v239
	v_add_u32_e32 v244, v244, v245
	v_mad_u32_u24 v130, v244, v243, v240
	v_add_u32_e32 v134, 0x58000, v130
	global_load_lds_dwordx4 v130, s[30:31]
	s_add_i32 m0, s47, 0x12000
	s_add_u32 s0, s30, 0xb0000
	global_load_lds_dwordx4 v134, s[30:31]
	s_addc_u32 s1, s31, 0
	s_add_i32 m0, s47, 0x14000
	s_mul_i32 s11, s64, 0x160000
	global_load_lds_dwordx4 v130, s[0:1]
	s_add_i32 m0, s47, 0x16000
	s_mul_hi_u32 s3, s64, 0x160000
	s_add_u32 s28, s39, s11
	s_addc_u32 s29, s40, s3
	s_add_i32 s48, s47, 0x2000
	global_load_lds_dwordx4 v134, s[0:1]
	s_mov_b32 m0, s47
	s_add_u32 s0, s28, 0xb0000
	global_load_lds_dwordx4 v128, s[28:29]
	s_mov_b32 m0, s48
	s_addc_u32 s1, s29, 0
	s_add_i32 s49, s47, 0x4000
	global_load_lds_dwordx4 v132, s[28:29]
	s_mov_b32 m0, s49
	s_add_i32 s50, s47, 0x6000
	global_load_lds_dwordx4 v128, s[0:1]
	s_mov_b32 m0, s50
	v_mov_b32_e32 v131, 0
	global_load_lds_dwordx4 v132, s[0:1]
	v_mov_b32_e32 v135, v131
	v_mov_b32_e32 v129, v131
	v_mov_b32_e32 v133, v131
	s_cmp_eq_u32 s17, 1
	s_mov_b32 s51, 0
	v_lshl_add_u64 v[6:7], s[30:31], 0, v[130:131]
	v_lshl_add_u64 v[4:5], s[30:31], 0, v[134:135]
	v_lshl_add_u64 v[0:1], s[28:29], 0, v[128:129]
	s_cselect_b64 s[10:11], -1, 0
	s_cmp_lg_u32 s17, 1
	v_lshl_add_u64 v[2:3], s[28:29], 0, v[132:133]
	s_cbranch_scc1 .LBB0_1195
	s_barrier
; #define PG8_STAGE(bufoff, gbase, voff) do { _Pragma("unroll") for (int _i = 0; _i < 2; ++_i) \
;         __builtin_amdgcn_global_load_lds((const unsigned*)((const char*)(gbase) + (voff)[_i]), (PG8_LAS unsigned*)(lds + (bufoff) + ldsw + _i * 8192), 16, 0, 0); } while (0)
; #define PG8_WAIT_V(n) asm volatile("s_waitcnt vmcnt(" #n ")" ::: "memory")
; #define PG8_BAR __builtin_amdgcn_s_barrier()
; template <class Epi, class Sched, bool ALIGN_EPI = false, bool SP2 = false>
; __device__ __forceinline__ void gemm_phase(PG8_LAS unsigned char* lds, const Gemm g, const Sched& S, const Epi& E) {
;     ...
;     const int aoff = lds_byte(wr * 64 + fr, fq * 8), boff = lds_byte(wc * 32 + fr, fq * 8);
;     ...
;         PG8_STAGE(PG8_SB(1, 0), cB + kstep, voffB); PG8_STAGE(PG8_SA(1, 0), cA + kstep, voffA); PG8_STAGE(PG8_SB(1, 1), cB + hstep + kstep, voffB);
;         PG8_WAIT_V(6); PG8_BAR;
;     ...
;     for (;;) {
;         const bool has_next = S.next(ui + 1, nxt);
;         const char* nA = has_next ? (const char*)g.A + (size_t)nxt.pm * tstep : cA; const char* nB = has_next ? (const char*)g.Bt + (size_t)nxt.pn * tstep : cB;
;         for (int t = 0; t < nt; t += 2) {
;             const bool last = (t == nt - 2);
;             const char* a1 = cA + (size_t)(t + 1) * kstep;
;             const char* a2 = last ? nA : cA + (size_t)(t + 2) * kstep; const char* b2 = last ? nB : cB + (size_t)(t + 2) * kstep;
.LBB0_1195:
	s_add_u32 s12, s4, 0x7100000
	s_addc_u32 s13, s5, 0
	s_lshl_b32 s0, s9, 5
	s_mov_b64 s[14:15], 0x80
	s_and_b32 s4, s0, 0x60
	s_add_i32 m0, s47, 0x18000
	v_lshl_add_u64 v[6:7], v[6:7], 0, s[14:15]
	s_lshl_b32 s3, s17, 13
	s_lshl_b32 s5, s4, 7
	s_waitcnt vmcnt(2)
	s_barrier
	global_load_lds_dwordx4 v[6:7], off
	v_lshl_add_u64 v[4:5], v[4:5], 0, s[14:15]
	s_add_i32 m0, s47, 0x1a000
	s_add_i32 s52, s47, 0x8000
	s_add_i32 s53, s47, 0xa000
	global_load_lds_dwordx4 v[4:5], off
	v_lshl_add_u64 v[0:1], v[0:1], 0, s[14:15]
	s_mov_b32 m0, s52
	s_add_u32 s0, s30, 0xb0080
	global_load_lds_dwordx4 v[0:1], off
	v_lshl_add_u64 v[0:1], v[2:3], 0, s[14:15]
	s_mov_b32 m0, s53
	s_addc_u32 s1, s31, 0
	global_load_lds_dwordx4 v[0:1], off
	s_add_i32 m0, s47, 0x1c000
	v_lshl_add_u64 v[0:1], s[0:1], 0, v[130:131]
	global_load_lds_dwordx4 v[0:1], off
	v_lshl_add_u64 v[0:1], s[0:1], 0, v[134:135]
	s_add_i32 m0, s47, 0x1e000
	s_mov_b64 s[0:1], 0xb0080
	global_load_lds_dwordx4 v[0:1], off
	v_lshrrev_b32_e32 v1, 1, v8
	v_and_b32_e32 v1, 24, v1
	v_and_b32_e32 v0, 15, v8
	v_lshlrev_b32_e32 v2, 1, v1
	v_lshl_or_b32 v144, s17, 6, v0
	v_lshl_or_b32 v0, v0, 6, v2
	v_lshlrev_b32_e32 v2, 2, v8
	v_and_b32_e32 v2, 32, v2
	v_bitop3_b32 v3, v0, s3, v2 bitop3:0xde
	v_bitop3_b32 v145, v0, s5, v2 bitop3:0xde
	v_and_b32_e32 v239, 15, v8
	v_and_b32_e32 v240, 7, v239
	v_lshrrev_b32_e32 v239, 3, v239
	v_lshlrev_b32_e32 v239, 10, v239
	v_lshl_add_u32 v239, v240, 7, v239
	v_bfe_u32 v241, v8, 4, 2
	v_xor_b32_e32 v242, v241, v240
	v_or_b32_e32 v241, 4, v241
	v_xor_b32_e32 v243, v241, v240
	v_lshl_add_u32 v242, v242, 4, v239
	v_lshl_add_u32 v243, v243, 4, v239
	v_lshrrev_b32_e32 v244, 8, v8
	v_lshlrev_b32_e32 v244, 13, v244
	v_add_u32_e32 v3, v244, v242
	v_add_u32_e32 v233, v244, v243
	v_bfe_u32 v244, v8, 6, 2
	v_lshlrev_b32_e32 v244, 12, v244
	v_add_u32_e32 v145, v244, v242
	v_add_u32_e32 v234, v244, v243
	v_or_b32_e32 v146, s4, v1
	v_lshrrev_b32_e32 v1, 1, v9
	v_mul_lo_u32 v0, v11, s8
	s_mov_b32 s3, 0xb000
	v_mad_u64_u32 v[0:1], s[4:5], v1, s3, v[0:1]
	v_or_b32_e32 v0, v0, v10
	v_add_lshl_u32 v0, v0, v12, 1
	v_mov_b32_e32 v1, v131
	v_lshl_add_u64 v[136:137], v[0:1], 0, s[0:1]
	v_add_u32_e32 v136, 0xb0080, v128
	v_mov_b32_e32 v137, 0
	v_lshrrev_b32_e32 v1, 1, v13
	v_mul_lo_u32 v0, v14, s8
	v_mad_u64_u32 v[0:1], s[4:5], v1, s3, v[0:1]
	s_waitcnt vmcnt(6)
	s_cmpk_lt_u32 s16, 0x100
	v_or_b32_e32 v0, v0, v15
	s_cselect_b64 s[16:17], -1, 0
	v_add_lshl_u32 v0, v0, v16, 1
	v_mov_b32_e32 v1, v131
	s_add_i32 s56, 0, 0x10000
	s_add_i32 s57, 0, 0x14000
	s_sext_i32_i8 s65, s18
	s_ashr_i32 s54, s94, 31
	s_mov_b32 s55, s94
	v_lshl_add_u64 v[138:139], v[0:1], 0, s[0:1]
	v_add_u32_e32 v138, 0xb0080, v132
	v_mov_b32_e32 v139, 0
	v_mov_b64_e32 v[140:141], 0x200
	v_mov_b64_e32 v[142:143], 0x1ff
	v_add_u32_e32 v147, s56, v145
	v_add_u32_e32 v235, s56, v234
	v_add_u32_e32 v148, s57, v145
	v_add_u32_e32 v236, s57, v234
	v_add_u32_e32 v149, 0, v3
	s_mov_b64 s[18:19], 0x40000
	s_mov_b32 s58, 0x40000
	s_mov_b64 s[20:21], 0x48000
	s_mov_b32 s59, 0x48000
	s_mov_b64 s[22:23], 0x50000
	s_mov_b32 s60, 0x50000
	s_mov_b64 s[24:25], 0x58000
	s_mov_b32 s61, 0x58000
	s_barrier
	s_branch .LBB0_1198

; #define PG8_STAGE(bufoff, gbase, voff) do { _Pragma("unroll") for (int _i = 0; _i < 2; ++_i) \
;         __builtin_amdgcn_global_load_lds((const unsigned*)((const char*)(gbase) + (voff)[_i]), (PG8_LAS unsigned*)(lds + (bufoff) + ldsw + _i * 8192), 16, 0, 0); } while (0)
; #define PG8_LDA(dst, b, h) do { _Pragma("unroll") for (int m = 0; m < 4; ++m) _Pragma("unroll") for (int k = 0; k < 2; ++k) dst[m][k] = *(const PG8_LAS bf16x8*)(lds + PG8_SA(b, h) + aoff + m * 2048 + k * 1024); } while (0)
; #define PG8_LDB(dst, b, h) do { _Pragma("unroll") for (int n = 0; n < 2; ++n) _Pragma("unroll") for (int k = 0; k < 2; ++k) dst[n][k] = *(const PG8_LAS bf16x8*)(lds + PG8_SB(b, h) + boff + n * 2048 + k * 1024); } while (0)
; #define PG8_MMA(ai, bj, At, Bt) do { __builtin_amdgcn_s_setprio(1); _Pragma("unroll") for (int m = 0; m < 4; ++m) _Pragma("unroll") for (int n = 0; n < 2; ++n) _Pragma("unroll") for (int k = 0; k < 2; ++k) \
;         acc[ai][bj][m][n] = __builtin_amdgcn_mfma_f32_16x16x32_bf16(Bt[n][k], At[m][k], acc[ai][bj][m][n], 0, 0, 0); __builtin_amdgcn_s_setprio(0); } while (0)
; #define PG8_WAIT_V(n) asm volatile("s_waitcnt vmcnt(" #n ")" ::: "memory")
; #define PG8_WAIT_L(n) asm volatile("s_waitcnt lgkmcnt(" #n ")" ::: "memory")
; #define PG8_BAR __builtin_amdgcn_s_barrier()
; #define PG8_SCHED __builtin_amdgcn_sched_barrier(0)
; template <class Epi, class Sched, bool ALIGN_EPI = false, bool SP2 = false>
; __device__ __forceinline__ void gemm_phase(PG8_LAS unsigned char* lds, const Gemm g, const Sched& S, const Epi& E) {
;     ...
;             PG8_LDB(B0, 0, 0); PG8_LDB(B1, 0, 1); PG8_SCHED; PG8_LDA(At, 0, 0); PG8_STAGE(PG8_SA(1, 1), a1 + hstep, voffA);
;             PG8_WAIT_V(8); PG8_WAIT_L(0); PG8_BAR; PG8_MMA(0, 0, At, B0); PG8_MMA(0, 1, At, B1); PG8_BAR; PG8_SCHED;
;             PG8_LDA(At, 0, 1); PG8_STAGE(PG8_SB(0, 0), b2, voffB); PG8_STAGE(PG8_SB(0, 1), b2 + hstep, voffB); PG8_STAGE(PG8_SA(0, 0), a2, voffA);
;             PG8_WAIT_V(8); PG8_WAIT_L(0); PG8_BAR; PG8_MMA(1, 0, At, B0); PG8_MMA(1, 1, At, B1); PG8_BAR; PG8_SCHED;
.LBB0_1209:
	ds_read_b128 v[150:153], v147
	ds_read_b128 v[154:157], v235
	ds_read_b128 v[158:161], v147 offset:2048
	ds_read_b128 v[162:165], v235 offset:2048
	ds_read_b128 v[166:169], v148
	ds_read_b128 v[170:173], v236
	ds_read_b128 v[174:177], v148 offset:2048
	ds_read_b128 v[178:181], v236 offset:2048
	s_add_u32 s30, s28, 0x100
	s_addc_u32 s31, s29, 0
	s_cmp_eq_u32 s68, 40
	s_cselect_b32 s37, s9, s31
	s_cselect_b32 s36, s8, s30
	s_cselect_b32 s35, s27, s67
	s_cselect_b32 s34, s26, s66
	v_lshl_add_u64 v[222:223], s[28:29], 0, v[136:137]
	s_add_i32 m0, s47, 0xc000
	ds_read_b128 v[190:193], v149
	ds_read_b128 v[194:197], v233
	ds_read_b128 v[198:201], v149 offset:2048
	ds_read_b128 v[202:205], v233 offset:2048
	ds_read_b128 v[206:209], v149 offset:4096
	ds_read_b128 v[210:213], v233 offset:4096
	ds_read_b128 v[214:217], v149 offset:6144
	ds_read_b128 v[218:221], v233 offset:6144
	global_load_lds_dwordx4 v[222:223], off
	v_lshl_add_u64 v[222:223], s[28:29], 0, v[138:139]
	s_add_i32 m0, s47, 0xe000
	s_nop 0
	global_load_lds_dwordx4 v[222:223], off
	s_waitcnt vmcnt(8)
	s_waitcnt lgkmcnt(0)
	s_barrier
	s_setprio 1
	s_waitcnt lgkmcnt(0)
	v_mfma_f32_16x16x32_bf16 v[124:127], v[150:153], v[190:193], v[124:127]
	v_mfma_f32_16x16x32_bf16 v[120:123], v[158:161], v[190:193], v[120:123]
	v_mfma_f32_16x16x32_bf16 v[116:119], v[150:153], v[198:201], v[116:119]
	v_mfma_f32_16x16x32_bf16 v[112:115], v[158:161], v[198:201], v[112:115]
	v_mfma_f32_16x16x32_bf16 v[108:111], v[150:153], v[206:209], v[108:111]
	v_mfma_f32_16x16x32_bf16 v[104:107], v[158:161], v[206:209], v[104:107]
	v_mfma_f32_16x16x32_bf16 v[100:103], v[150:153], v[214:217], v[100:103]
	v_mfma_f32_16x16x32_bf16 v[96:99], v[158:161], v[214:217], v[96:99]
	v_mfma_f32_16x16x32_bf16 v[124:127], v[154:157], v[194:197], v[124:127]
	v_mfma_f32_16x16x32_bf16 v[120:123], v[162:165], v[194:197], v[120:123]
	v_mfma_f32_16x16x32_bf16 v[116:119], v[154:157], v[202:205], v[116:119]
	v_mfma_f32_16x16x32_bf16 v[112:115], v[162:165], v[202:205], v[112:115]
	v_mfma_f32_16x16x32_bf16 v[108:111], v[154:157], v[210:213], v[108:111]
	v_mfma_f32_16x16x32_bf16 v[104:107], v[162:165], v[210:213], v[104:107]
	v_mfma_f32_16x16x32_bf16 v[100:103], v[154:157], v[218:221], v[100:103]
	v_mfma_f32_16x16x32_bf16 v[96:99], v[162:165], v[218:221], v[96:99]
	s_setprio 0
	s_setprio 1
	v_mfma_f32_16x16x32_bf16 v[76:79], v[166:169], v[190:193], v[76:79]
	v_mfma_f32_16x16x32_bf16 v[68:71], v[174:177], v[190:193], v[68:71]
	v_mfma_f32_16x16x32_bf16 v[60:63], v[166:169], v[198:201], v[60:63]
	v_mfma_f32_16x16x32_bf16 v[52:55], v[174:177], v[198:201], v[52:55]
	v_mfma_f32_16x16x32_bf16 v[44:47], v[166:169], v[206:209], v[44:47]
	v_mfma_f32_16x16x32_bf16 v[40:43], v[174:177], v[206:209], v[40:43]
	v_mfma_f32_16x16x32_bf16 v[36:39], v[166:169], v[214:217], v[36:39]
	v_mfma_f32_16x16x32_bf16 v[32:35], v[174:177], v[214:217], v[32:35]
	v_mfma_f32_16x16x32_bf16 v[76:79], v[170:173], v[194:197], v[76:79]
	v_mfma_f32_16x16x32_bf16 v[68:71], v[178:181], v[194:197], v[68:71]
	v_mfma_f32_16x16x32_bf16 v[60:63], v[170:173], v[202:205], v[60:63]
	v_mfma_f32_16x16x32_bf16 v[52:55], v[178:181], v[202:205], v[52:55]
	v_mfma_f32_16x16x32_bf16 v[44:47], v[170:173], v[210:213], v[44:47]
	v_mfma_f32_16x16x32_bf16 v[40:43], v[178:181], v[210:213], v[40:43]
	v_mfma_f32_16x16x32_bf16 v[36:39], v[170:173], v[218:221], v[36:39]
	v_mfma_f32_16x16x32_bf16 v[32:35], v[178:181], v[218:221], v[32:35]
	s_setprio 0
	s_barrier
	s_add_i32 s0, s56, s43
	v_lshl_add_u64 v[222:223], s[34:35], 0, v[130:131]
	s_mov_b32 m0, s0
	ds_read_b128 v[190:193], v149 offset:16384
	ds_read_b128 v[194:197], v233 offset:16384
	ds_read_b128 v[198:201], v149 offset:18432
	ds_read_b128 v[202:205], v233 offset:18432
	ds_read_b128 v[206:209], v149 offset:20480
	ds_read_b128 v[210:213], v233 offset:20480
	ds_read_b128 v[214:217], v149 offset:22528
	ds_read_b128 v[218:221], v233 offset:22528
	global_load_lds_dwordx4 v[222:223], off
	s_add_i32 m0, s0, 0x2000
	s_add_u32 s0, s34, 0xb0000
	v_lshl_add_u64 v[224:225], s[34:35], 0, v[134:135]
	s_addc_u32 s1, s35, 0
	s_add_i32 s3, s57, s43
	global_load_lds_dwordx4 v[224:225], off
	v_lshl_add_u64 v[226:227], s[0:1], 0, v[130:131]
	s_mov_b32 m0, s3
	v_lshl_add_u64 v[228:229], s[36:37], 0, v[132:133]
	global_load_lds_dwordx4 v[226:227], off
	v_lshl_add_u64 v[226:227], s[0:1], 0, v[134:135]
	s_add_i32 m0, s3, 0x2000
	s_nop 0
	global_load_lds_dwordx4 v[226:227], off
	v_lshl_add_u64 v[226:227], s[36:37], 0, v[128:129]
	s_mov_b32 m0, s47
	s_nop 0
	global_load_lds_dwordx4 v[226:227], off
	s_mov_b32 m0, s48
	s_nop 0
	global_load_lds_dwordx4 v[228:229], off
	s_waitcnt vmcnt(8)
	s_waitcnt lgkmcnt(0)
	s_barrier
; #define PG8_STAGE(bufoff, gbase, voff) do { _Pragma("unroll") for (int _i = 0; _i < 2; ++_i) \
;         __builtin_amdgcn_global_load_lds((const unsigned*)((const char*)(gbase) + (voff)[_i]), (PG8_LAS unsigned*)(lds + (bufoff) + ldsw + _i * 8192), 16, 0, 0); } while (0)
; #define PG8_LDA(dst, b, h) do { _Pragma("unroll") for (int m = 0; m < 4; ++m) _Pragma("unroll") for (int k = 0; k < 2; ++k) dst[m][k] = *(const PG8_LAS bf16x8*)(lds + PG8_SA(b, h) + aoff + m * 2048 + k * 1024); } while (0)
; #define PG8_LDB(dst, b, h) do { _Pragma("unroll") for (int n = 0; n < 2; ++n) _Pragma("unroll") for (int k = 0; k < 2; ++k) dst[n][k] = *(const PG8_LAS bf16x8*)(lds + PG8_SB(b, h) + boff + n * 2048 + k * 1024); } while (0)
; #define PG8_MMA(ai, bj, At, Bt) do { __builtin_amdgcn_s_setprio(1); _Pragma("unroll") for (int m = 0; m < 4; ++m) _Pragma("unroll") for (int n = 0; n < 2; ++n) _Pragma("unroll") for (int k = 0; k < 2; ++k) \
;         acc[ai][bj][m][n] = __builtin_amdgcn_mfma_f32_16x16x32_bf16(Bt[n][k], At[m][k], acc[ai][bj][m][n], 0, 0, 0); __builtin_amdgcn_s_setprio(0); } while (0)
; #define PG8_WAIT_V(n) asm volatile("s_waitcnt vmcnt(" #n ")" ::: "memory")
; #define PG8_WAIT_L(n) asm volatile("s_waitcnt lgkmcnt(" #n ")" ::: "memory")
; #define PG8_BAR __builtin_amdgcn_s_barrier()
; #define PG8_SCHED __builtin_amdgcn_sched_barrier(0)
; template <class Epi, class Sched, bool ALIGN_EPI = false, bool SP2 = false>
; __device__ __forceinline__ void gemm_phase(PG8_LAS unsigned char* lds, const Gemm g, const Sched& S, const Epi& E) {
;     ...
;             PG8_WAIT_V(8); PG8_WAIT_L(0); PG8_BAR; PG8_MMA(1, 0, At, B0); PG8_MMA(1, 1, At, B1); PG8_BAR; PG8_SCHED;
;             PG8_LDB(B0, 1, 0); PG8_LDB(B1, 1, 1); PG8_SCHED; PG8_LDA(At, 1, 0); PG8_STAGE(PG8_SA(0, 1), a2 + hstep, voffA);
;             PG8_WAIT_V(8); PG8_WAIT_L(0); PG8_BAR; PG8_MMA(0, 0, At, B0); PG8_MMA(0, 1, At, B1); PG8_BAR; PG8_SCHED;
;             PG8_LDA(At, 1, 1); PG8_STAGE(PG8_SB(1, 0), b3, voffB); PG8_STAGE(PG8_SB(1, 1), b3 + hstep, voffB); PG8_STAGE(PG8_SA(1, 0), a3, voffA);
	s_setprio 1
	s_waitcnt lgkmcnt(0)
	v_mfma_f32_16x16x32_bf16 v[92:95], v[150:153], v[190:193], v[92:95]
	v_mfma_f32_16x16x32_bf16 v[88:91], v[158:161], v[190:193], v[88:91]
	v_mfma_f32_16x16x32_bf16 v[84:87], v[150:153], v[198:201], v[84:87]
	v_mfma_f32_16x16x32_bf16 v[80:83], v[158:161], v[198:201], v[80:83]
	v_mfma_f32_16x16x32_bf16 v[72:75], v[150:153], v[206:209], v[72:75]
	v_mfma_f32_16x16x32_bf16 v[64:67], v[158:161], v[206:209], v[64:67]
	v_mfma_f32_16x16x32_bf16 v[56:59], v[150:153], v[214:217], v[56:59]
	v_mfma_f32_16x16x32_bf16 v[48:51], v[158:161], v[214:217], v[48:51]
	v_mfma_f32_16x16x32_bf16 v[92:95], v[154:157], v[194:197], v[92:95]
	v_mfma_f32_16x16x32_bf16 v[88:91], v[162:165], v[194:197], v[88:91]
	v_mfma_f32_16x16x32_bf16 v[84:87], v[154:157], v[202:205], v[84:87]
	v_mfma_f32_16x16x32_bf16 v[80:83], v[162:165], v[202:205], v[80:83]
	v_mfma_f32_16x16x32_bf16 v[72:75], v[154:157], v[210:213], v[72:75]
	v_mfma_f32_16x16x32_bf16 v[64:67], v[162:165], v[210:213], v[64:67]
	v_mfma_f32_16x16x32_bf16 v[56:59], v[154:157], v[218:221], v[56:59]
	v_mfma_f32_16x16x32_bf16 v[48:51], v[162:165], v[218:221], v[48:51]
	s_setprio 0
	s_setprio 1
	v_mfma_f32_16x16x32_bf16 v[28:31], v[166:169], v[190:193], v[28:31]
	v_mfma_f32_16x16x32_bf16 v[24:27], v[174:177], v[190:193], v[24:27]
	v_mfma_f32_16x16x32_bf16 v[20:23], v[166:169], v[198:201], v[20:23]
	v_mfma_f32_16x16x32_bf16 v[16:19], v[174:177], v[198:201], v[16:19]
	v_mfma_f32_16x16x32_bf16 v[12:15], v[166:169], v[206:209], v[12:15]
	v_mfma_f32_16x16x32_bf16 v[8:11], v[174:177], v[206:209], v[8:11]
	v_mfma_f32_16x16x32_bf16 v[4:7], v[166:169], v[214:217], v[4:7]
	v_mfma_f32_16x16x32_bf16 v[0:3], v[174:177], v[214:217], v[0:3]
	v_mfma_f32_16x16x32_bf16 v[28:31], v[170:173], v[194:197], v[28:31]
	v_mfma_f32_16x16x32_bf16 v[24:27], v[178:181], v[194:197], v[24:27]
	v_mfma_f32_16x16x32_bf16 v[20:23], v[170:173], v[202:205], v[20:23]
	v_mfma_f32_16x16x32_bf16 v[16:19], v[178:181], v[202:205], v[16:19]
	v_mfma_f32_16x16x32_bf16 v[12:15], v[170:173], v[210:213], v[12:15]
	v_mfma_f32_16x16x32_bf16 v[8:11], v[178:181], v[210:213], v[8:11]
	v_mfma_f32_16x16x32_bf16 v[4:7], v[170:173], v[218:221], v[4:7]
	v_mfma_f32_16x16x32_bf16 v[0:3], v[178:181], v[218:221], v[0:3]
	s_setprio 0
	s_barrier
	s_add_i32 s3, 0, 0x18000
	s_add_i32 s28, 0, 0x1c000
	v_add_u32_e32 v162, s3, v145
	v_add_u32_e32 v237, s3, v234
	v_add_u32_e32 v178, s28, v145
	v_add_u32_e32 v238, s28, v234
	ds_read_b128 v[150:153], v162
	ds_read_b128 v[154:157], v237
	ds_read_b128 v[158:161], v162 offset:2048
	ds_read_b128 v[162:165], v237 offset:2048
	ds_read_b128 v[166:169], v178
	ds_read_b128 v[170:173], v238
	ds_read_b128 v[174:177], v178 offset:2048
	ds_read_b128 v[178:181], v238 offset:2048
	s_add_u32 s0, s36, 0xb0000
	s_addc_u32 s1, s37, 0
	s_mov_b32 m0, s49
	v_lshl_add_u64 v[230:231], s[0:1], 0, v[128:129]
	ds_read_b128 v[190:193], v149 offset:32768
	ds_read_b128 v[194:197], v233 offset:32768
	ds_read_b128 v[198:201], v149 offset:34816
	ds_read_b128 v[202:205], v233 offset:34816
	ds_read_b128 v[206:209], v149 offset:36864
	ds_read_b128 v[210:213], v233 offset:36864
	ds_read_b128 v[214:217], v149 offset:38912
	ds_read_b128 v[218:221], v233 offset:38912
	global_load_lds_dwordx4 v[230:231], off
	v_lshl_add_u64 v[230:231], s[0:1], 0, v[132:133]
	s_mov_b32 m0, s50
	s_nop 0
	global_load_lds_dwordx4 v[230:231], off
	s_waitcnt vmcnt(8)
	s_waitcnt lgkmcnt(0)
	s_barrier
	s_setprio 1
	s_waitcnt lgkmcnt(0)
	v_mfma_f32_16x16x32_bf16 v[124:127], v[150:153], v[190:193], v[124:127]
	v_mfma_f32_16x16x32_bf16 v[120:123], v[158:161], v[190:193], v[120:123]
	v_mfma_f32_16x16x32_bf16 v[116:119], v[150:153], v[198:201], v[116:119]
	v_mfma_f32_16x16x32_bf16 v[112:115], v[158:161], v[198:201], v[112:115]
	v_mfma_f32_16x16x32_bf16 v[108:111], v[150:153], v[206:209], v[108:111]
	v_mfma_f32_16x16x32_bf16 v[104:107], v[158:161], v[206:209], v[104:107]
	v_mfma_f32_16x16x32_bf16 v[100:103], v[150:153], v[214:217], v[100:103]
	v_mfma_f32_16x16x32_bf16 v[96:99], v[158:161], v[214:217], v[96:99]
	v_mfma_f32_16x16x32_bf16 v[124:127], v[154:157], v[194:197], v[124:127]
	v_mfma_f32_16x16x32_bf16 v[120:123], v[162:165], v[194:197], v[120:123]
	v_mfma_f32_16x16x32_bf16 v[116:119], v[154:157], v[202:205], v[116:119]
	v_mfma_f32_16x16x32_bf16 v[112:115], v[162:165], v[202:205], v[112:115]
	v_mfma_f32_16x16x32_bf16 v[108:111], v[154:157], v[210:213], v[108:111]
	v_mfma_f32_16x16x32_bf16 v[104:107], v[162:165], v[210:213], v[104:107]
	v_mfma_f32_16x16x32_bf16 v[100:103], v[154:157], v[218:221], v[100:103]
	v_mfma_f32_16x16x32_bf16 v[96:99], v[162:165], v[218:221], v[96:99]
	s_setprio 0
	s_setprio 1
	v_mfma_f32_16x16x32_bf16 v[76:79], v[166:169], v[190:193], v[76:79]
	v_mfma_f32_16x16x32_bf16 v[68:71], v[174:177], v[190:193], v[68:71]
	v_mfma_f32_16x16x32_bf16 v[60:63], v[166:169], v[198:201], v[60:63]
	v_mfma_f32_16x16x32_bf16 v[52:55], v[174:177], v[198:201], v[52:55]
	v_mfma_f32_16x16x32_bf16 v[44:47], v[166:169], v[206:209], v[44:47]
	v_mfma_f32_16x16x32_bf16 v[40:43], v[174:177], v[206:209], v[40:43]
	v_mfma_f32_16x16x32_bf16 v[36:39], v[166:169], v[214:217], v[36:39]
	v_mfma_f32_16x16x32_bf16 v[32:35], v[174:177], v[214:217], v[32:35]
	v_mfma_f32_16x16x32_bf16 v[76:79], v[170:173], v[194:197], v[76:79]
	v_mfma_f32_16x16x32_bf16 v[68:71], v[178:181], v[194:197], v[68:71]
	v_mfma_f32_16x16x32_bf16 v[60:63], v[170:173], v[202:205], v[60:63]
	v_mfma_f32_16x16x32_bf16 v[52:55], v[178:181], v[202:205], v[52:55]
	v_mfma_f32_16x16x32_bf16 v[44:47], v[170:173], v[210:213], v[44:47]
	v_mfma_f32_16x16x32_bf16 v[40:43], v[178:181], v[210:213], v[40:43]
	v_mfma_f32_16x16x32_bf16 v[36:39], v[170:173], v[218:221], v[36:39]
	v_mfma_f32_16x16x32_bf16 v[32:35], v[178:181], v[218:221], v[32:35]
	s_setprio 0
	s_barrier
; #define PG8_STAGE(bufoff, gbase, voff) do { _Pragma("unroll") for (int _i = 0; _i < 2; ++_i) \
;         __builtin_amdgcn_global_load_lds((const unsigned*)((const char*)(gbase) + (voff)[_i]), (PG8_LAS unsigned*)(lds + (bufoff) + ldsw + _i * 8192), 16, 0, 0); } while (0)
; #define PG8_LDA(dst, b, h) do { _Pragma("unroll") for (int m = 0; m < 4; ++m) _Pragma("unroll") for (int k = 0; k < 2; ++k) dst[m][k] = *(const PG8_LAS bf16x8*)(lds + PG8_SA(b, h) + aoff + m * 2048 + k * 1024); } while (0)
; #define PG8_MMA(ai, bj, At, Bt) do { __builtin_amdgcn_s_setprio(1); _Pragma("unroll") for (int m = 0; m < 4; ++m) _Pragma("unroll") for (int n = 0; n < 2; ++n) _Pragma("unroll") for (int k = 0; k < 2; ++k) \
;         acc[ai][bj][m][n] = __builtin_amdgcn_mfma_f32_16x16x32_bf16(Bt[n][k], At[m][k], acc[ai][bj][m][n], 0, 0, 0); __builtin_amdgcn_s_setprio(0); } while (0)
; #define PG8_WAIT_V(n) asm volatile("s_waitcnt vmcnt(" #n ")" ::: "memory")
; #define PG8_WAIT_L(n) asm volatile("s_waitcnt lgkmcnt(" #n ")" ::: "memory")
; #define PG8_BAR __builtin_amdgcn_s_barrier()
; #define PG8_SCHED __builtin_amdgcn_sched_barrier(0)
; template <class Epi, class Sched, bool ALIGN_EPI = false, bool SP2 = false>
; __device__ __forceinline__ void gemm_phase(PG8_LAS unsigned char* lds, const Gemm g, const Sched& S, const Epi& E) {
;     ...
;         for (int t = 0; t < nt; t += 2) {
;     ...
;             PG8_LDA(At, 1, 1); PG8_STAGE(PG8_SB(1, 0), b3, voffB); PG8_STAGE(PG8_SB(1, 1), b3 + hstep, voffB); PG8_STAGE(PG8_SA(1, 0), a3, voffA);
;             PG8_WAIT_V(8); PG8_WAIT_L(0); PG8_BAR; PG8_MMA(1, 0, At, B0); PG8_MMA(1, 1, At, B1); PG8_BAR; PG8_SCHED;
	s_add_i32 s0, s3, s43
	v_lshl_add_u64 v[222:223], v[222:223], 0, s[14:15]
	s_mov_b32 m0, s0
	ds_read_b128 v[190:193], v149 offset:49152
	ds_read_b128 v[194:197], v233 offset:49152
	ds_read_b128 v[198:201], v149 offset:51200
	ds_read_b128 v[202:205], v233 offset:51200
	ds_read_b128 v[206:209], v149 offset:53248
	ds_read_b128 v[210:213], v233 offset:53248
	ds_read_b128 v[214:217], v149 offset:55296
	ds_read_b128 v[218:221], v233 offset:55296
	global_load_lds_dwordx4 v[222:223], off
	s_add_i32 m0, s0, 0x2000
	s_add_u32 s0, s34, 0xb0080
	v_lshl_add_u64 v[222:223], v[224:225], 0, s[14:15]
	s_addc_u32 s1, s35, 0
	s_add_i32 s3, s28, s43
	global_load_lds_dwordx4 v[222:223], off
	v_lshl_add_u64 v[222:223], s[0:1], 0, v[130:131]
	s_mov_b32 m0, s3
	s_nop 0
	global_load_lds_dwordx4 v[222:223], off
	v_lshl_add_u64 v[222:223], s[0:1], 0, v[134:135]
	s_add_i32 m0, s3, 0x2000
	s_nop 0
	global_load_lds_dwordx4 v[222:223], off
	v_lshl_add_u64 v[222:223], v[226:227], 0, s[14:15]
	s_mov_b32 m0, s52
	s_nop 0
	global_load_lds_dwordx4 v[222:223], off
	v_lshl_add_u64 v[222:223], v[228:229], 0, s[14:15]
	s_mov_b32 m0, s53
	s_nop 0
	global_load_lds_dwordx4 v[222:223], off
	s_waitcnt vmcnt(8)
	s_waitcnt lgkmcnt(0)
	s_barrier
	s_setprio 1
	s_waitcnt lgkmcnt(0)
	v_mfma_f32_16x16x32_bf16 v[92:95], v[150:153], v[190:193], v[92:95]
	v_mfma_f32_16x16x32_bf16 v[88:91], v[158:161], v[190:193], v[88:91]
	v_mfma_f32_16x16x32_bf16 v[84:87], v[150:153], v[198:201], v[84:87]
	v_mfma_f32_16x16x32_bf16 v[80:83], v[158:161], v[198:201], v[80:83]
	v_mfma_f32_16x16x32_bf16 v[72:75], v[150:153], v[206:209], v[72:75]
	v_mfma_f32_16x16x32_bf16 v[64:67], v[158:161], v[206:209], v[64:67]
	v_mfma_f32_16x16x32_bf16 v[56:59], v[150:153], v[214:217], v[56:59]
	v_mfma_f32_16x16x32_bf16 v[48:51], v[158:161], v[214:217], v[48:51]
	v_mfma_f32_16x16x32_bf16 v[92:95], v[154:157], v[194:197], v[92:95]
	v_mfma_f32_16x16x32_bf16 v[88:91], v[162:165], v[194:197], v[88:91]
	v_mfma_f32_16x16x32_bf16 v[84:87], v[154:157], v[202:205], v[84:87]
	v_mfma_f32_16x16x32_bf16 v[80:83], v[162:165], v[202:205], v[80:83]
	v_mfma_f32_16x16x32_bf16 v[72:75], v[154:157], v[210:213], v[72:75]
	v_mfma_f32_16x16x32_bf16 v[64:67], v[162:165], v[210:213], v[64:67]
	v_mfma_f32_16x16x32_bf16 v[56:59], v[154:157], v[218:221], v[56:59]
	v_mfma_f32_16x16x32_bf16 v[48:51], v[162:165], v[218:221], v[48:51]
	s_setprio 0
	s_setprio 1
	v_mfma_f32_16x16x32_bf16 v[28:31], v[166:169], v[190:193], v[28:31]
	v_mfma_f32_16x16x32_bf16 v[24:27], v[174:177], v[190:193], v[24:27]
	v_mfma_f32_16x16x32_bf16 v[20:23], v[166:169], v[198:201], v[20:23]
	v_mfma_f32_16x16x32_bf16 v[16:19], v[174:177], v[198:201], v[16:19]
	v_mfma_f32_16x16x32_bf16 v[12:15], v[166:169], v[206:209], v[12:15]
	v_mfma_f32_16x16x32_bf16 v[8:11], v[174:177], v[206:209], v[8:11]
	v_mfma_f32_16x16x32_bf16 v[4:7], v[166:169], v[214:217], v[4:7]
	v_mfma_f32_16x16x32_bf16 v[0:3], v[174:177], v[214:217], v[0:3]
	v_mfma_f32_16x16x32_bf16 v[28:31], v[170:173], v[194:197], v[28:31]
	v_mfma_f32_16x16x32_bf16 v[24:27], v[178:181], v[194:197], v[24:27]
	v_mfma_f32_16x16x32_bf16 v[20:23], v[170:173], v[202:205], v[20:23]
	v_mfma_f32_16x16x32_bf16 v[16:19], v[178:181], v[202:205], v[16:19]
	v_mfma_f32_16x16x32_bf16 v[12:15], v[170:173], v[210:213], v[12:15]
	v_mfma_f32_16x16x32_bf16 v[8:11], v[178:181], v[210:213], v[8:11]
	v_mfma_f32_16x16x32_bf16 v[4:7], v[170:173], v[218:221], v[4:7]
	v_mfma_f32_16x16x32_bf16 v[0:3], v[178:181], v[218:221], v[0:3]
	s_setprio 0
	s_barrier
	s_add_i32 s68, s68, 2
	s_add_u32 s66, s66, 0x100
	s_addc_u32 s67, s67, 0
	s_cmp_gt_u32 s68, 41
	s_mov_b64 s[28:29], s[30:31]
	s_cbranch_scc0 .LBB0_1209
	s_and_b64 vcc, exec, s[16:17]
	s_cbranch_vccz .LBB0_1212
	s_barrier
